# v36: v35 plus SwiGLU epilogue strength reduction - the 2^-6 and 2^-3 scalings folded into the first multiply, exp argument taken from the accumulator (4 muls per output instead of 5, bit-identical)
# baseline (speedup 1.0000x reference)
.LBB0_688:
	s_add_u32 s10, s34, 0x100
	s_addc_u32 s11, s35, 0
	s_add_u32 s30, s29, s34
	s_addc_u32 s31, s55, s35
	s_cmpk_eq_i32 s34, 0x300
	s_cselect_b64 vcc, -1, 0
	s_and_b64 s[0:1], vcc, exec
	s_cselect_b32 s1, 0, s10
	s_cselect_b32 s0, 0, s11
	s_cselect_b32 s30, s27, s30
	s_cselect_b32 s31, s25, s31
	s_add_u32 s36, s14, s1
	s_addc_u32 s37, s15, s0
	s_add_i32 s1, 0, 0x10000
	v_add_u32_e32 v14, s1, v197
	ds_read_b128 v[2:5], v14
	ds_read_b128 v[6:9], v14 offset:1024
	ds_read_b128 v[10:13], v14 offset:2048
	ds_read_b128 v[14:17], v14 offset:3072
	v_cndmask_b32_e32 v162, v168, v171, vcc
	v_cndmask_b32_e32 v184, v170, v198, vcc
	v_cndmask_b32_e32 v175, v172, v199, vcc
	v_cndmask_b32_e32 v173, v174, v200, vcc
	v_lshl_add_u64 v[18:19], v[178:179], 0, s[34:35]
	s_add_i32 m0, s45, 0xc000
	ds_read_b128 v[202:205], v169
	ds_read_b128 v[206:209], v169 offset:1024
	ds_read_b128 v[210:213], v169 offset:2048
	ds_read_b128 v[214:217], v169 offset:3072
	ds_read_b128 v[218:221], v169 offset:4096
	ds_read_b128 v[222:225], v169 offset:5120
	ds_read_b128 v[226:229], v169 offset:6144
	ds_read_b128 v[230:233], v169 offset:7168
	global_load_lds_dwordx4 v[18:19], off
	v_lshl_add_u64 v[18:19], v[176:177], 0, s[34:35]
	s_add_i32 m0, s45, 0xe000
	s_nop 0
	global_load_lds_dwordx4 v[18:19], off
	s_waitcnt lgkmcnt(8)
	s_waitcnt vmcnt(10)
	s_barrier
	s_waitcnt lgkmcnt(0)
	s_waitcnt lgkmcnt(0)
	v_mfma_scale_f32_16x16x128_f8f6f4 v[158:161], v[2:9], v[202:209], v[158:161], v188, v188 op_sel_hi:[0,0,0]
	v_mfma_scale_f32_16x16x128_f8f6f4 v[150:153], v[10:17], v[202:209], v[150:153], v188, v188 op_sel_hi:[0,0,0]
	v_mfma_scale_f32_16x16x128_f8f6f4 v[142:145], v[2:9], v[210:217], v[142:145], v188, v188 op_sel_hi:[0,0,0]
	v_mfma_scale_f32_16x16x128_f8f6f4 v[134:137], v[10:17], v[210:217], v[134:137], v188, v188 op_sel_hi:[0,0,0]
	v_mfma_scale_f32_16x16x128_f8f6f4 v[126:129], v[2:9], v[218:225], v[126:129], v188, v188 op_sel_hi:[0,0,0]
	v_mfma_scale_f32_16x16x128_f8f6f4 v[118:121], v[10:17], v[218:225], v[118:121], v188, v188 op_sel_hi:[0,0,0]
	v_mfma_scale_f32_16x16x128_f8f6f4 v[110:113], v[2:9], v[226:233], v[110:113], v188, v188 op_sel_hi:[0,0,0]
	v_mfma_scale_f32_16x16x128_f8f6f4 v[102:105], v[10:17], v[226:233], v[102:105], v188, v188 op_sel_hi:[0,0,0]
	s_barrier
	s_add_i32 s0, 0, 0x14000
	s_add_i32 s1, s1, s43
	v_add_u32_e32 v30, s0, v197
	v_lshl_add_u64 v[180:181], s[30:31], 0, v[164:165]
	s_mov_b32 m0, s1
	ds_read_b128 v[18:21], v30
	ds_read_b128 v[22:25], v30 offset:1024
	ds_read_b128 v[26:29], v30 offset:2048
	ds_read_b128 v[30:33], v30 offset:3072
	global_load_lds_dwordx4 v[180:181], off
	v_lshl_add_u64 v[182:183], s[30:31], 0, v[166:167]
	s_add_i32 m0, s1, 0x2000
	s_nop 0
	global_load_lds_dwordx4 v[182:183], off
	s_waitcnt vmcnt(10)
	s_barrier
	s_waitcnt lgkmcnt(0)
	s_waitcnt lgkmcnt(0)
	v_mfma_scale_f32_16x16x128_f8f6f4 v[154:157], v[18:25], v[202:209], v[154:157], v188, v188 op_sel_hi:[0,0,0]
	v_mfma_scale_f32_16x16x128_f8f6f4 v[146:149], v[26:33], v[202:209], v[146:149], v188, v188 op_sel_hi:[0,0,0]
	v_mfma_scale_f32_16x16x128_f8f6f4 v[138:141], v[18:25], v[210:217], v[138:141], v188, v188 op_sel_hi:[0,0,0]
	v_mfma_scale_f32_16x16x128_f8f6f4 v[130:133], v[26:33], v[210:217], v[130:133], v188, v188 op_sel_hi:[0,0,0]
	v_mfma_scale_f32_16x16x128_f8f6f4 v[122:125], v[18:25], v[218:225], v[122:125], v188, v188 op_sel_hi:[0,0,0]
	v_mfma_scale_f32_16x16x128_f8f6f4 v[114:117], v[26:33], v[218:225], v[114:117], v188, v188 op_sel_hi:[0,0,0]
	v_mfma_scale_f32_16x16x128_f8f6f4 v[106:109], v[18:25], v[226:233], v[106:109], v188, v188 op_sel_hi:[0,0,0]
	v_mfma_scale_f32_16x16x128_f8f6f4 v[98:101], v[26:33], v[226:233], v[98:101], v188, v188 op_sel_hi:[0,0,0]
	s_mov_b32 m0, s45
	s_barrier
	ds_read_b128 v[202:205], v169 offset:16384
	ds_read_b128 v[206:209], v169 offset:17408
	ds_read_b128 v[210:213], v169 offset:18432
	ds_read_b128 v[214:217], v169 offset:19456
	ds_read_b128 v[218:221], v169 offset:20480
	ds_read_b128 v[222:225], v169 offset:21504
	ds_read_b128 v[226:229], v169 offset:22528
	ds_read_b128 v[230:233], v169 offset:23552
	global_load_lds_dwordx4 v162, s[36:37]
	s_mov_b32 m0, s46
	v_mov_b32_e32 v185, v163
	global_load_lds_dwordx4 v184, s[36:37]
	s_waitcnt vmcnt(10)
	s_barrier
	s_waitcnt lgkmcnt(0)
	v_lshl_add_u64 v[186:187], s[36:37], 0, v[162:163]
	v_lshl_add_u64 v[184:185], s[36:37], 0, v[184:185]
	s_waitcnt lgkmcnt(0)
	v_mfma_scale_f32_16x16x128_f8f6f4 v[94:97], v[2:9], v[202:209], v[94:97], v188, v188 op_sel_hi:[0,0,0]
	v_mfma_scale_f32_16x16x128_f8f6f4 v[86:89], v[10:17], v[202:209], v[86:89], v188, v188 op_sel_hi:[0,0,0]
	v_mfma_scale_f32_16x16x128_f8f6f4 v[78:81], v[2:9], v[210:217], v[78:81], v188, v188 op_sel_hi:[0,0,0]
	v_mfma_scale_f32_16x16x128_f8f6f4 v[70:73], v[10:17], v[210:217], v[70:73], v188, v188 op_sel_hi:[0,0,0]
	v_mfma_scale_f32_16x16x128_f8f6f4 v[62:65], v[2:9], v[218:225], v[62:65], v188, v188 op_sel_hi:[0,0,0]
	v_mfma_scale_f32_16x16x128_f8f6f4 v[54:57], v[10:17], v[218:225], v[54:57], v188, v188 op_sel_hi:[0,0,0]
	v_mfma_scale_f32_16x16x128_f8f6f4 v[46:49], v[2:9], v[226:233], v[46:49], v188, v188 op_sel_hi:[0,0,0]
	v_mfma_scale_f32_16x16x128_f8f6f4 v[38:41], v[10:17], v[226:233], v[38:41], v188, v188 op_sel_hi:[0,0,0]
	s_barrier
	s_add_u32 s34, s30, 0x20000
	s_addc_u32 s35, s31, 0
	s_add_i32 s0, s0, s43
	v_lshl_add_u64 v[2:3], s[34:35], 0, v[164:165]
	s_mov_b32 m0, s0
	s_nop 0
	global_load_lds_dwordx4 v[2:3], off
	v_lshl_add_u64 v[2:3], s[34:35], 0, v[166:167]
	s_add_i32 m0, s0, 0x2000
	s_nop 0
	global_load_lds_dwordx4 v[2:3], off
	s_waitcnt vmcnt(10)
	s_barrier
	v_mfma_scale_f32_16x16x128_f8f6f4 v[90:93], v[18:25], v[202:209], v[90:93], v188, v188 op_sel_hi:[0,0,0]
	v_mfma_scale_f32_16x16x128_f8f6f4 v[82:85], v[26:33], v[202:209], v[82:85], v188, v188 op_sel_hi:[0,0,0]
	v_mfma_scale_f32_16x16x128_f8f6f4 v[74:77], v[18:25], v[210:217], v[74:77], v188, v188 op_sel_hi:[0,0,0]
	v_mfma_scale_f32_16x16x128_f8f6f4 v[66:69], v[26:33], v[210:217], v[66:69], v188, v188 op_sel_hi:[0,0,0]
	v_mfma_scale_f32_16x16x128_f8f6f4 v[58:61], v[18:25], v[218:225], v[58:61], v188, v188 op_sel_hi:[0,0,0]
	v_mfma_scale_f32_16x16x128_f8f6f4 v[50:53], v[26:33], v[218:225], v[50:53], v188, v188 op_sel_hi:[0,0,0]
	v_mfma_scale_f32_16x16x128_f8f6f4 v[42:45], v[18:25], v[226:233], v[42:45], v188, v188 op_sel_hi:[0,0,0]
	v_mfma_scale_f32_16x16x128_f8f6f4 v[34:37], v[26:33], v[226:233], v[34:37], v188, v188 op_sel_hi:[0,0,0]
	s_add_i32 s0, 0, 0x18000
	v_add_u32_e32 v14, s0, v197
	s_barrier
	ds_read_b128 v[2:5], v14
	ds_read_b128 v[6:9], v14 offset:1024
	ds_read_b128 v[10:13], v14 offset:2048
	ds_read_b128 v[14:17], v14 offset:3072
	s_mov_b32 m0, s47
	ds_read_b128 v[18:21], v169 offset:32768
	ds_read_b128 v[22:25], v169 offset:33792
	ds_read_b128 v[26:29], v169 offset:34816
	ds_read_b128 v[30:33], v169 offset:35840
	ds_read_b128 v[202:205], v169 offset:36864
	ds_read_b128 v[206:209], v169 offset:37888
	ds_read_b128 v[210:213], v169 offset:38912
	ds_read_b128 v[214:217], v169 offset:39936
	global_load_lds_dwordx4 v175, s[36:37]
	s_mov_b32 m0, s48
	s_nop 0
	global_load_lds_dwordx4 v173, s[36:37]
	s_waitcnt lgkmcnt(8)
	s_waitcnt vmcnt(10)
	s_barrier
	s_waitcnt lgkmcnt(0)
	s_waitcnt lgkmcnt(0)
	v_mfma_scale_f32_16x16x128_f8f6f4 v[158:161], v[2:9], v[18:25], v[158:161], v188, v188 op_sel_hi:[0,0,0]
	v_mfma_scale_f32_16x16x128_f8f6f4 v[150:153], v[10:17], v[18:25], v[150:153], v188, v188 op_sel_hi:[0,0,0]
	v_mfma_scale_f32_16x16x128_f8f6f4 v[142:145], v[2:9], v[26:33], v[142:145], v188, v188 op_sel_hi:[0,0,0]
	v_mfma_scale_f32_16x16x128_f8f6f4 v[134:137], v[10:17], v[26:33], v[134:137], v188, v188 op_sel_hi:[0,0,0]
	v_mfma_scale_f32_16x16x128_f8f6f4 v[126:129], v[2:9], v[202:209], v[126:129], v188, v188 op_sel_hi:[0,0,0]
	v_mfma_scale_f32_16x16x128_f8f6f4 v[118:121], v[10:17], v[202:209], v[118:121], v188, v188 op_sel_hi:[0,0,0]
	v_mfma_scale_f32_16x16x128_f8f6f4 v[110:113], v[2:9], v[210:217], v[110:113], v188, v188 op_sel_hi:[0,0,0]
	v_mfma_scale_f32_16x16x128_f8f6f4 v[102:105], v[10:17], v[210:217], v[102:105], v188, v188 op_sel_hi:[0,0,0]
	s_barrier
	s_add_i32 s34, 0, 0x1c000
	s_add_i32 s0, s0, s43
	v_add_u32_e32 v162, s34, v197
	v_lshl_add_u64 v[180:181], v[180:181], 0, s[20:21]
	s_mov_b32 m0, s0
	ds_read_b128 v[218:221], v162
	ds_read_b128 v[222:225], v162 offset:1024
	ds_read_b128 v[226:229], v162 offset:2048
	ds_read_b128 v[230:233], v162 offset:3072
	global_load_lds_dwordx4 v[180:181], off
	v_lshl_add_u64 v[180:181], v[182:183], 0, s[20:21]
	s_add_i32 m0, s0, 0x2000
	s_nop 0
	global_load_lds_dwordx4 v[180:181], off
	s_waitcnt vmcnt(10)
	s_barrier
	s_waitcnt lgkmcnt(0)
	s_waitcnt lgkmcnt(0)
	v_mfma_scale_f32_16x16x128_f8f6f4 v[154:157], v[218:225], v[18:25], v[154:157], v188, v188 op_sel_hi:[0,0,0]
	v_mfma_scale_f32_16x16x128_f8f6f4 v[146:149], v[226:233], v[18:25], v[146:149], v188, v188 op_sel_hi:[0,0,0]
	v_mfma_scale_f32_16x16x128_f8f6f4 v[138:141], v[218:225], v[26:33], v[138:141], v188, v188 op_sel_hi:[0,0,0]
	v_mfma_scale_f32_16x16x128_f8f6f4 v[130:133], v[226:233], v[26:33], v[130:133], v188, v188 op_sel_hi:[0,0,0]
	v_mfma_scale_f32_16x16x128_f8f6f4 v[122:125], v[218:225], v[202:209], v[122:125], v188, v188 op_sel_hi:[0,0,0]
	v_mfma_scale_f32_16x16x128_f8f6f4 v[114:117], v[226:233], v[202:209], v[114:117], v188, v188 op_sel_hi:[0,0,0]
	v_mfma_scale_f32_16x16x128_f8f6f4 v[106:109], v[218:225], v[210:217], v[106:109], v188, v188 op_sel_hi:[0,0,0]
	v_mfma_scale_f32_16x16x128_f8f6f4 v[98:101], v[226:233], v[210:217], v[98:101], v188, v188 op_sel_hi:[0,0,0]
	s_mov_b32 m0, s51
	v_lshl_add_u64 v[180:181], v[186:187], 0, s[20:21]
	s_barrier
	ds_read_b128 v[18:21], v169 offset:49152
	ds_read_b128 v[22:25], v169 offset:50176
	ds_read_b128 v[26:29], v169 offset:51200
	ds_read_b128 v[30:33], v169 offset:52224
	ds_read_b128 v[202:205], v169 offset:53248
	ds_read_b128 v[206:209], v169 offset:54272
	ds_read_b128 v[210:213], v169 offset:55296
	ds_read_b128 v[214:217], v169 offset:56320
	global_load_lds_dwordx4 v[180:181], off
	v_lshl_add_u64 v[180:181], v[184:185], 0, s[20:21]
	s_mov_b32 m0, s52
	s_nop 0
	global_load_lds_dwordx4 v[180:181], off
	s_waitcnt vmcnt(10)
	s_barrier
	s_waitcnt lgkmcnt(0)
	s_waitcnt lgkmcnt(0)
	v_mfma_scale_f32_16x16x128_f8f6f4 v[94:97], v[2:9], v[18:25], v[94:97], v188, v188 op_sel_hi:[0,0,0]
	v_mfma_scale_f32_16x16x128_f8f6f4 v[86:89], v[10:17], v[18:25], v[86:89], v188, v188 op_sel_hi:[0,0,0]
	v_mfma_scale_f32_16x16x128_f8f6f4 v[78:81], v[2:9], v[26:33], v[78:81], v188, v188 op_sel_hi:[0,0,0]
	v_mfma_scale_f32_16x16x128_f8f6f4 v[70:73], v[10:17], v[26:33], v[70:73], v188, v188 op_sel_hi:[0,0,0]
	v_mfma_scale_f32_16x16x128_f8f6f4 v[62:65], v[2:9], v[202:209], v[62:65], v188, v188 op_sel_hi:[0,0,0]
	v_mfma_scale_f32_16x16x128_f8f6f4 v[54:57], v[10:17], v[202:209], v[54:57], v188, v188 op_sel_hi:[0,0,0]
	v_mfma_scale_f32_16x16x128_f8f6f4 v[46:49], v[2:9], v[210:217], v[46:49], v188, v188 op_sel_hi:[0,0,0]
	v_mfma_scale_f32_16x16x128_f8f6f4 v[38:41], v[10:17], v[210:217], v[38:41], v188, v188 op_sel_hi:[0,0,0]
	s_barrier
	s_add_u32 s0, s30, 0x20080
	s_addc_u32 s1, s31, 0
	s_add_i32 s30, s34, s43
	v_lshl_add_u64 v[2:3], s[0:1], 0, v[164:165]
	s_mov_b32 m0, s30
	s_nop 0
	global_load_lds_dwordx4 v[2:3], off
	v_lshl_add_u64 v[2:3], s[0:1], 0, v[166:167]
	s_add_i32 m0, s30, 0x2000
	s_nop 0
	global_load_lds_dwordx4 v[2:3], off
	s_waitcnt vmcnt(10)
	s_barrier
	v_mfma_scale_f32_16x16x128_f8f6f4 v[90:93], v[218:225], v[18:25], v[90:93], v188, v188 op_sel_hi:[0,0,0]
	v_mfma_scale_f32_16x16x128_f8f6f4 v[82:85], v[226:233], v[18:25], v[82:85], v188, v188 op_sel_hi:[0,0,0]
	v_mfma_scale_f32_16x16x128_f8f6f4 v[74:77], v[218:225], v[26:33], v[74:77], v188, v188 op_sel_hi:[0,0,0]
	v_mfma_scale_f32_16x16x128_f8f6f4 v[66:69], v[226:233], v[26:33], v[66:69], v188, v188 op_sel_hi:[0,0,0]
	v_mfma_scale_f32_16x16x128_f8f6f4 v[58:61], v[218:225], v[202:209], v[58:61], v188, v188 op_sel_hi:[0,0,0]
	v_mfma_scale_f32_16x16x128_f8f6f4 v[50:53], v[226:233], v[202:209], v[50:53], v188, v188 op_sel_hi:[0,0,0]
	v_mfma_scale_f32_16x16x128_f8f6f4 v[42:45], v[218:225], v[210:217], v[42:45], v188, v188 op_sel_hi:[0,0,0]
	v_mfma_scale_f32_16x16x128_f8f6f4 v[34:37], v[226:233], v[210:217], v[34:37], v188, v188 op_sel_hi:[0,0,0]
	s_add_i32 s56, s56, 2
	s_cmp_gt_u32 s56, 5
	s_mov_b64 s[34:35], s[10:11]
	s_barrier
	s_cbranch_scc0 .LBB0_688
	v_mul_f32_e32 v5, 0x3b000000, v158
	v_mul_f32_e32 v6, 0xbcb8aa3b, v158
	v_exp_f32_e32 v6, v6
	s_ashr_i32 s29, s28, 31
	s_ashr_i32 s27, s26, 31
	s_lshl_b64 s[10:11], s[28:29], 18
	v_add_f32_e32 v6, 1.0, v6
	v_rcp_f32_e32 v6, v6
	s_lshl_b64 s[26:27], s[26:27], 15
	v_mov_b32_e32 v3, v195
	s_add_u32 s0, s6, s10
	v_mul_f32_e32 v5, v5, v6
	v_mul_f32_e32 v6, 0x3b000000, v159
	v_mul_f32_e32 v7, 0xbcb8aa3b, v159
	v_exp_f32_e32 v7, v7
	v_mul_f32_e32 v5, v5, v154
	v_med3_f32 v5, v5, s40, v190
	v_add_f32_e32 v7, 1.0, v7
	v_rcp_f32_e32 v7, v7
	s_nop 15
	s_nop 15
	v_mov_b32_e32 v2, v196
	v_mul_f32_e32 v6, v6, v7
	v_mul_f32_e32 v7, 0x3b000000, v160
	v_mul_f32_e32 v8, 0xbcb8aa3b, v160
	v_exp_f32_e32 v8, v8
	v_mul_f32_e32 v6, v6, v155
	v_add_u32_e32 v4, s49, v3
	v_add_f32_e32 v8, 1.0, v8
	v_rcp_f32_e32 v8, v8
	s_addc_u32 s1, s7, s11
	s_add_u32 s10, s0, s26
	v_mul_f32_e32 v7, v7, v8
	v_mul_f32_e32 v8, 0x3b000000, v161
	v_mul_f32_e32 v9, 0xbcb8aa3b, v161
	v_exp_f32_e32 v9, v9
	v_mul_f32_e32 v7, v7, v156
	v_lshl_add_u32 v2, v2, 3, s50
	v_add_f32_e32 v9, 1.0, v9
	v_rcp_f32_e32 v9, v9
	s_addc_u32 s11, s1, s27
	v_ashrrev_i32_e32 v3, 31, v2
	s_and_b64 vcc, exec, s[8:9]
	v_mul_f32_e32 v8, v8, v9
	v_mul_f32_e32 v9, 0x3b000000, v150
	v_mul_f32_e32 v10, 0xbcb8aa3b, v150
	v_exp_f32_e32 v10, v10
	v_mul_f32_e32 v8, v8, v157
	v_mov_b32_e32 v174, v200
	v_add_f32_e32 v10, 1.0, v10
	v_rcp_f32_e32 v10, v10
	v_mov_b32_e32 v172, v199
	v_mov_b32_e32 v170, v198
	v_mov_b32_e32 v168, v171
	v_mul_f32_e32 v9, v9, v10
	v_mul_f32_e32 v10, 0x3b000000, v151
	v_mul_f32_e32 v11, 0xbcb8aa3b, v151
	v_exp_f32_e32 v11, v11
	v_mul_f32_e32 v9, v9, v146
	s_mov_b32 s26, s24
	v_add_f32_e32 v11, 1.0, v11
	v_rcp_f32_e32 v11, v11
	s_mov_b32 s28, s54
	s_mov_b64 s[30:31], s[12:13]
	v_mul_f32_e32 v10, v10, v11
	v_mul_f32_e32 v11, 0x3b000000, v152
	v_mul_f32_e32 v12, 0xbcb8aa3b, v152
	v_exp_f32_e32 v12, v12
	v_mul_f32_e32 v10, v10, v147
	v_add_f32_e32 v12, 1.0, v12
	v_rcp_f32_e32 v12, v12
	s_nop 0
	v_mul_f32_e32 v11, v11, v12
	v_mul_f32_e32 v12, 0x3b000000, v153
	v_mul_f32_e32 v13, 0xbcb8aa3b, v153
	v_exp_f32_e32 v13, v13
	v_mul_f32_e32 v11, v11, v148
	v_add_f32_e32 v13, 1.0, v13
	v_rcp_f32_e32 v13, v13
	s_nop 0
	v_mul_f32_e32 v12, v12, v13
	v_med3_f32 v13, v6, s40, v190
	v_mov_b32_e32 v6, v163
	v_cvt_pk_fp8_f32 v6, v5, v13
	v_med3_f32 v5, v7, s40, v190
	v_med3_f32 v7, v8, s40, v190
	v_med3_f32 v8, v10, s40, v190
	v_cvt_pk_fp8_f32 v6, v5, v7 op_sel:[0,0,1]
	v_med3_f32 v5, v9, s40, v190
	v_mov_b32_e32 v7, v163
	v_cvt_pk_fp8_f32 v7, v5, v8
	v_mul_f32_e32 v12, v12, v149
	v_med3_f32 v5, v11, s40, v190
	v_med3_f32 v8, v12, s40, v190
	v_cvt_pk_fp8_f32 v7, v5, v8 op_sel:[0,0,1]
	v_ashrrev_i32_e32 v5, 31, v4
	v_lshlrev_b64 v[8:9], 7, v[4:5]
	v_lshl_add_u64 v[8:9], s[10:11], 0, v[8:9]
	v_lshl_add_u64 v[8:9], v[8:9], 0, v[2:3]
	v_mul_f32_e32 v5, 0x3b000000, v142
	global_store_dwordx2 v[8:9], v[6:7], off
	v_mul_f32_e32 v6, 0xbcb8aa3b, v142
	v_exp_f32_e32 v6, v6
	s_nop 0
	v_add_f32_e32 v6, 1.0, v6
	v_rcp_f32_e32 v6, v6
	s_nop 0
	v_mul_f32_e32 v5, v5, v6
	v_mul_f32_e32 v6, 0x3b000000, v143
	v_mul_f32_e32 v7, 0xbcb8aa3b, v143
	v_exp_f32_e32 v7, v7
	v_mul_f32_e32 v5, v5, v138
	v_med3_f32 v5, v5, s40, v190
	v_add_f32_e32 v7, 1.0, v7
	v_rcp_f32_e32 v7, v7
	s_nop 0
	v_mul_f32_e32 v6, v6, v7
	v_mul_f32_e32 v7, v6, v139
	v_mul_f32_e32 v6, 0x3b000000, v144
	v_mul_f32_e32 v8, 0xbcb8aa3b, v144
	v_exp_f32_e32 v8, v8
	v_med3_f32 v7, v7, s40, v190
	v_add_f32_e32 v8, 1.0, v8
	v_rcp_f32_e32 v8, v8
	s_nop 0
	v_mul_f32_e32 v6, v6, v8
	v_mul_f32_e32 v9, v6, v140
	v_mul_f32_e32 v6, 0x3b000000, v145
	v_mul_f32_e32 v8, 0xbcb8aa3b, v145
	v_exp_f32_e32 v8, v8
	s_nop 0
	v_add_f32_e32 v8, 1.0, v8
	v_rcp_f32_e32 v8, v8
	s_nop 0
	v_mul_f32_e32 v6, v6, v8
	v_mul_f32_e32 v10, v6, v141
	v_mul_f32_e32 v6, 0x3b000000, v134
	v_mul_f32_e32 v8, 0xbcb8aa3b, v134
	v_exp_f32_e32 v8, v8
	s_nop 0
	v_add_f32_e32 v8, 1.0, v8
	v_rcp_f32_e32 v8, v8
	s_nop 0
	v_mul_f32_e32 v6, v6, v8
	v_mul_f32_e32 v11, v6, v130
	v_mul_f32_e32 v6, 0x3b000000, v135
	v_mul_f32_e32 v8, 0xbcb8aa3b, v135
	v_exp_f32_e32 v8, v8
	s_nop 0
	v_add_f32_e32 v8, 1.0, v8
	v_rcp_f32_e32 v8, v8
	s_nop 0
	v_mul_f32_e32 v6, v6, v8
	v_mul_f32_e32 v12, v6, v131
	v_mul_f32_e32 v6, 0x3b000000, v136
	v_mul_f32_e32 v8, 0xbcb8aa3b, v136
	v_exp_f32_e32 v8, v8
	s_nop 0
	v_add_f32_e32 v8, 1.0, v8
	v_rcp_f32_e32 v8, v8
	s_nop 0
	v_mul_f32_e32 v6, v6, v8
	v_mul_f32_e32 v13, v6, v132
	v_mul_f32_e32 v6, 0x3b000000, v137
	v_mul_f32_e32 v8, 0xbcb8aa3b, v137
	v_exp_f32_e32 v8, v8
	s_nop 0
	v_add_f32_e32 v8, 1.0, v8
	v_rcp_f32_e32 v8, v8
	s_nop 0
	v_mul_f32_e32 v6, v6, v8
	v_mov_b32_e32 v8, v163
	v_cvt_pk_fp8_f32 v8, v5, v7
	v_med3_f32 v5, v9, s40, v190
	v_med3_f32 v7, v10, s40, v190
	v_mov_b32_e32 v9, v163
	v_cvt_pk_fp8_f32 v8, v5, v7 op_sel:[0,0,1]
	v_med3_f32 v5, v11, s40, v190
	v_med3_f32 v7, v12, s40, v190
	v_cvt_pk_fp8_f32 v9, v5, v7
	v_mul_f32_e32 v14, v6, v133
	v_add_u32_e32 v6, 16, v4
	v_med3_f32 v5, v13, s40, v190
	v_med3_f32 v7, v14, s40, v190
	v_cvt_pk_fp8_f32 v9, v5, v7 op_sel:[0,0,1]
	v_ashrrev_i32_e32 v7, 31, v6
	v_lshlrev_b64 v[6:7], 7, v[6:7]
	v_lshl_add_u64 v[6:7], s[10:11], 0, v[6:7]
	v_lshl_add_u64 v[6:7], v[6:7], 0, v[2:3]
	v_mul_f32_e32 v5, 0x3b000000, v126
	global_store_dwordx2 v[6:7], v[8:9], off
	v_mul_f32_e32 v6, 0xbcb8aa3b, v126
	v_exp_f32_e32 v6, v6
	s_nop 0
	v_add_f32_e32 v6, 1.0, v6
	v_rcp_f32_e32 v6, v6
	s_nop 0
	v_mul_f32_e32 v5, v5, v6
	v_mul_f32_e32 v6, 0x3b000000, v127
	v_mul_f32_e32 v7, 0xbcb8aa3b, v127
	v_exp_f32_e32 v7, v7
	v_mul_f32_e32 v5, v5, v122
	v_med3_f32 v5, v5, s40, v190
	v_add_f32_e32 v7, 1.0, v7
	v_rcp_f32_e32 v7, v7
	s_nop 0
	v_mul_f32_e32 v6, v6, v7
	v_mul_f32_e32 v7, v6, v123
	v_mul_f32_e32 v6, 0x3b000000, v128
	v_mul_f32_e32 v8, 0xbcb8aa3b, v128
	v_exp_f32_e32 v8, v8
	v_med3_f32 v7, v7, s40, v190
	v_add_f32_e32 v8, 1.0, v8
	v_rcp_f32_e32 v8, v8
	s_nop 0
	v_mul_f32_e32 v6, v6, v8
	v_mul_f32_e32 v9, v6, v124
	v_mul_f32_e32 v6, 0x3b000000, v129
	v_mul_f32_e32 v8, 0xbcb8aa3b, v129
	v_exp_f32_e32 v8, v8
	s_nop 0
	v_add_f32_e32 v8, 1.0, v8
	v_rcp_f32_e32 v8, v8
	s_nop 0
	v_mul_f32_e32 v6, v6, v8
	v_mul_f32_e32 v10, v6, v125
	v_mul_f32_e32 v6, 0x3b000000, v118
	v_mul_f32_e32 v8, 0xbcb8aa3b, v118
	v_exp_f32_e32 v8, v8
	s_nop 0
	v_add_f32_e32 v8, 1.0, v8
	v_rcp_f32_e32 v8, v8
	s_nop 0
	v_mul_f32_e32 v6, v6, v8
	v_mul_f32_e32 v11, v6, v114
	v_mul_f32_e32 v6, 0x3b000000, v119
	v_mul_f32_e32 v8, 0xbcb8aa3b, v119
	v_exp_f32_e32 v8, v8
	s_nop 0
	v_add_f32_e32 v8, 1.0, v8
	v_rcp_f32_e32 v8, v8
	s_nop 0
	v_mul_f32_e32 v6, v6, v8
	v_mul_f32_e32 v12, v6, v115
	v_mul_f32_e32 v6, 0x3b000000, v120
	v_mul_f32_e32 v8, 0xbcb8aa3b, v120
	v_exp_f32_e32 v8, v8
	s_nop 0
	v_add_f32_e32 v8, 1.0, v8
	v_rcp_f32_e32 v8, v8
	s_nop 0
	v_mul_f32_e32 v6, v6, v8
	v_mul_f32_e32 v13, v6, v116
	v_mul_f32_e32 v6, 0x3b000000, v121
	v_mul_f32_e32 v8, 0xbcb8aa3b, v121
	v_exp_f32_e32 v8, v8
	s_nop 0
	v_add_f32_e32 v8, 1.0, v8
	v_rcp_f32_e32 v8, v8
	s_nop 0
	v_mul_f32_e32 v6, v6, v8
	v_mov_b32_e32 v8, v163
	v_cvt_pk_fp8_f32 v8, v5, v7
	v_med3_f32 v5, v9, s40, v190
	v_med3_f32 v7, v10, s40, v190
	v_mov_b32_e32 v9, v163
	v_cvt_pk_fp8_f32 v8, v5, v7 op_sel:[0,0,1]
	v_med3_f32 v5, v11, s40, v190
	v_med3_f32 v7, v12, s40, v190
	v_cvt_pk_fp8_f32 v9, v5, v7
	v_mul_f32_e32 v14, v6, v117
	v_add_u32_e32 v6, 32, v4
	v_med3_f32 v5, v13, s40, v190
	v_med3_f32 v7, v14, s40, v190
	v_cvt_pk_fp8_f32 v9, v5, v7 op_sel:[0,0,1]
	v_ashrrev_i32_e32 v7, 31, v6
	v_lshlrev_b64 v[6:7], 7, v[6:7]
	v_lshl_add_u64 v[6:7], s[10:11], 0, v[6:7]
	v_lshl_add_u64 v[6:7], v[6:7], 0, v[2:3]
	v_mul_f32_e32 v5, 0x3b000000, v110
	global_store_dwordx2 v[6:7], v[8:9], off
	v_mul_f32_e32 v6, 0xbcb8aa3b, v110
	v_exp_f32_e32 v6, v6
	s_nop 0
	v_add_f32_e32 v6, 1.0, v6
	v_rcp_f32_e32 v6, v6
	s_nop 0
	v_mul_f32_e32 v5, v5, v6
	v_mul_f32_e32 v6, 0x3b000000, v111
	v_mul_f32_e32 v7, 0xbcb8aa3b, v111
	v_exp_f32_e32 v7, v7
	v_mul_f32_e32 v5, v5, v106
	v_med3_f32 v5, v5, s40, v190
	v_add_f32_e32 v7, 1.0, v7
	v_rcp_f32_e32 v7, v7
	s_nop 0
	v_mul_f32_e32 v6, v6, v7
	v_mul_f32_e32 v7, v6, v107
	v_mul_f32_e32 v6, 0x3b000000, v112
	v_mul_f32_e32 v8, 0xbcb8aa3b, v112
	v_exp_f32_e32 v8, v8
	v_med3_f32 v7, v7, s40, v190
	v_add_f32_e32 v8, 1.0, v8
	v_rcp_f32_e32 v8, v8
	s_nop 0
	v_mul_f32_e32 v6, v6, v8
	v_mul_f32_e32 v9, v6, v108
	v_mul_f32_e32 v6, 0x3b000000, v113
	v_mul_f32_e32 v8, 0xbcb8aa3b, v113
	v_exp_f32_e32 v8, v8
	s_nop 0
	v_add_f32_e32 v8, 1.0, v8
	v_rcp_f32_e32 v8, v8
	s_nop 0
	v_mul_f32_e32 v6, v6, v8
	v_mul_f32_e32 v10, v6, v109
	v_mul_f32_e32 v6, 0x3b000000, v102
	v_mul_f32_e32 v8, 0xbcb8aa3b, v102
	v_exp_f32_e32 v8, v8
	s_nop 0
	v_add_f32_e32 v8, 1.0, v8
	v_rcp_f32_e32 v8, v8
	s_nop 0
	v_mul_f32_e32 v6, v6, v8
	v_mul_f32_e32 v11, v6, v98
	v_mul_f32_e32 v6, 0x3b000000, v103
	v_mul_f32_e32 v8, 0xbcb8aa3b, v103
	v_exp_f32_e32 v8, v8
	s_nop 0
	v_add_f32_e32 v8, 1.0, v8
	v_rcp_f32_e32 v8, v8
	s_nop 0
	v_mul_f32_e32 v6, v6, v8
	v_mul_f32_e32 v12, v6, v99
	v_mul_f32_e32 v6, 0x3b000000, v104
	v_mul_f32_e32 v8, 0xbcb8aa3b, v104
	v_exp_f32_e32 v8, v8
	s_nop 0
	v_add_f32_e32 v8, 1.0, v8
	v_rcp_f32_e32 v8, v8
	s_nop 0
	v_mul_f32_e32 v6, v6, v8
	v_mul_f32_e32 v13, v6, v100
	v_mul_f32_e32 v6, 0x3b000000, v105
	v_mul_f32_e32 v8, 0xbcb8aa3b, v105
	v_exp_f32_e32 v8, v8
	s_nop 0
	v_add_f32_e32 v8, 1.0, v8
	v_rcp_f32_e32 v8, v8
	s_nop 0
	v_mul_f32_e32 v6, v6, v8
	v_mov_b32_e32 v8, v163
	v_cvt_pk_fp8_f32 v8, v5, v7
	v_med3_f32 v5, v9, s40, v190
	v_med3_f32 v7, v10, s40, v190
	v_mov_b32_e32 v9, v163
	v_cvt_pk_fp8_f32 v8, v5, v7 op_sel:[0,0,1]
	v_med3_f32 v5, v11, s40, v190
	v_med3_f32 v7, v12, s40, v190
	v_cvt_pk_fp8_f32 v9, v5, v7
	v_mul_f32_e32 v14, v6, v101
	v_add_u32_e32 v6, 48, v4
	v_med3_f32 v5, v13, s40, v190
	v_med3_f32 v7, v14, s40, v190
	v_cvt_pk_fp8_f32 v9, v5, v7 op_sel:[0,0,1]
	v_ashrrev_i32_e32 v7, 31, v6
	v_lshlrev_b64 v[6:7], 7, v[6:7]
	v_lshl_add_u64 v[6:7], s[10:11], 0, v[6:7]
	v_lshl_add_u64 v[6:7], v[6:7], 0, v[2:3]
	v_mul_f32_e32 v5, 0x3b000000, v94
	global_store_dwordx2 v[6:7], v[8:9], off
	v_mul_f32_e32 v7, 0xbcb8aa3b, v94
	v_exp_f32_e32 v7, v7
	v_add_u32_e32 v6, 0x80, v4
	v_add_f32_e32 v7, 1.0, v7
	v_rcp_f32_e32 v7, v7
	s_nop 0
	v_mul_f32_e32 v5, v5, v7
	v_mul_f32_e32 v7, 0x3b000000, v95
	v_mul_f32_e32 v8, 0xbcb8aa3b, v95
	v_exp_f32_e32 v8, v8
	v_mul_f32_e32 v5, v5, v90
	v_med3_f32 v5, v5, s40, v190
	v_add_f32_e32 v8, 1.0, v8
	v_rcp_f32_e32 v8, v8
	s_nop 0
	v_mul_f32_e32 v7, v7, v8
	v_mul_f32_e32 v8, 0x3b000000, v96
	v_mul_f32_e32 v9, 0xbcb8aa3b, v96
	v_exp_f32_e32 v9, v9
	v_mul_f32_e32 v7, v7, v91
	v_med3_f32 v7, v7, s40, v190
	v_add_f32_e32 v9, 1.0, v9
	v_rcp_f32_e32 v9, v9
	s_nop 0
	v_mul_f32_e32 v8, v8, v9
	v_mul_f32_e32 v9, v8, v92
	v_mul_f32_e32 v8, 0x3b000000, v97
	v_mul_f32_e32 v10, 0xbcb8aa3b, v97
	v_exp_f32_e32 v10, v10
	s_nop 0
	v_add_f32_e32 v10, 1.0, v10
	v_rcp_f32_e32 v10, v10
	s_nop 0
	v_mul_f32_e32 v8, v8, v10
	v_mul_f32_e32 v10, v8, v93
	v_mul_f32_e32 v8, 0x3b000000, v86
	v_mul_f32_e32 v11, 0xbcb8aa3b, v86
	v_exp_f32_e32 v11, v11
	s_nop 0
	v_add_f32_e32 v11, 1.0, v11
	v_rcp_f32_e32 v11, v11
	s_nop 0
	v_mul_f32_e32 v8, v8, v11
	v_mul_f32_e32 v11, v8, v82
	v_mul_f32_e32 v8, 0x3b000000, v87
	v_mul_f32_e32 v12, 0xbcb8aa3b, v87
	v_exp_f32_e32 v12, v12
	s_nop 0
	v_add_f32_e32 v12, 1.0, v12
	v_rcp_f32_e32 v12, v12
	s_nop 0
	v_mul_f32_e32 v8, v8, v12
	v_mul_f32_e32 v12, v8, v83
	v_mul_f32_e32 v8, 0x3b000000, v88
	v_mul_f32_e32 v13, 0xbcb8aa3b, v88
	v_exp_f32_e32 v13, v13
	s_nop 0
	v_add_f32_e32 v13, 1.0, v13
	v_rcp_f32_e32 v13, v13
	s_nop 0
	v_mul_f32_e32 v8, v8, v13
	v_mul_f32_e32 v13, v8, v84
	v_mul_f32_e32 v8, 0x3b000000, v89
	v_mul_f32_e32 v14, 0xbcb8aa3b, v89
	v_exp_f32_e32 v14, v14
	s_nop 0
	v_add_f32_e32 v14, 1.0, v14
	v_rcp_f32_e32 v14, v14
	s_nop 0
	v_mul_f32_e32 v8, v8, v14
	v_mul_f32_e32 v14, v8, v85
	v_mov_b32_e32 v8, v163
	v_cvt_pk_fp8_f32 v8, v5, v7
	v_med3_f32 v5, v9, s40, v190
	v_med3_f32 v7, v10, s40, v190
	v_mov_b32_e32 v9, v163
	v_cvt_pk_fp8_f32 v8, v5, v7 op_sel:[0,0,1]
	v_med3_f32 v5, v11, s40, v190
	v_med3_f32 v7, v12, s40, v190
	v_cvt_pk_fp8_f32 v9, v5, v7
	v_med3_f32 v5, v13, s40, v190
	v_med3_f32 v7, v14, s40, v190
	v_cvt_pk_fp8_f32 v9, v5, v7 op_sel:[0,0,1]
	v_ashrrev_i32_e32 v7, 31, v6
	v_lshlrev_b64 v[6:7], 7, v[6:7]
	v_lshl_add_u64 v[6:7], s[10:11], 0, v[6:7]
	v_lshl_add_u64 v[6:7], v[6:7], 0, v[2:3]
	v_mul_f32_e32 v5, 0x3b000000, v78
	global_store_dwordx2 v[6:7], v[8:9], off
	v_mul_f32_e32 v6, 0xbcb8aa3b, v78
	v_exp_f32_e32 v6, v6
	s_nop 0
	v_add_f32_e32 v6, 1.0, v6
	v_rcp_f32_e32 v6, v6
	s_nop 0
	v_mul_f32_e32 v5, v5, v6
	v_mul_f32_e32 v6, 0x3b000000, v79
	v_mul_f32_e32 v7, 0xbcb8aa3b, v79
	v_exp_f32_e32 v7, v7
	v_mul_f32_e32 v5, v5, v74
	v_med3_f32 v5, v5, s40, v190
	v_add_f32_e32 v7, 1.0, v7
	v_rcp_f32_e32 v7, v7
	s_nop 0
	v_mul_f32_e32 v6, v6, v7
	v_mul_f32_e32 v7, v6, v75
	v_mul_f32_e32 v6, 0x3b000000, v80
	v_mul_f32_e32 v8, 0xbcb8aa3b, v80
	v_exp_f32_e32 v8, v8
	v_med3_f32 v7, v7, s40, v190
	v_add_f32_e32 v8, 1.0, v8
	v_rcp_f32_e32 v8, v8
	s_nop 0
	v_mul_f32_e32 v6, v6, v8
	v_mul_f32_e32 v9, v6, v76
	v_mul_f32_e32 v6, 0x3b000000, v81
	v_mul_f32_e32 v8, 0xbcb8aa3b, v81
	v_exp_f32_e32 v8, v8
	s_nop 0
	v_add_f32_e32 v8, 1.0, v8
	v_rcp_f32_e32 v8, v8
	s_nop 0
	v_mul_f32_e32 v6, v6, v8
	v_mul_f32_e32 v10, v6, v77
	v_mul_f32_e32 v6, 0x3b000000, v70
	v_mul_f32_e32 v8, 0xbcb8aa3b, v70
	v_exp_f32_e32 v8, v8
	s_nop 0
	v_add_f32_e32 v8, 1.0, v8
	v_rcp_f32_e32 v8, v8
	s_nop 0
	v_mul_f32_e32 v6, v6, v8
	v_mul_f32_e32 v11, v6, v66
	v_mul_f32_e32 v6, 0x3b000000, v71
	v_mul_f32_e32 v8, 0xbcb8aa3b, v71
	v_exp_f32_e32 v8, v8
	s_nop 0
	v_add_f32_e32 v8, 1.0, v8
	v_rcp_f32_e32 v8, v8
	s_nop 0
	v_mul_f32_e32 v6, v6, v8
	v_mul_f32_e32 v12, v6, v67
	v_mul_f32_e32 v6, 0x3b000000, v72
	v_mul_f32_e32 v8, 0xbcb8aa3b, v72
	v_exp_f32_e32 v8, v8
	s_nop 0
	v_add_f32_e32 v8, 1.0, v8
	v_rcp_f32_e32 v8, v8
	s_nop 0
	v_mul_f32_e32 v6, v6, v8
	v_mul_f32_e32 v13, v6, v68
	v_mul_f32_e32 v6, 0x3b000000, v73
	v_mul_f32_e32 v8, 0xbcb8aa3b, v73
	v_exp_f32_e32 v8, v8
	s_nop 0
	v_add_f32_e32 v8, 1.0, v8
	v_rcp_f32_e32 v8, v8
	s_nop 0
	v_mul_f32_e32 v6, v6, v8
	v_mov_b32_e32 v8, v163
	v_cvt_pk_fp8_f32 v8, v5, v7
	v_med3_f32 v5, v9, s40, v190
	v_med3_f32 v7, v10, s40, v190
	v_mov_b32_e32 v9, v163
	v_cvt_pk_fp8_f32 v8, v5, v7 op_sel:[0,0,1]
	v_med3_f32 v5, v11, s40, v190
	v_med3_f32 v7, v12, s40, v190
	v_cvt_pk_fp8_f32 v9, v5, v7
	v_mul_f32_e32 v14, v6, v69
	v_add_u32_e32 v6, 0x90, v4
	v_med3_f32 v5, v13, s40, v190
	v_med3_f32 v7, v14, s40, v190
	v_cvt_pk_fp8_f32 v9, v5, v7 op_sel:[0,0,1]
	v_ashrrev_i32_e32 v7, 31, v6
	v_lshlrev_b64 v[6:7], 7, v[6:7]
	v_lshl_add_u64 v[6:7], s[10:11], 0, v[6:7]
	v_lshl_add_u64 v[6:7], v[6:7], 0, v[2:3]
	v_mul_f32_e32 v5, 0x3b000000, v62
	global_store_dwordx2 v[6:7], v[8:9], off
	v_mul_f32_e32 v6, 0xbcb8aa3b, v62
	v_exp_f32_e32 v6, v6
	s_nop 0
	v_add_f32_e32 v6, 1.0, v6
	v_rcp_f32_e32 v6, v6
	s_nop 0
	v_mul_f32_e32 v5, v5, v6
	v_mul_f32_e32 v6, 0x3b000000, v63
	v_mul_f32_e32 v7, 0xbcb8aa3b, v63
	v_exp_f32_e32 v7, v7
	v_mul_f32_e32 v5, v5, v58
	v_med3_f32 v5, v5, s40, v190
	v_add_f32_e32 v7, 1.0, v7
	v_rcp_f32_e32 v7, v7
	s_nop 0
	v_mul_f32_e32 v6, v6, v7
	v_mul_f32_e32 v7, v6, v59
	v_mul_f32_e32 v6, 0x3b000000, v64
	v_mul_f32_e32 v8, 0xbcb8aa3b, v64
	v_exp_f32_e32 v8, v8
	v_med3_f32 v7, v7, s40, v190
	v_add_f32_e32 v8, 1.0, v8
	v_rcp_f32_e32 v8, v8
	s_nop 0
	v_mul_f32_e32 v6, v6, v8
	v_mul_f32_e32 v9, v6, v60
	v_mul_f32_e32 v6, 0x3b000000, v65
	v_mul_f32_e32 v8, 0xbcb8aa3b, v65
	v_exp_f32_e32 v8, v8
	s_nop 0
	v_add_f32_e32 v8, 1.0, v8
	v_rcp_f32_e32 v8, v8
	s_nop 0
	v_mul_f32_e32 v6, v6, v8
	v_mul_f32_e32 v10, v6, v61
	v_mul_f32_e32 v6, 0x3b000000, v54
	v_mul_f32_e32 v8, 0xbcb8aa3b, v54
	v_exp_f32_e32 v8, v8
	s_nop 0
	v_add_f32_e32 v8, 1.0, v8
	v_rcp_f32_e32 v8, v8
	s_nop 0
	v_mul_f32_e32 v6, v6, v8
	v_mul_f32_e32 v11, v6, v50
	v_mul_f32_e32 v6, 0x3b000000, v55
	v_mul_f32_e32 v8, 0xbcb8aa3b, v55
	v_exp_f32_e32 v8, v8
	s_nop 0
	v_add_f32_e32 v8, 1.0, v8
	v_rcp_f32_e32 v8, v8
	s_nop 0
	v_mul_f32_e32 v6, v6, v8
	v_mul_f32_e32 v12, v6, v51
	v_mul_f32_e32 v6, 0x3b000000, v56
	v_mul_f32_e32 v8, 0xbcb8aa3b, v56
	v_exp_f32_e32 v8, v8
	s_nop 0
	v_add_f32_e32 v8, 1.0, v8
	v_rcp_f32_e32 v8, v8
	s_nop 0
	v_mul_f32_e32 v6, v6, v8
	v_mul_f32_e32 v13, v6, v52
	v_mul_f32_e32 v6, 0x3b000000, v57
	v_mul_f32_e32 v8, 0xbcb8aa3b, v57
	v_exp_f32_e32 v8, v8
	s_nop 0
	v_add_f32_e32 v8, 1.0, v8
	v_rcp_f32_e32 v8, v8
	s_nop 0
	v_mul_f32_e32 v6, v6, v8
	v_mov_b32_e32 v8, v163
	v_cvt_pk_fp8_f32 v8, v5, v7
	v_med3_f32 v5, v9, s40, v190
	v_med3_f32 v7, v10, s40, v190
	v_mov_b32_e32 v9, v163
	v_cvt_pk_fp8_f32 v8, v5, v7 op_sel:[0,0,1]
	v_med3_f32 v5, v11, s40, v190
	v_med3_f32 v7, v12, s40, v190
	v_cvt_pk_fp8_f32 v9, v5, v7
	v_mul_f32_e32 v14, v6, v53
	v_add_u32_e32 v6, 0xa0, v4
	v_med3_f32 v5, v13, s40, v190
	v_med3_f32 v7, v14, s40, v190
	v_cvt_pk_fp8_f32 v9, v5, v7 op_sel:[0,0,1]
	v_ashrrev_i32_e32 v7, 31, v6
	v_lshlrev_b64 v[6:7], 7, v[6:7]
	v_lshl_add_u64 v[6:7], s[10:11], 0, v[6:7]
	v_lshl_add_u64 v[6:7], v[6:7], 0, v[2:3]
	v_mul_f32_e32 v5, 0x3b000000, v46
	global_store_dwordx2 v[6:7], v[8:9], off
	v_mul_f32_e32 v6, 0xbcb8aa3b, v46
	v_exp_f32_e32 v6, v6
	v_add_u32_e32 v4, 0xb0, v4
	v_add_f32_e32 v6, 1.0, v6
	v_rcp_f32_e32 v6, v6
	s_nop 0
	v_mul_f32_e32 v5, v5, v6
	v_mul_f32_e32 v6, 0x3b000000, v47
	v_mul_f32_e32 v7, 0xbcb8aa3b, v47
	v_exp_f32_e32 v7, v7
	v_mul_f32_e32 v5, v5, v42
	v_med3_f32 v5, v5, s40, v190
	v_add_f32_e32 v7, 1.0, v7
	v_rcp_f32_e32 v7, v7
	s_nop 0
	v_mul_f32_e32 v6, v6, v7
	v_mul_f32_e32 v7, 0x3b000000, v48
	v_mul_f32_e32 v8, 0xbcb8aa3b, v48
	v_exp_f32_e32 v8, v8
	v_mul_f32_e32 v6, v6, v43
	v_add_f32_e32 v8, 1.0, v8
	v_rcp_f32_e32 v8, v8
	s_nop 0
	v_mul_f32_e32 v7, v7, v8
	v_mul_f32_e32 v8, 0x3b000000, v49
	v_mul_f32_e32 v9, 0xbcb8aa3b, v49
	v_exp_f32_e32 v9, v9
	v_mul_f32_e32 v7, v7, v44
	v_add_f32_e32 v9, 1.0, v9
	v_rcp_f32_e32 v9, v9
	s_nop 0
	v_mul_f32_e32 v8, v8, v9
	v_mul_f32_e32 v9, 0x3b000000, v38
	v_mul_f32_e32 v10, 0xbcb8aa3b, v38
	v_exp_f32_e32 v10, v10
	v_mul_f32_e32 v8, v8, v45
	v_add_f32_e32 v10, 1.0, v10
	v_rcp_f32_e32 v10, v10
	s_nop 0
	v_mul_f32_e32 v9, v9, v10
	v_mul_f32_e32 v10, 0x3b000000, v39
	v_mul_f32_e32 v11, 0xbcb8aa3b, v39
	v_exp_f32_e32 v11, v11
	v_mul_f32_e32 v9, v9, v34
	v_add_f32_e32 v11, 1.0, v11
	v_rcp_f32_e32 v11, v11
	s_nop 0
	v_mul_f32_e32 v10, v10, v11
	v_mul_f32_e32 v11, 0x3b000000, v40
	v_mul_f32_e32 v12, 0xbcb8aa3b, v40
	v_exp_f32_e32 v12, v12
	v_mul_f32_e32 v10, v10, v35
	v_add_f32_e32 v12, 1.0, v12
	v_rcp_f32_e32 v12, v12
	s_nop 0
	v_mul_f32_e32 v11, v11, v12
	v_mul_f32_e32 v12, 0x3b000000, v41
	v_mul_f32_e32 v13, 0xbcb8aa3b, v41
	v_exp_f32_e32 v13, v13
	v_mul_f32_e32 v11, v11, v36
	v_add_f32_e32 v13, 1.0, v13
	v_rcp_f32_e32 v13, v13
	s_nop 0
	v_mul_f32_e32 v12, v12, v13
	v_med3_f32 v13, v6, s40, v190
	v_mov_b32_e32 v6, v163
	v_cvt_pk_fp8_f32 v6, v5, v13
	v_med3_f32 v5, v7, s40, v190
	v_med3_f32 v7, v8, s40, v190
	v_med3_f32 v8, v10, s40, v190
	v_cvt_pk_fp8_f32 v6, v5, v7 op_sel:[0,0,1]
	v_med3_f32 v5, v9, s40, v190
	v_mov_b32_e32 v7, v163
	v_cvt_pk_fp8_f32 v7, v5, v8
	v_mul_f32_e32 v12, v12, v37
	v_med3_f32 v5, v11, s40, v190
	v_med3_f32 v8, v12, s40, v190
	v_cvt_pk_fp8_f32 v7, v5, v8 op_sel:[0,0,1]
	v_ashrrev_i32_e32 v5, 31, v4
	v_lshlrev_b64 v[4:5], 7, v[4:5]
	v_lshl_add_u64 v[4:5], s[10:11], 0, v[4:5]
	v_lshl_add_u64 v[2:3], v[4:5], 0, v[2:3]
	global_store_dwordx2 v[2:3], v[6:7], off
	s_cbranch_vccz .LBB0_677
	s_waitcnt vmcnt(0)
	s_cmpk_gt_u32 s42, 0xff
	s_cbranch_scc1 .LBB0_623
	s_barrier
	s_branch .LBB0_623

.LBB0_1302:
	s_add_u32 s12, s36, 0x100
	s_addc_u32 s13, s37, 0
	s_add_u32 s34, s31, s36
	s_addc_u32 s35, s55, s37
	s_cmpk_eq_i32 s36, 0x300
	s_cselect_b64 vcc, -1, 0
	s_and_b64 s[0:1], vcc, exec
	s_cselect_b32 s1, 0, s12
	s_cselect_b32 s0, 0, s13
	s_cselect_b32 s34, s29, s34
	s_cselect_b32 s35, s27, s35
	s_add_u32 s38, s16, s1
	s_addc_u32 s39, s17, s0
	s_add_i32 s1, 0, 0x10000
	v_add_u32_e32 v14, s1, v197
	ds_read_b128 v[2:5], v14
	ds_read_b128 v[6:9], v14 offset:1024
	ds_read_b128 v[10:13], v14 offset:2048
	ds_read_b128 v[14:17], v14 offset:3072
	v_cndmask_b32_e32 v162, v168, v171, vcc
	v_cndmask_b32_e32 v184, v170, v198, vcc
	v_cndmask_b32_e32 v175, v172, v199, vcc
	v_cndmask_b32_e32 v173, v174, v200, vcc
	v_lshl_add_u64 v[18:19], v[178:179], 0, s[36:37]
	s_add_i32 m0, s45, 0xc000
	ds_read_b128 v[202:205], v169
	ds_read_b128 v[206:209], v169 offset:1024
	ds_read_b128 v[210:213], v169 offset:2048
	ds_read_b128 v[214:217], v169 offset:3072
	ds_read_b128 v[218:221], v169 offset:4096
	ds_read_b128 v[222:225], v169 offset:5120
	ds_read_b128 v[226:229], v169 offset:6144
	ds_read_b128 v[230:233], v169 offset:7168
	global_load_lds_dwordx4 v[18:19], off
	v_lshl_add_u64 v[18:19], v[176:177], 0, s[36:37]
	s_add_i32 m0, s45, 0xe000
	s_nop 0
	global_load_lds_dwordx4 v[18:19], off
	s_waitcnt lgkmcnt(8)
	s_waitcnt vmcnt(10)
	s_barrier
	s_waitcnt lgkmcnt(0)
	s_waitcnt lgkmcnt(0)
	v_mfma_scale_f32_16x16x128_f8f6f4 v[158:161], v[2:9], v[202:209], v[158:161], v188, v188 op_sel_hi:[0,0,0]
	v_mfma_scale_f32_16x16x128_f8f6f4 v[150:153], v[10:17], v[202:209], v[150:153], v188, v188 op_sel_hi:[0,0,0]
	v_mfma_scale_f32_16x16x128_f8f6f4 v[142:145], v[2:9], v[210:217], v[142:145], v188, v188 op_sel_hi:[0,0,0]
	v_mfma_scale_f32_16x16x128_f8f6f4 v[134:137], v[10:17], v[210:217], v[134:137], v188, v188 op_sel_hi:[0,0,0]
	v_mfma_scale_f32_16x16x128_f8f6f4 v[126:129], v[2:9], v[218:225], v[126:129], v188, v188 op_sel_hi:[0,0,0]
	v_mfma_scale_f32_16x16x128_f8f6f4 v[118:121], v[10:17], v[218:225], v[118:121], v188, v188 op_sel_hi:[0,0,0]
	v_mfma_scale_f32_16x16x128_f8f6f4 v[110:113], v[2:9], v[226:233], v[110:113], v188, v188 op_sel_hi:[0,0,0]
	v_mfma_scale_f32_16x16x128_f8f6f4 v[102:105], v[10:17], v[226:233], v[102:105], v188, v188 op_sel_hi:[0,0,0]
	s_barrier
	s_add_i32 s0, 0, 0x14000
	s_add_i32 s1, s1, s43
	v_add_u32_e32 v30, s0, v197
	v_lshl_add_u64 v[180:181], s[34:35], 0, v[164:165]
	s_mov_b32 m0, s1
	ds_read_b128 v[18:21], v30
	ds_read_b128 v[22:25], v30 offset:1024
	ds_read_b128 v[26:29], v30 offset:2048
	ds_read_b128 v[30:33], v30 offset:3072
	global_load_lds_dwordx4 v[180:181], off
	v_lshl_add_u64 v[182:183], s[34:35], 0, v[166:167]
	s_add_i32 m0, s1, 0x2000
	s_nop 0
	global_load_lds_dwordx4 v[182:183], off
	s_waitcnt vmcnt(10)
	s_barrier
	s_waitcnt lgkmcnt(0)
	s_waitcnt lgkmcnt(0)
	v_mfma_scale_f32_16x16x128_f8f6f4 v[154:157], v[18:25], v[202:209], v[154:157], v188, v188 op_sel_hi:[0,0,0]
	v_mfma_scale_f32_16x16x128_f8f6f4 v[146:149], v[26:33], v[202:209], v[146:149], v188, v188 op_sel_hi:[0,0,0]
	v_mfma_scale_f32_16x16x128_f8f6f4 v[138:141], v[18:25], v[210:217], v[138:141], v188, v188 op_sel_hi:[0,0,0]
	v_mfma_scale_f32_16x16x128_f8f6f4 v[130:133], v[26:33], v[210:217], v[130:133], v188, v188 op_sel_hi:[0,0,0]
	v_mfma_scale_f32_16x16x128_f8f6f4 v[122:125], v[18:25], v[218:225], v[122:125], v188, v188 op_sel_hi:[0,0,0]
	v_mfma_scale_f32_16x16x128_f8f6f4 v[114:117], v[26:33], v[218:225], v[114:117], v188, v188 op_sel_hi:[0,0,0]
	v_mfma_scale_f32_16x16x128_f8f6f4 v[106:109], v[18:25], v[226:233], v[106:109], v188, v188 op_sel_hi:[0,0,0]
	v_mfma_scale_f32_16x16x128_f8f6f4 v[98:101], v[26:33], v[226:233], v[98:101], v188, v188 op_sel_hi:[0,0,0]
	s_mov_b32 m0, s45
	s_barrier
	ds_read_b128 v[202:205], v169 offset:16384
	ds_read_b128 v[206:209], v169 offset:17408
	ds_read_b128 v[210:213], v169 offset:18432
	ds_read_b128 v[214:217], v169 offset:19456
	ds_read_b128 v[218:221], v169 offset:20480
	ds_read_b128 v[222:225], v169 offset:21504
	ds_read_b128 v[226:229], v169 offset:22528
	ds_read_b128 v[230:233], v169 offset:23552
	global_load_lds_dwordx4 v162, s[38:39]
	s_mov_b32 m0, s46
	v_mov_b32_e32 v185, v163
	global_load_lds_dwordx4 v184, s[38:39]
	s_waitcnt vmcnt(10)
	s_barrier
	s_waitcnt lgkmcnt(0)
	v_lshl_add_u64 v[186:187], s[38:39], 0, v[162:163]
	v_lshl_add_u64 v[184:185], s[38:39], 0, v[184:185]
	s_waitcnt lgkmcnt(0)
	v_mfma_scale_f32_16x16x128_f8f6f4 v[94:97], v[2:9], v[202:209], v[94:97], v188, v188 op_sel_hi:[0,0,0]
	v_mfma_scale_f32_16x16x128_f8f6f4 v[86:89], v[10:17], v[202:209], v[86:89], v188, v188 op_sel_hi:[0,0,0]
	v_mfma_scale_f32_16x16x128_f8f6f4 v[78:81], v[2:9], v[210:217], v[78:81], v188, v188 op_sel_hi:[0,0,0]
	v_mfma_scale_f32_16x16x128_f8f6f4 v[70:73], v[10:17], v[210:217], v[70:73], v188, v188 op_sel_hi:[0,0,0]
	v_mfma_scale_f32_16x16x128_f8f6f4 v[62:65], v[2:9], v[218:225], v[62:65], v188, v188 op_sel_hi:[0,0,0]
	v_mfma_scale_f32_16x16x128_f8f6f4 v[54:57], v[10:17], v[218:225], v[54:57], v188, v188 op_sel_hi:[0,0,0]
	v_mfma_scale_f32_16x16x128_f8f6f4 v[46:49], v[2:9], v[226:233], v[46:49], v188, v188 op_sel_hi:[0,0,0]
	v_mfma_scale_f32_16x16x128_f8f6f4 v[38:41], v[10:17], v[226:233], v[38:41], v188, v188 op_sel_hi:[0,0,0]
	s_barrier
	s_add_u32 s36, s34, 0x20000
	s_addc_u32 s37, s35, 0
	s_add_i32 s0, s0, s43
	v_lshl_add_u64 v[2:3], s[36:37], 0, v[164:165]
	s_mov_b32 m0, s0
	s_nop 0
	global_load_lds_dwordx4 v[2:3], off
	v_lshl_add_u64 v[2:3], s[36:37], 0, v[166:167]
	s_add_i32 m0, s0, 0x2000
	s_nop 0
	global_load_lds_dwordx4 v[2:3], off
	s_waitcnt vmcnt(10)
	s_barrier
	v_mfma_scale_f32_16x16x128_f8f6f4 v[90:93], v[18:25], v[202:209], v[90:93], v188, v188 op_sel_hi:[0,0,0]
	v_mfma_scale_f32_16x16x128_f8f6f4 v[82:85], v[26:33], v[202:209], v[82:85], v188, v188 op_sel_hi:[0,0,0]
	v_mfma_scale_f32_16x16x128_f8f6f4 v[74:77], v[18:25], v[210:217], v[74:77], v188, v188 op_sel_hi:[0,0,0]
	v_mfma_scale_f32_16x16x128_f8f6f4 v[66:69], v[26:33], v[210:217], v[66:69], v188, v188 op_sel_hi:[0,0,0]
	v_mfma_scale_f32_16x16x128_f8f6f4 v[58:61], v[18:25], v[218:225], v[58:61], v188, v188 op_sel_hi:[0,0,0]
	v_mfma_scale_f32_16x16x128_f8f6f4 v[50:53], v[26:33], v[218:225], v[50:53], v188, v188 op_sel_hi:[0,0,0]
	v_mfma_scale_f32_16x16x128_f8f6f4 v[42:45], v[18:25], v[226:233], v[42:45], v188, v188 op_sel_hi:[0,0,0]
	v_mfma_scale_f32_16x16x128_f8f6f4 v[34:37], v[26:33], v[226:233], v[34:37], v188, v188 op_sel_hi:[0,0,0]
	s_add_i32 s0, 0, 0x18000
	v_add_u32_e32 v14, s0, v197
	s_barrier
	ds_read_b128 v[2:5], v14
	ds_read_b128 v[6:9], v14 offset:1024
	ds_read_b128 v[10:13], v14 offset:2048
	ds_read_b128 v[14:17], v14 offset:3072
	s_mov_b32 m0, s47
	ds_read_b128 v[18:21], v169 offset:32768
	ds_read_b128 v[22:25], v169 offset:33792
	ds_read_b128 v[26:29], v169 offset:34816
	ds_read_b128 v[30:33], v169 offset:35840
	ds_read_b128 v[202:205], v169 offset:36864
	ds_read_b128 v[206:209], v169 offset:37888
	ds_read_b128 v[210:213], v169 offset:38912
	ds_read_b128 v[214:217], v169 offset:39936
	global_load_lds_dwordx4 v175, s[38:39]
	s_mov_b32 m0, s48
	s_nop 0
	global_load_lds_dwordx4 v173, s[38:39]
	s_waitcnt lgkmcnt(8)
	s_waitcnt vmcnt(10)
	s_barrier
	s_waitcnt lgkmcnt(0)
	s_waitcnt lgkmcnt(0)
	v_mfma_scale_f32_16x16x128_f8f6f4 v[158:161], v[2:9], v[18:25], v[158:161], v188, v188 op_sel_hi:[0,0,0]
	v_mfma_scale_f32_16x16x128_f8f6f4 v[150:153], v[10:17], v[18:25], v[150:153], v188, v188 op_sel_hi:[0,0,0]
	v_mfma_scale_f32_16x16x128_f8f6f4 v[142:145], v[2:9], v[26:33], v[142:145], v188, v188 op_sel_hi:[0,0,0]
	v_mfma_scale_f32_16x16x128_f8f6f4 v[134:137], v[10:17], v[26:33], v[134:137], v188, v188 op_sel_hi:[0,0,0]
	v_mfma_scale_f32_16x16x128_f8f6f4 v[126:129], v[2:9], v[202:209], v[126:129], v188, v188 op_sel_hi:[0,0,0]
	v_mfma_scale_f32_16x16x128_f8f6f4 v[118:121], v[10:17], v[202:209], v[118:121], v188, v188 op_sel_hi:[0,0,0]
	v_mfma_scale_f32_16x16x128_f8f6f4 v[110:113], v[2:9], v[210:217], v[110:113], v188, v188 op_sel_hi:[0,0,0]
	v_mfma_scale_f32_16x16x128_f8f6f4 v[102:105], v[10:17], v[210:217], v[102:105], v188, v188 op_sel_hi:[0,0,0]
	s_barrier
	s_add_i32 s36, 0, 0x1c000
	s_add_i32 s0, s0, s43
	v_add_u32_e32 v162, s36, v197
	v_lshl_add_u64 v[180:181], v[180:181], 0, s[22:23]
	s_mov_b32 m0, s0
	ds_read_b128 v[218:221], v162
	ds_read_b128 v[222:225], v162 offset:1024
	ds_read_b128 v[226:229], v162 offset:2048
	ds_read_b128 v[230:233], v162 offset:3072
	global_load_lds_dwordx4 v[180:181], off
	v_lshl_add_u64 v[180:181], v[182:183], 0, s[22:23]
	s_add_i32 m0, s0, 0x2000
	s_nop 0
	global_load_lds_dwordx4 v[180:181], off
	s_waitcnt vmcnt(10)
	s_barrier
	s_waitcnt lgkmcnt(0)
	s_waitcnt lgkmcnt(0)
	v_mfma_scale_f32_16x16x128_f8f6f4 v[154:157], v[218:225], v[18:25], v[154:157], v188, v188 op_sel_hi:[0,0,0]
	v_mfma_scale_f32_16x16x128_f8f6f4 v[146:149], v[226:233], v[18:25], v[146:149], v188, v188 op_sel_hi:[0,0,0]
	v_mfma_scale_f32_16x16x128_f8f6f4 v[138:141], v[218:225], v[26:33], v[138:141], v188, v188 op_sel_hi:[0,0,0]
	v_mfma_scale_f32_16x16x128_f8f6f4 v[130:133], v[226:233], v[26:33], v[130:133], v188, v188 op_sel_hi:[0,0,0]
	v_mfma_scale_f32_16x16x128_f8f6f4 v[122:125], v[218:225], v[202:209], v[122:125], v188, v188 op_sel_hi:[0,0,0]
	v_mfma_scale_f32_16x16x128_f8f6f4 v[114:117], v[226:233], v[202:209], v[114:117], v188, v188 op_sel_hi:[0,0,0]
	v_mfma_scale_f32_16x16x128_f8f6f4 v[106:109], v[218:225], v[210:217], v[106:109], v188, v188 op_sel_hi:[0,0,0]
	v_mfma_scale_f32_16x16x128_f8f6f4 v[98:101], v[226:233], v[210:217], v[98:101], v188, v188 op_sel_hi:[0,0,0]
	s_mov_b32 m0, s51
	v_lshl_add_u64 v[180:181], v[186:187], 0, s[22:23]
	s_barrier
	ds_read_b128 v[18:21], v169 offset:49152
	ds_read_b128 v[22:25], v169 offset:50176
	ds_read_b128 v[26:29], v169 offset:51200
	ds_read_b128 v[30:33], v169 offset:52224
	ds_read_b128 v[202:205], v169 offset:53248
	ds_read_b128 v[206:209], v169 offset:54272
	ds_read_b128 v[210:213], v169 offset:55296
	ds_read_b128 v[214:217], v169 offset:56320
	global_load_lds_dwordx4 v[180:181], off
	v_lshl_add_u64 v[180:181], v[184:185], 0, s[22:23]
	s_mov_b32 m0, s52
	s_nop 0
	global_load_lds_dwordx4 v[180:181], off
	s_waitcnt vmcnt(10)
	s_barrier
	s_waitcnt lgkmcnt(0)
	s_waitcnt lgkmcnt(0)
	v_mfma_scale_f32_16x16x128_f8f6f4 v[94:97], v[2:9], v[18:25], v[94:97], v188, v188 op_sel_hi:[0,0,0]
	v_mfma_scale_f32_16x16x128_f8f6f4 v[86:89], v[10:17], v[18:25], v[86:89], v188, v188 op_sel_hi:[0,0,0]
	v_mfma_scale_f32_16x16x128_f8f6f4 v[78:81], v[2:9], v[26:33], v[78:81], v188, v188 op_sel_hi:[0,0,0]
	v_mfma_scale_f32_16x16x128_f8f6f4 v[70:73], v[10:17], v[26:33], v[70:73], v188, v188 op_sel_hi:[0,0,0]
	v_mfma_scale_f32_16x16x128_f8f6f4 v[62:65], v[2:9], v[202:209], v[62:65], v188, v188 op_sel_hi:[0,0,0]
	v_mfma_scale_f32_16x16x128_f8f6f4 v[54:57], v[10:17], v[202:209], v[54:57], v188, v188 op_sel_hi:[0,0,0]
	v_mfma_scale_f32_16x16x128_f8f6f4 v[46:49], v[2:9], v[210:217], v[46:49], v188, v188 op_sel_hi:[0,0,0]
	v_mfma_scale_f32_16x16x128_f8f6f4 v[38:41], v[10:17], v[210:217], v[38:41], v188, v188 op_sel_hi:[0,0,0]
	s_barrier
	s_add_u32 s0, s34, 0x20080
	s_addc_u32 s1, s35, 0
	s_add_i32 s34, s36, s43
	v_lshl_add_u64 v[2:3], s[0:1], 0, v[164:165]
	s_mov_b32 m0, s34
	s_nop 0
	global_load_lds_dwordx4 v[2:3], off
	v_lshl_add_u64 v[2:3], s[0:1], 0, v[166:167]
	s_add_i32 m0, s34, 0x2000
	s_nop 0
	global_load_lds_dwordx4 v[2:3], off
	s_waitcnt vmcnt(10)
	s_barrier
	v_mfma_scale_f32_16x16x128_f8f6f4 v[90:93], v[218:225], v[18:25], v[90:93], v188, v188 op_sel_hi:[0,0,0]
	v_mfma_scale_f32_16x16x128_f8f6f4 v[82:85], v[226:233], v[18:25], v[82:85], v188, v188 op_sel_hi:[0,0,0]
	v_mfma_scale_f32_16x16x128_f8f6f4 v[74:77], v[218:225], v[26:33], v[74:77], v188, v188 op_sel_hi:[0,0,0]
	v_mfma_scale_f32_16x16x128_f8f6f4 v[66:69], v[226:233], v[26:33], v[66:69], v188, v188 op_sel_hi:[0,0,0]
	v_mfma_scale_f32_16x16x128_f8f6f4 v[58:61], v[218:225], v[202:209], v[58:61], v188, v188 op_sel_hi:[0,0,0]
	v_mfma_scale_f32_16x16x128_f8f6f4 v[50:53], v[226:233], v[202:209], v[50:53], v188, v188 op_sel_hi:[0,0,0]
	v_mfma_scale_f32_16x16x128_f8f6f4 v[42:45], v[218:225], v[210:217], v[42:45], v188, v188 op_sel_hi:[0,0,0]
	v_mfma_scale_f32_16x16x128_f8f6f4 v[34:37], v[226:233], v[210:217], v[34:37], v188, v188 op_sel_hi:[0,0,0]
	s_add_i32 s56, s56, 2
	s_cmp_gt_u32 s56, 5
	s_mov_b64 s[36:37], s[12:13]
	s_barrier
	s_cbranch_scc0 .LBB0_1302
	v_mul_f32_e32 v5, 0x3b000000, v158
	v_mul_f32_e32 v6, 0xbcb8aa3b, v158
	v_exp_f32_e32 v6, v6
	s_ashr_i32 s31, s30, 31
	s_ashr_i32 s29, s28, 31
	s_lshl_b64 s[12:13], s[30:31], 18
	v_add_f32_e32 v6, 1.0, v6
	v_rcp_f32_e32 v6, v6
	s_lshl_b64 s[28:29], s[28:29], 15
	v_mov_b32_e32 v3, v195
	s_add_u32 s0, s6, s12
	v_mul_f32_e32 v5, v5, v6
	v_mul_f32_e32 v6, 0x3b000000, v159
	v_mul_f32_e32 v7, 0xbcb8aa3b, v159
	v_exp_f32_e32 v7, v7
	v_mul_f32_e32 v5, v5, v154
	v_med3_f32 v5, v5, s40, v190
	v_add_f32_e32 v7, 1.0, v7
	v_rcp_f32_e32 v7, v7
	s_nop 15
	s_nop 15
	v_mov_b32_e32 v2, v196
	v_mul_f32_e32 v6, v6, v7
	v_mul_f32_e32 v7, 0x3b000000, v160
	v_mul_f32_e32 v8, 0xbcb8aa3b, v160
	v_exp_f32_e32 v8, v8
	v_mul_f32_e32 v6, v6, v155
	v_add_u32_e32 v4, s49, v3
	v_add_f32_e32 v8, 1.0, v8
	v_rcp_f32_e32 v8, v8
	s_addc_u32 s1, s7, s13
	s_add_u32 s12, s0, s28
	v_mul_f32_e32 v7, v7, v8
	v_mul_f32_e32 v8, 0x3b000000, v161
	v_mul_f32_e32 v9, 0xbcb8aa3b, v161
	v_exp_f32_e32 v9, v9
	v_mul_f32_e32 v7, v7, v156
	v_lshl_add_u32 v2, v2, 3, s50
	v_add_f32_e32 v9, 1.0, v9
	v_rcp_f32_e32 v9, v9
	s_addc_u32 s13, s1, s29
	v_ashrrev_i32_e32 v3, 31, v2
	s_and_b64 vcc, exec, s[8:9]
	v_mul_f32_e32 v8, v8, v9
	v_mul_f32_e32 v9, 0x3b000000, v150
	v_mul_f32_e32 v10, 0xbcb8aa3b, v150
	v_exp_f32_e32 v10, v10
	v_mul_f32_e32 v8, v8, v157
	v_mov_b32_e32 v174, v200
	v_add_f32_e32 v10, 1.0, v10
	v_rcp_f32_e32 v10, v10
	v_mov_b32_e32 v172, v199
	v_mov_b32_e32 v170, v198
	v_mov_b32_e32 v168, v171
	v_mul_f32_e32 v9, v9, v10
	v_mul_f32_e32 v10, 0x3b000000, v151
	v_mul_f32_e32 v11, 0xbcb8aa3b, v151
	v_exp_f32_e32 v11, v11
	v_mul_f32_e32 v9, v9, v146
	s_mov_b32 s28, s26
	v_add_f32_e32 v11, 1.0, v11
	v_rcp_f32_e32 v11, v11
	s_mov_b32 s30, s54
	s_mov_b64 s[34:35], s[14:15]
	v_mul_f32_e32 v10, v10, v11
	v_mul_f32_e32 v11, 0x3b000000, v152
	v_mul_f32_e32 v12, 0xbcb8aa3b, v152
	v_exp_f32_e32 v12, v12
	v_mul_f32_e32 v10, v10, v147
	v_add_f32_e32 v12, 1.0, v12
	v_rcp_f32_e32 v12, v12
	s_nop 0
	v_mul_f32_e32 v11, v11, v12
	v_mul_f32_e32 v12, 0x3b000000, v153
	v_mul_f32_e32 v13, 0xbcb8aa3b, v153
	v_exp_f32_e32 v13, v13
	v_mul_f32_e32 v11, v11, v148
	v_add_f32_e32 v13, 1.0, v13
	v_rcp_f32_e32 v13, v13
	s_nop 0
	v_mul_f32_e32 v12, v12, v13
	v_med3_f32 v13, v6, s40, v190
	v_mov_b32_e32 v6, v163
	v_cvt_pk_fp8_f32 v6, v5, v13
	v_med3_f32 v5, v7, s40, v190
	v_med3_f32 v7, v8, s40, v190
	v_med3_f32 v8, v10, s40, v190
	v_cvt_pk_fp8_f32 v6, v5, v7 op_sel:[0,0,1]
	v_med3_f32 v5, v9, s40, v190
	v_mov_b32_e32 v7, v163
	v_cvt_pk_fp8_f32 v7, v5, v8
	v_mul_f32_e32 v12, v12, v149
	v_med3_f32 v5, v11, s40, v190
	v_med3_f32 v8, v12, s40, v190
	v_cvt_pk_fp8_f32 v7, v5, v8 op_sel:[0,0,1]
	v_ashrrev_i32_e32 v5, 31, v4
	v_lshlrev_b64 v[8:9], 7, v[4:5]
	v_lshl_add_u64 v[8:9], s[12:13], 0, v[8:9]
	v_lshl_add_u64 v[8:9], v[8:9], 0, v[2:3]
	v_mul_f32_e32 v5, 0x3b000000, v142
	global_store_dwordx2 v[8:9], v[6:7], off
	v_mul_f32_e32 v6, 0xbcb8aa3b, v142
	v_exp_f32_e32 v6, v6
	s_nop 0
	v_add_f32_e32 v6, 1.0, v6
	v_rcp_f32_e32 v6, v6
	s_nop 0
	v_mul_f32_e32 v5, v5, v6
	v_mul_f32_e32 v6, 0x3b000000, v143
	v_mul_f32_e32 v7, 0xbcb8aa3b, v143
	v_exp_f32_e32 v7, v7
	v_mul_f32_e32 v5, v5, v138
	v_med3_f32 v5, v5, s40, v190
	v_add_f32_e32 v7, 1.0, v7
	v_rcp_f32_e32 v7, v7
	s_nop 0
	v_mul_f32_e32 v6, v6, v7
	v_mul_f32_e32 v7, v6, v139
	v_mul_f32_e32 v6, 0x3b000000, v144
	v_mul_f32_e32 v8, 0xbcb8aa3b, v144
	v_exp_f32_e32 v8, v8
	v_med3_f32 v7, v7, s40, v190
	v_add_f32_e32 v8, 1.0, v8
	v_rcp_f32_e32 v8, v8
	s_nop 0
	v_mul_f32_e32 v6, v6, v8
	v_mul_f32_e32 v9, v6, v140
	v_mul_f32_e32 v6, 0x3b000000, v145
	v_mul_f32_e32 v8, 0xbcb8aa3b, v145
	v_exp_f32_e32 v8, v8
	s_nop 0
	v_add_f32_e32 v8, 1.0, v8
	v_rcp_f32_e32 v8, v8
	s_nop 0
	v_mul_f32_e32 v6, v6, v8
	v_mul_f32_e32 v10, v6, v141
	v_mul_f32_e32 v6, 0x3b000000, v134
	v_mul_f32_e32 v8, 0xbcb8aa3b, v134
	v_exp_f32_e32 v8, v8
	s_nop 0
	v_add_f32_e32 v8, 1.0, v8
	v_rcp_f32_e32 v8, v8
	s_nop 0
	v_mul_f32_e32 v6, v6, v8
	v_mul_f32_e32 v11, v6, v130
	v_mul_f32_e32 v6, 0x3b000000, v135
	v_mul_f32_e32 v8, 0xbcb8aa3b, v135
	v_exp_f32_e32 v8, v8
	s_nop 0
	v_add_f32_e32 v8, 1.0, v8
	v_rcp_f32_e32 v8, v8
	s_nop 0
	v_mul_f32_e32 v6, v6, v8
	v_mul_f32_e32 v12, v6, v131
	v_mul_f32_e32 v6, 0x3b000000, v136
	v_mul_f32_e32 v8, 0xbcb8aa3b, v136
	v_exp_f32_e32 v8, v8
	s_nop 0
	v_add_f32_e32 v8, 1.0, v8
	v_rcp_f32_e32 v8, v8
	s_nop 0
	v_mul_f32_e32 v6, v6, v8
	v_mul_f32_e32 v13, v6, v132
	v_mul_f32_e32 v6, 0x3b000000, v137
	v_mul_f32_e32 v8, 0xbcb8aa3b, v137
	v_exp_f32_e32 v8, v8
	s_nop 0
	v_add_f32_e32 v8, 1.0, v8
	v_rcp_f32_e32 v8, v8
	s_nop 0
	v_mul_f32_e32 v6, v6, v8
	v_mov_b32_e32 v8, v163
	v_cvt_pk_fp8_f32 v8, v5, v7
	v_med3_f32 v5, v9, s40, v190
	v_med3_f32 v7, v10, s40, v190
	v_mov_b32_e32 v9, v163
	v_cvt_pk_fp8_f32 v8, v5, v7 op_sel:[0,0,1]
	v_med3_f32 v5, v11, s40, v190
	v_med3_f32 v7, v12, s40, v190
	v_cvt_pk_fp8_f32 v9, v5, v7
	v_mul_f32_e32 v14, v6, v133
	v_add_u32_e32 v6, 16, v4
	v_med3_f32 v5, v13, s40, v190
	v_med3_f32 v7, v14, s40, v190
	v_cvt_pk_fp8_f32 v9, v5, v7 op_sel:[0,0,1]
	v_ashrrev_i32_e32 v7, 31, v6
	v_lshlrev_b64 v[6:7], 7, v[6:7]
	v_lshl_add_u64 v[6:7], s[12:13], 0, v[6:7]
	v_lshl_add_u64 v[6:7], v[6:7], 0, v[2:3]
	v_mul_f32_e32 v5, 0x3b000000, v126
	global_store_dwordx2 v[6:7], v[8:9], off
	v_mul_f32_e32 v6, 0xbcb8aa3b, v126
	v_exp_f32_e32 v6, v6
	s_nop 0
	v_add_f32_e32 v6, 1.0, v6
	v_rcp_f32_e32 v6, v6
	s_nop 0
	v_mul_f32_e32 v5, v5, v6
	v_mul_f32_e32 v6, 0x3b000000, v127
	v_mul_f32_e32 v7, 0xbcb8aa3b, v127
	v_exp_f32_e32 v7, v7
	v_mul_f32_e32 v5, v5, v122
	v_med3_f32 v5, v5, s40, v190
	v_add_f32_e32 v7, 1.0, v7
	v_rcp_f32_e32 v7, v7
	s_nop 0
	v_mul_f32_e32 v6, v6, v7
	v_mul_f32_e32 v7, v6, v123
	v_mul_f32_e32 v6, 0x3b000000, v128
	v_mul_f32_e32 v8, 0xbcb8aa3b, v128
	v_exp_f32_e32 v8, v8
	v_med3_f32 v7, v7, s40, v190
	v_add_f32_e32 v8, 1.0, v8
	v_rcp_f32_e32 v8, v8
	s_nop 0
	v_mul_f32_e32 v6, v6, v8
	v_mul_f32_e32 v9, v6, v124
	v_mul_f32_e32 v6, 0x3b000000, v129
	v_mul_f32_e32 v8, 0xbcb8aa3b, v129
	v_exp_f32_e32 v8, v8
	s_nop 0
	v_add_f32_e32 v8, 1.0, v8
	v_rcp_f32_e32 v8, v8
	s_nop 0
	v_mul_f32_e32 v6, v6, v8
	v_mul_f32_e32 v10, v6, v125
	v_mul_f32_e32 v6, 0x3b000000, v118
	v_mul_f32_e32 v8, 0xbcb8aa3b, v118
	v_exp_f32_e32 v8, v8
	s_nop 0
	v_add_f32_e32 v8, 1.0, v8
	v_rcp_f32_e32 v8, v8
	s_nop 0
	v_mul_f32_e32 v6, v6, v8
	v_mul_f32_e32 v11, v6, v114
	v_mul_f32_e32 v6, 0x3b000000, v119
	v_mul_f32_e32 v8, 0xbcb8aa3b, v119
	v_exp_f32_e32 v8, v8
	s_nop 0
	v_add_f32_e32 v8, 1.0, v8
	v_rcp_f32_e32 v8, v8
	s_nop 0
	v_mul_f32_e32 v6, v6, v8
	v_mul_f32_e32 v12, v6, v115
	v_mul_f32_e32 v6, 0x3b000000, v120
	v_mul_f32_e32 v8, 0xbcb8aa3b, v120
	v_exp_f32_e32 v8, v8
	s_nop 0
	v_add_f32_e32 v8, 1.0, v8
	v_rcp_f32_e32 v8, v8
	s_nop 0
	v_mul_f32_e32 v6, v6, v8
	v_mul_f32_e32 v13, v6, v116
	v_mul_f32_e32 v6, 0x3b000000, v121
	v_mul_f32_e32 v8, 0xbcb8aa3b, v121
	v_exp_f32_e32 v8, v8
	s_nop 0
	v_add_f32_e32 v8, 1.0, v8
	v_rcp_f32_e32 v8, v8
	s_nop 0
	v_mul_f32_e32 v6, v6, v8
	v_mov_b32_e32 v8, v163
	v_cvt_pk_fp8_f32 v8, v5, v7
	v_med3_f32 v5, v9, s40, v190
	v_med3_f32 v7, v10, s40, v190
	v_mov_b32_e32 v9, v163
	v_cvt_pk_fp8_f32 v8, v5, v7 op_sel:[0,0,1]
	v_med3_f32 v5, v11, s40, v190
	v_med3_f32 v7, v12, s40, v190
	v_cvt_pk_fp8_f32 v9, v5, v7
	v_mul_f32_e32 v14, v6, v117
	v_add_u32_e32 v6, 32, v4
	v_med3_f32 v5, v13, s40, v190
	v_med3_f32 v7, v14, s40, v190
	v_cvt_pk_fp8_f32 v9, v5, v7 op_sel:[0,0,1]
	v_ashrrev_i32_e32 v7, 31, v6
	v_lshlrev_b64 v[6:7], 7, v[6:7]
	v_lshl_add_u64 v[6:7], s[12:13], 0, v[6:7]
	v_lshl_add_u64 v[6:7], v[6:7], 0, v[2:3]
	v_mul_f32_e32 v5, 0x3b000000, v110
	global_store_dwordx2 v[6:7], v[8:9], off
	v_mul_f32_e32 v6, 0xbcb8aa3b, v110
	v_exp_f32_e32 v6, v6
	s_nop 0
	v_add_f32_e32 v6, 1.0, v6
	v_rcp_f32_e32 v6, v6
	s_nop 0
	v_mul_f32_e32 v5, v5, v6
	v_mul_f32_e32 v6, 0x3b000000, v111
	v_mul_f32_e32 v7, 0xbcb8aa3b, v111
	v_exp_f32_e32 v7, v7
	v_mul_f32_e32 v5, v5, v106
	v_med3_f32 v5, v5, s40, v190
	v_add_f32_e32 v7, 1.0, v7
	v_rcp_f32_e32 v7, v7
	s_nop 0
	v_mul_f32_e32 v6, v6, v7
	v_mul_f32_e32 v7, v6, v107
	v_mul_f32_e32 v6, 0x3b000000, v112
	v_mul_f32_e32 v8, 0xbcb8aa3b, v112
	v_exp_f32_e32 v8, v8
	v_med3_f32 v7, v7, s40, v190
	v_add_f32_e32 v8, 1.0, v8
	v_rcp_f32_e32 v8, v8
	s_nop 0
	v_mul_f32_e32 v6, v6, v8
	v_mul_f32_e32 v9, v6, v108
	v_mul_f32_e32 v6, 0x3b000000, v113
	v_mul_f32_e32 v8, 0xbcb8aa3b, v113
	v_exp_f32_e32 v8, v8
	s_nop 0
	v_add_f32_e32 v8, 1.0, v8
	v_rcp_f32_e32 v8, v8
	s_nop 0
	v_mul_f32_e32 v6, v6, v8
	v_mul_f32_e32 v10, v6, v109
	v_mul_f32_e32 v6, 0x3b000000, v102
	v_mul_f32_e32 v8, 0xbcb8aa3b, v102
	v_exp_f32_e32 v8, v8
	s_nop 0
	v_add_f32_e32 v8, 1.0, v8
	v_rcp_f32_e32 v8, v8
	s_nop 0
	v_mul_f32_e32 v6, v6, v8
	v_mul_f32_e32 v11, v6, v98
	v_mul_f32_e32 v6, 0x3b000000, v103
	v_mul_f32_e32 v8, 0xbcb8aa3b, v103
	v_exp_f32_e32 v8, v8
	s_nop 0
	v_add_f32_e32 v8, 1.0, v8
	v_rcp_f32_e32 v8, v8
	s_nop 0
	v_mul_f32_e32 v6, v6, v8
	v_mul_f32_e32 v12, v6, v99
	v_mul_f32_e32 v6, 0x3b000000, v104
	v_mul_f32_e32 v8, 0xbcb8aa3b, v104
	v_exp_f32_e32 v8, v8
	s_nop 0
	v_add_f32_e32 v8, 1.0, v8
	v_rcp_f32_e32 v8, v8
	s_nop 0
	v_mul_f32_e32 v6, v6, v8
	v_mul_f32_e32 v13, v6, v100
	v_mul_f32_e32 v6, 0x3b000000, v105
	v_mul_f32_e32 v8, 0xbcb8aa3b, v105
	v_exp_f32_e32 v8, v8
	s_nop 0
	v_add_f32_e32 v8, 1.0, v8
	v_rcp_f32_e32 v8, v8
	s_nop 0
	v_mul_f32_e32 v6, v6, v8
	v_mov_b32_e32 v8, v163
	v_cvt_pk_fp8_f32 v8, v5, v7
	v_med3_f32 v5, v9, s40, v190
	v_med3_f32 v7, v10, s40, v190
	v_mov_b32_e32 v9, v163
	v_cvt_pk_fp8_f32 v8, v5, v7 op_sel:[0,0,1]
	v_med3_f32 v5, v11, s40, v190
	v_med3_f32 v7, v12, s40, v190
	v_cvt_pk_fp8_f32 v9, v5, v7
	v_mul_f32_e32 v14, v6, v101
	v_add_u32_e32 v6, 48, v4
	v_med3_f32 v5, v13, s40, v190
	v_med3_f32 v7, v14, s40, v190
	v_cvt_pk_fp8_f32 v9, v5, v7 op_sel:[0,0,1]
	v_ashrrev_i32_e32 v7, 31, v6
	v_lshlrev_b64 v[6:7], 7, v[6:7]
	v_lshl_add_u64 v[6:7], s[12:13], 0, v[6:7]
	v_lshl_add_u64 v[6:7], v[6:7], 0, v[2:3]
	v_mul_f32_e32 v5, 0x3b000000, v94
	global_store_dwordx2 v[6:7], v[8:9], off
	v_mul_f32_e32 v7, 0xbcb8aa3b, v94
	v_exp_f32_e32 v7, v7
	v_add_u32_e32 v6, 0x80, v4
	v_add_f32_e32 v7, 1.0, v7
	v_rcp_f32_e32 v7, v7
	s_nop 0
	v_mul_f32_e32 v5, v5, v7
	v_mul_f32_e32 v7, 0x3b000000, v95
	v_mul_f32_e32 v8, 0xbcb8aa3b, v95
	v_exp_f32_e32 v8, v8
	v_mul_f32_e32 v5, v5, v90
	v_med3_f32 v5, v5, s40, v190
	v_add_f32_e32 v8, 1.0, v8
	v_rcp_f32_e32 v8, v8
	s_nop 0
	v_mul_f32_e32 v7, v7, v8
	v_mul_f32_e32 v8, 0x3b000000, v96
	v_mul_f32_e32 v9, 0xbcb8aa3b, v96
	v_exp_f32_e32 v9, v9
	v_mul_f32_e32 v7, v7, v91
	v_med3_f32 v7, v7, s40, v190
	v_add_f32_e32 v9, 1.0, v9
	v_rcp_f32_e32 v9, v9
	s_nop 0
	v_mul_f32_e32 v8, v8, v9
	v_mul_f32_e32 v9, v8, v92
	v_mul_f32_e32 v8, 0x3b000000, v97
	v_mul_f32_e32 v10, 0xbcb8aa3b, v97
	v_exp_f32_e32 v10, v10
	s_nop 0
	v_add_f32_e32 v10, 1.0, v10
	v_rcp_f32_e32 v10, v10
	s_nop 0
	v_mul_f32_e32 v8, v8, v10
	v_mul_f32_e32 v10, v8, v93
	v_mul_f32_e32 v8, 0x3b000000, v86
	v_mul_f32_e32 v11, 0xbcb8aa3b, v86
	v_exp_f32_e32 v11, v11
	s_nop 0
	v_add_f32_e32 v11, 1.0, v11
	v_rcp_f32_e32 v11, v11
	s_nop 0
	v_mul_f32_e32 v8, v8, v11
	v_mul_f32_e32 v11, v8, v82
	v_mul_f32_e32 v8, 0x3b000000, v87
	v_mul_f32_e32 v12, 0xbcb8aa3b, v87
	v_exp_f32_e32 v12, v12
	s_nop 0
	v_add_f32_e32 v12, 1.0, v12
	v_rcp_f32_e32 v12, v12
	s_nop 0
	v_mul_f32_e32 v8, v8, v12
	v_mul_f32_e32 v12, v8, v83
	v_mul_f32_e32 v8, 0x3b000000, v88
	v_mul_f32_e32 v13, 0xbcb8aa3b, v88
	v_exp_f32_e32 v13, v13
	s_nop 0
	v_add_f32_e32 v13, 1.0, v13
	v_rcp_f32_e32 v13, v13
	s_nop 0
	v_mul_f32_e32 v8, v8, v13
	v_mul_f32_e32 v13, v8, v84
	v_mul_f32_e32 v8, 0x3b000000, v89
	v_mul_f32_e32 v14, 0xbcb8aa3b, v89
	v_exp_f32_e32 v14, v14
	s_nop 0
	v_add_f32_e32 v14, 1.0, v14
	v_rcp_f32_e32 v14, v14
	s_nop 0
	v_mul_f32_e32 v8, v8, v14
	v_mul_f32_e32 v14, v8, v85
	v_mov_b32_e32 v8, v163
	v_cvt_pk_fp8_f32 v8, v5, v7
	v_med3_f32 v5, v9, s40, v190
	v_med3_f32 v7, v10, s40, v190
	v_mov_b32_e32 v9, v163
	v_cvt_pk_fp8_f32 v8, v5, v7 op_sel:[0,0,1]
	v_med3_f32 v5, v11, s40, v190
	v_med3_f32 v7, v12, s40, v190
	v_cvt_pk_fp8_f32 v9, v5, v7
	v_med3_f32 v5, v13, s40, v190
	v_med3_f32 v7, v14, s40, v190
	v_cvt_pk_fp8_f32 v9, v5, v7 op_sel:[0,0,1]
	v_ashrrev_i32_e32 v7, 31, v6
	v_lshlrev_b64 v[6:7], 7, v[6:7]
	v_lshl_add_u64 v[6:7], s[12:13], 0, v[6:7]
	v_lshl_add_u64 v[6:7], v[6:7], 0, v[2:3]
	v_mul_f32_e32 v5, 0x3b000000, v78
	global_store_dwordx2 v[6:7], v[8:9], off
	v_mul_f32_e32 v6, 0xbcb8aa3b, v78
	v_exp_f32_e32 v6, v6
	s_nop 0
	v_add_f32_e32 v6, 1.0, v6
	v_rcp_f32_e32 v6, v6
	s_nop 0
	v_mul_f32_e32 v5, v5, v6
	v_mul_f32_e32 v6, 0x3b000000, v79
	v_mul_f32_e32 v7, 0xbcb8aa3b, v79
	v_exp_f32_e32 v7, v7
	v_mul_f32_e32 v5, v5, v74
	v_med3_f32 v5, v5, s40, v190
	v_add_f32_e32 v7, 1.0, v7
	v_rcp_f32_e32 v7, v7
	s_nop 0
	v_mul_f32_e32 v6, v6, v7
	v_mul_f32_e32 v7, v6, v75
	v_mul_f32_e32 v6, 0x3b000000, v80
	v_mul_f32_e32 v8, 0xbcb8aa3b, v80
	v_exp_f32_e32 v8, v8
	v_med3_f32 v7, v7, s40, v190
	v_add_f32_e32 v8, 1.0, v8
	v_rcp_f32_e32 v8, v8
	s_nop 0
	v_mul_f32_e32 v6, v6, v8
	v_mul_f32_e32 v9, v6, v76
	v_mul_f32_e32 v6, 0x3b000000, v81
	v_mul_f32_e32 v8, 0xbcb8aa3b, v81
	v_exp_f32_e32 v8, v8
	s_nop 0
	v_add_f32_e32 v8, 1.0, v8
	v_rcp_f32_e32 v8, v8
	s_nop 0
	v_mul_f32_e32 v6, v6, v8
	v_mul_f32_e32 v10, v6, v77
	v_mul_f32_e32 v6, 0x3b000000, v70
	v_mul_f32_e32 v8, 0xbcb8aa3b, v70
	v_exp_f32_e32 v8, v8
	s_nop 0
	v_add_f32_e32 v8, 1.0, v8
	v_rcp_f32_e32 v8, v8
	s_nop 0
	v_mul_f32_e32 v6, v6, v8
	v_mul_f32_e32 v11, v6, v66
	v_mul_f32_e32 v6, 0x3b000000, v71
	v_mul_f32_e32 v8, 0xbcb8aa3b, v71
	v_exp_f32_e32 v8, v8
	s_nop 0
	v_add_f32_e32 v8, 1.0, v8
	v_rcp_f32_e32 v8, v8
	s_nop 0
	v_mul_f32_e32 v6, v6, v8
	v_mul_f32_e32 v12, v6, v67
	v_mul_f32_e32 v6, 0x3b000000, v72
	v_mul_f32_e32 v8, 0xbcb8aa3b, v72
	v_exp_f32_e32 v8, v8
	s_nop 0
	v_add_f32_e32 v8, 1.0, v8
	v_rcp_f32_e32 v8, v8
	s_nop 0
	v_mul_f32_e32 v6, v6, v8
	v_mul_f32_e32 v13, v6, v68
	v_mul_f32_e32 v6, 0x3b000000, v73
	v_mul_f32_e32 v8, 0xbcb8aa3b, v73
	v_exp_f32_e32 v8, v8
	s_nop 0
	v_add_f32_e32 v8, 1.0, v8
	v_rcp_f32_e32 v8, v8
	s_nop 0
	v_mul_f32_e32 v6, v6, v8
	v_mov_b32_e32 v8, v163
	v_cvt_pk_fp8_f32 v8, v5, v7
	v_med3_f32 v5, v9, s40, v190
	v_med3_f32 v7, v10, s40, v190
	v_mov_b32_e32 v9, v163
	v_cvt_pk_fp8_f32 v8, v5, v7 op_sel:[0,0,1]
	v_med3_f32 v5, v11, s40, v190
	v_med3_f32 v7, v12, s40, v190
	v_cvt_pk_fp8_f32 v9, v5, v7
	v_mul_f32_e32 v14, v6, v69
	v_add_u32_e32 v6, 0x90, v4
	v_med3_f32 v5, v13, s40, v190
	v_med3_f32 v7, v14, s40, v190
	v_cvt_pk_fp8_f32 v9, v5, v7 op_sel:[0,0,1]
	v_ashrrev_i32_e32 v7, 31, v6
	v_lshlrev_b64 v[6:7], 7, v[6:7]
	v_lshl_add_u64 v[6:7], s[12:13], 0, v[6:7]
	v_lshl_add_u64 v[6:7], v[6:7], 0, v[2:3]
	v_mul_f32_e32 v5, 0x3b000000, v62
	global_store_dwordx2 v[6:7], v[8:9], off
	v_mul_f32_e32 v6, 0xbcb8aa3b, v62
	v_exp_f32_e32 v6, v6
	s_nop 0
	v_add_f32_e32 v6, 1.0, v6
	v_rcp_f32_e32 v6, v6
	s_nop 0
	v_mul_f32_e32 v5, v5, v6
	v_mul_f32_e32 v6, 0x3b000000, v63
	v_mul_f32_e32 v7, 0xbcb8aa3b, v63
	v_exp_f32_e32 v7, v7
	v_mul_f32_e32 v5, v5, v58
	v_med3_f32 v5, v5, s40, v190
	v_add_f32_e32 v7, 1.0, v7
	v_rcp_f32_e32 v7, v7
	s_nop 0
	v_mul_f32_e32 v6, v6, v7
	v_mul_f32_e32 v7, v6, v59
	v_mul_f32_e32 v6, 0x3b000000, v64
	v_mul_f32_e32 v8, 0xbcb8aa3b, v64
	v_exp_f32_e32 v8, v8
	v_med3_f32 v7, v7, s40, v190
	v_add_f32_e32 v8, 1.0, v8
	v_rcp_f32_e32 v8, v8
	s_nop 0
	v_mul_f32_e32 v6, v6, v8
	v_mul_f32_e32 v9, v6, v60
	v_mul_f32_e32 v6, 0x3b000000, v65
	v_mul_f32_e32 v8, 0xbcb8aa3b, v65
	v_exp_f32_e32 v8, v8
	s_nop 0
	v_add_f32_e32 v8, 1.0, v8
	v_rcp_f32_e32 v8, v8
	s_nop 0
	v_mul_f32_e32 v6, v6, v8
	v_mul_f32_e32 v10, v6, v61
	v_mul_f32_e32 v6, 0x3b000000, v54
	v_mul_f32_e32 v8, 0xbcb8aa3b, v54
	v_exp_f32_e32 v8, v8
	s_nop 0
	v_add_f32_e32 v8, 1.0, v8
	v_rcp_f32_e32 v8, v8
	s_nop 0
	v_mul_f32_e32 v6, v6, v8
	v_mul_f32_e32 v11, v6, v50
	v_mul_f32_e32 v6, 0x3b000000, v55
	v_mul_f32_e32 v8, 0xbcb8aa3b, v55
	v_exp_f32_e32 v8, v8
	s_nop 0
	v_add_f32_e32 v8, 1.0, v8
	v_rcp_f32_e32 v8, v8
	s_nop 0
	v_mul_f32_e32 v6, v6, v8
	v_mul_f32_e32 v12, v6, v51
	v_mul_f32_e32 v6, 0x3b000000, v56
	v_mul_f32_e32 v8, 0xbcb8aa3b, v56
	v_exp_f32_e32 v8, v8
	s_nop 0
	v_add_f32_e32 v8, 1.0, v8
	v_rcp_f32_e32 v8, v8
	s_nop 0
	v_mul_f32_e32 v6, v6, v8
	v_mul_f32_e32 v13, v6, v52
	v_mul_f32_e32 v6, 0x3b000000, v57
	v_mul_f32_e32 v8, 0xbcb8aa3b, v57
	v_exp_f32_e32 v8, v8
	s_nop 0
	v_add_f32_e32 v8, 1.0, v8
	v_rcp_f32_e32 v8, v8
	s_nop 0
	v_mul_f32_e32 v6, v6, v8
	v_mov_b32_e32 v8, v163
	v_cvt_pk_fp8_f32 v8, v5, v7
	v_med3_f32 v5, v9, s40, v190
	v_med3_f32 v7, v10, s40, v190
	v_mov_b32_e32 v9, v163
	v_cvt_pk_fp8_f32 v8, v5, v7 op_sel:[0,0,1]
	v_med3_f32 v5, v11, s40, v190
	v_med3_f32 v7, v12, s40, v190
	v_cvt_pk_fp8_f32 v9, v5, v7
	v_mul_f32_e32 v14, v6, v53
	v_add_u32_e32 v6, 0xa0, v4
	v_med3_f32 v5, v13, s40, v190
	v_med3_f32 v7, v14, s40, v190
	v_cvt_pk_fp8_f32 v9, v5, v7 op_sel:[0,0,1]
	v_ashrrev_i32_e32 v7, 31, v6
	v_lshlrev_b64 v[6:7], 7, v[6:7]
	v_lshl_add_u64 v[6:7], s[12:13], 0, v[6:7]
	v_lshl_add_u64 v[6:7], v[6:7], 0, v[2:3]
	v_mul_f32_e32 v5, 0x3b000000, v46
	global_store_dwordx2 v[6:7], v[8:9], off
	v_mul_f32_e32 v6, 0xbcb8aa3b, v46
	v_exp_f32_e32 v6, v6
	v_add_u32_e32 v4, 0xb0, v4
	v_add_f32_e32 v6, 1.0, v6
	v_rcp_f32_e32 v6, v6
	s_nop 0
	v_mul_f32_e32 v5, v5, v6
	v_mul_f32_e32 v6, 0x3b000000, v47
	v_mul_f32_e32 v7, 0xbcb8aa3b, v47
	v_exp_f32_e32 v7, v7
	v_mul_f32_e32 v5, v5, v42
	v_med3_f32 v5, v5, s40, v190
	v_add_f32_e32 v7, 1.0, v7
	v_rcp_f32_e32 v7, v7
	s_nop 0
	v_mul_f32_e32 v6, v6, v7
	v_mul_f32_e32 v7, 0x3b000000, v48
	v_mul_f32_e32 v8, 0xbcb8aa3b, v48
	v_exp_f32_e32 v8, v8
	v_mul_f32_e32 v6, v6, v43
	v_add_f32_e32 v8, 1.0, v8
	v_rcp_f32_e32 v8, v8
	s_nop 0
	v_mul_f32_e32 v7, v7, v8
	v_mul_f32_e32 v8, 0x3b000000, v49
	v_mul_f32_e32 v9, 0xbcb8aa3b, v49
	v_exp_f32_e32 v9, v9
	v_mul_f32_e32 v7, v7, v44
	v_add_f32_e32 v9, 1.0, v9
	v_rcp_f32_e32 v9, v9
	s_nop 0
	v_mul_f32_e32 v8, v8, v9
	v_mul_f32_e32 v9, 0x3b000000, v38
	v_mul_f32_e32 v10, 0xbcb8aa3b, v38
	v_exp_f32_e32 v10, v10
	v_mul_f32_e32 v8, v8, v45
	v_add_f32_e32 v10, 1.0, v10
	v_rcp_f32_e32 v10, v10
	s_nop 0
	v_mul_f32_e32 v9, v9, v10
	v_mul_f32_e32 v10, 0x3b000000, v39
	v_mul_f32_e32 v11, 0xbcb8aa3b, v39
	v_exp_f32_e32 v11, v11
	v_mul_f32_e32 v9, v9, v34
	v_add_f32_e32 v11, 1.0, v11
	v_rcp_f32_e32 v11, v11
	s_nop 0
	v_mul_f32_e32 v10, v10, v11
	v_mul_f32_e32 v11, 0x3b000000, v40
	v_mul_f32_e32 v12, 0xbcb8aa3b, v40
	v_exp_f32_e32 v12, v12
	v_mul_f32_e32 v10, v10, v35
	v_add_f32_e32 v12, 1.0, v12
	v_rcp_f32_e32 v12, v12
	s_nop 0
	v_mul_f32_e32 v11, v11, v12
	v_mul_f32_e32 v12, 0x3b000000, v41
	v_mul_f32_e32 v13, 0xbcb8aa3b, v41
	v_exp_f32_e32 v13, v13
	v_mul_f32_e32 v11, v11, v36
	v_add_f32_e32 v13, 1.0, v13
	v_rcp_f32_e32 v13, v13
	s_nop 0
	v_mul_f32_e32 v12, v12, v13
	v_med3_f32 v13, v6, s40, v190
	v_mov_b32_e32 v6, v163
	v_cvt_pk_fp8_f32 v6, v5, v13
	v_med3_f32 v5, v7, s40, v190
	v_med3_f32 v7, v8, s40, v190
	v_med3_f32 v8, v10, s40, v190
	v_cvt_pk_fp8_f32 v6, v5, v7 op_sel:[0,0,1]
	v_med3_f32 v5, v9, s40, v190
	v_mov_b32_e32 v7, v163
	v_cvt_pk_fp8_f32 v7, v5, v8
	v_mul_f32_e32 v12, v12, v37
	v_med3_f32 v5, v11, s40, v190
	v_med3_f32 v8, v12, s40, v190
	v_cvt_pk_fp8_f32 v7, v5, v8 op_sel:[0,0,1]
	v_ashrrev_i32_e32 v5, 31, v4
	v_lshlrev_b64 v[4:5], 7, v[4:5]
	v_lshl_add_u64 v[4:5], s[12:13], 0, v[4:5]
	v_lshl_add_u64 v[2:3], v[4:5], 0, v[2:3]
	global_store_dwordx2 v[2:3], v[6:7], off
	s_cbranch_vccz .LBB0_1291
	s_waitcnt vmcnt(0)
	s_cmpk_gt_u32 s42, 0xff
	s_cbranch_scc1 .LBB0_1237
	s_barrier
	s_branch .LBB0_1237

.LBB0_2041:
	s_add_u32 s14, s38, 0x100
	s_addc_u32 s15, s39, 0
	s_add_u32 s36, s35, s38
	s_addc_u32 s37, s55, s39
	s_cmpk_eq_i32 s38, 0x300
	s_cselect_b64 vcc, -1, 0
	s_and_b64 s[0:1], vcc, exec
	s_cselect_b32 s1, 0, s14
	s_cselect_b32 s0, 0, s15
	s_cselect_b32 s36, s31, s36
	s_cselect_b32 s37, s29, s37
	s_add_u32 s40, s18, s1
	s_addc_u32 s41, s19, s0
	s_add_i32 s1, 0, 0x10000
	v_add_u32_e32 v14, s1, v197
	ds_read_b128 v[2:5], v14
	ds_read_b128 v[6:9], v14 offset:1024
	ds_read_b128 v[10:13], v14 offset:2048
	ds_read_b128 v[14:17], v14 offset:3072
	v_cndmask_b32_e32 v162, v168, v171, vcc
	v_cndmask_b32_e32 v184, v170, v198, vcc
	v_cndmask_b32_e32 v175, v172, v199, vcc
	v_cndmask_b32_e32 v173, v174, v200, vcc
	v_lshl_add_u64 v[18:19], v[178:179], 0, s[38:39]
	s_add_i32 m0, s45, 0xc000
	ds_read_b128 v[202:205], v169
	ds_read_b128 v[206:209], v169 offset:1024
	ds_read_b128 v[210:213], v169 offset:2048
	ds_read_b128 v[214:217], v169 offset:3072
	ds_read_b128 v[218:221], v169 offset:4096
	ds_read_b128 v[222:225], v169 offset:5120
	ds_read_b128 v[226:229], v169 offset:6144
	ds_read_b128 v[230:233], v169 offset:7168
	global_load_lds_dwordx4 v[18:19], off
	v_lshl_add_u64 v[18:19], v[176:177], 0, s[38:39]
	s_add_i32 m0, s45, 0xe000
	s_nop 0
	global_load_lds_dwordx4 v[18:19], off
	s_waitcnt lgkmcnt(8)
	s_waitcnt vmcnt(10)
	s_barrier
	s_waitcnt lgkmcnt(0)
	s_waitcnt lgkmcnt(0)
	v_mfma_scale_f32_16x16x128_f8f6f4 v[158:161], v[2:9], v[202:209], v[158:161], v188, v188 op_sel_hi:[0,0,0]
	v_mfma_scale_f32_16x16x128_f8f6f4 v[150:153], v[10:17], v[202:209], v[150:153], v188, v188 op_sel_hi:[0,0,0]
	v_mfma_scale_f32_16x16x128_f8f6f4 v[142:145], v[2:9], v[210:217], v[142:145], v188, v188 op_sel_hi:[0,0,0]
	v_mfma_scale_f32_16x16x128_f8f6f4 v[134:137], v[10:17], v[210:217], v[134:137], v188, v188 op_sel_hi:[0,0,0]
	v_mfma_scale_f32_16x16x128_f8f6f4 v[126:129], v[2:9], v[218:225], v[126:129], v188, v188 op_sel_hi:[0,0,0]
	v_mfma_scale_f32_16x16x128_f8f6f4 v[118:121], v[10:17], v[218:225], v[118:121], v188, v188 op_sel_hi:[0,0,0]
	v_mfma_scale_f32_16x16x128_f8f6f4 v[110:113], v[2:9], v[226:233], v[110:113], v188, v188 op_sel_hi:[0,0,0]
	v_mfma_scale_f32_16x16x128_f8f6f4 v[102:105], v[10:17], v[226:233], v[102:105], v188, v188 op_sel_hi:[0,0,0]
	s_barrier
	s_add_i32 s0, 0, 0x14000
	s_add_i32 s1, s1, s43
	v_add_u32_e32 v30, s0, v197
	v_lshl_add_u64 v[180:181], s[36:37], 0, v[164:165]
	s_mov_b32 m0, s1
	ds_read_b128 v[18:21], v30
	ds_read_b128 v[22:25], v30 offset:1024
	ds_read_b128 v[26:29], v30 offset:2048
	ds_read_b128 v[30:33], v30 offset:3072
	global_load_lds_dwordx4 v[180:181], off
	v_lshl_add_u64 v[182:183], s[36:37], 0, v[166:167]
	s_add_i32 m0, s1, 0x2000
	s_nop 0
	global_load_lds_dwordx4 v[182:183], off
	s_waitcnt vmcnt(10)
	s_barrier
	s_waitcnt lgkmcnt(0)
	s_waitcnt lgkmcnt(0)
	v_mfma_scale_f32_16x16x128_f8f6f4 v[154:157], v[18:25], v[202:209], v[154:157], v188, v188 op_sel_hi:[0,0,0]
	v_mfma_scale_f32_16x16x128_f8f6f4 v[146:149], v[26:33], v[202:209], v[146:149], v188, v188 op_sel_hi:[0,0,0]
	v_mfma_scale_f32_16x16x128_f8f6f4 v[138:141], v[18:25], v[210:217], v[138:141], v188, v188 op_sel_hi:[0,0,0]
	v_mfma_scale_f32_16x16x128_f8f6f4 v[130:133], v[26:33], v[210:217], v[130:133], v188, v188 op_sel_hi:[0,0,0]
	v_mfma_scale_f32_16x16x128_f8f6f4 v[122:125], v[18:25], v[218:225], v[122:125], v188, v188 op_sel_hi:[0,0,0]
	v_mfma_scale_f32_16x16x128_f8f6f4 v[114:117], v[26:33], v[218:225], v[114:117], v188, v188 op_sel_hi:[0,0,0]
	v_mfma_scale_f32_16x16x128_f8f6f4 v[106:109], v[18:25], v[226:233], v[106:109], v188, v188 op_sel_hi:[0,0,0]
	v_mfma_scale_f32_16x16x128_f8f6f4 v[98:101], v[26:33], v[226:233], v[98:101], v188, v188 op_sel_hi:[0,0,0]
	s_mov_b32 m0, s45
	s_barrier
	ds_read_b128 v[202:205], v169 offset:16384
	ds_read_b128 v[206:209], v169 offset:17408
	ds_read_b128 v[210:213], v169 offset:18432
	ds_read_b128 v[214:217], v169 offset:19456
	ds_read_b128 v[218:221], v169 offset:20480
	ds_read_b128 v[222:225], v169 offset:21504
	ds_read_b128 v[226:229], v169 offset:22528
	ds_read_b128 v[230:233], v169 offset:23552
	global_load_lds_dwordx4 v162, s[40:41]
	s_mov_b32 m0, s46
	v_mov_b32_e32 v185, v163
	global_load_lds_dwordx4 v184, s[40:41]
	s_waitcnt vmcnt(10)
	s_barrier
	s_waitcnt lgkmcnt(0)
	v_lshl_add_u64 v[186:187], s[40:41], 0, v[162:163]
	v_lshl_add_u64 v[184:185], s[40:41], 0, v[184:185]
	s_waitcnt lgkmcnt(0)
	v_mfma_scale_f32_16x16x128_f8f6f4 v[94:97], v[2:9], v[202:209], v[94:97], v188, v188 op_sel_hi:[0,0,0]
	v_mfma_scale_f32_16x16x128_f8f6f4 v[86:89], v[10:17], v[202:209], v[86:89], v188, v188 op_sel_hi:[0,0,0]
	v_mfma_scale_f32_16x16x128_f8f6f4 v[78:81], v[2:9], v[210:217], v[78:81], v188, v188 op_sel_hi:[0,0,0]
	v_mfma_scale_f32_16x16x128_f8f6f4 v[70:73], v[10:17], v[210:217], v[70:73], v188, v188 op_sel_hi:[0,0,0]
	v_mfma_scale_f32_16x16x128_f8f6f4 v[62:65], v[2:9], v[218:225], v[62:65], v188, v188 op_sel_hi:[0,0,0]
	v_mfma_scale_f32_16x16x128_f8f6f4 v[54:57], v[10:17], v[218:225], v[54:57], v188, v188 op_sel_hi:[0,0,0]
	v_mfma_scale_f32_16x16x128_f8f6f4 v[46:49], v[2:9], v[226:233], v[46:49], v188, v188 op_sel_hi:[0,0,0]
	v_mfma_scale_f32_16x16x128_f8f6f4 v[38:41], v[10:17], v[226:233], v[38:41], v188, v188 op_sel_hi:[0,0,0]
	s_barrier
	s_add_u32 s38, s36, 0x20000
	s_addc_u32 s39, s37, 0
	s_add_i32 s0, s0, s43
	v_lshl_add_u64 v[2:3], s[38:39], 0, v[164:165]
	s_mov_b32 m0, s0
	s_nop 0
	global_load_lds_dwordx4 v[2:3], off
	v_lshl_add_u64 v[2:3], s[38:39], 0, v[166:167]
	s_add_i32 m0, s0, 0x2000
	s_nop 0
	global_load_lds_dwordx4 v[2:3], off
	s_waitcnt vmcnt(10)
	s_barrier
	v_mfma_scale_f32_16x16x128_f8f6f4 v[90:93], v[18:25], v[202:209], v[90:93], v188, v188 op_sel_hi:[0,0,0]
	v_mfma_scale_f32_16x16x128_f8f6f4 v[82:85], v[26:33], v[202:209], v[82:85], v188, v188 op_sel_hi:[0,0,0]
	v_mfma_scale_f32_16x16x128_f8f6f4 v[74:77], v[18:25], v[210:217], v[74:77], v188, v188 op_sel_hi:[0,0,0]
	v_mfma_scale_f32_16x16x128_f8f6f4 v[66:69], v[26:33], v[210:217], v[66:69], v188, v188 op_sel_hi:[0,0,0]
	v_mfma_scale_f32_16x16x128_f8f6f4 v[58:61], v[18:25], v[218:225], v[58:61], v188, v188 op_sel_hi:[0,0,0]
	v_mfma_scale_f32_16x16x128_f8f6f4 v[50:53], v[26:33], v[218:225], v[50:53], v188, v188 op_sel_hi:[0,0,0]
	v_mfma_scale_f32_16x16x128_f8f6f4 v[42:45], v[18:25], v[226:233], v[42:45], v188, v188 op_sel_hi:[0,0,0]
	v_mfma_scale_f32_16x16x128_f8f6f4 v[34:37], v[26:33], v[226:233], v[34:37], v188, v188 op_sel_hi:[0,0,0]
	s_add_i32 s0, 0, 0x18000
	v_add_u32_e32 v14, s0, v197
	s_barrier
	ds_read_b128 v[2:5], v14
	ds_read_b128 v[6:9], v14 offset:1024
	ds_read_b128 v[10:13], v14 offset:2048
	ds_read_b128 v[14:17], v14 offset:3072
	s_mov_b32 m0, s47
	ds_read_b128 v[18:21], v169 offset:32768
	ds_read_b128 v[22:25], v169 offset:33792
	ds_read_b128 v[26:29], v169 offset:34816
	ds_read_b128 v[30:33], v169 offset:35840
	ds_read_b128 v[202:205], v169 offset:36864
	ds_read_b128 v[206:209], v169 offset:37888
	ds_read_b128 v[210:213], v169 offset:38912
	ds_read_b128 v[214:217], v169 offset:39936
	global_load_lds_dwordx4 v175, s[40:41]
	s_mov_b32 m0, s48
	s_nop 0
	global_load_lds_dwordx4 v173, s[40:41]
	s_waitcnt lgkmcnt(8)
	s_waitcnt vmcnt(10)
	s_barrier
	s_waitcnt lgkmcnt(0)
	s_waitcnt lgkmcnt(0)
	v_mfma_scale_f32_16x16x128_f8f6f4 v[158:161], v[2:9], v[18:25], v[158:161], v188, v188 op_sel_hi:[0,0,0]
	v_mfma_scale_f32_16x16x128_f8f6f4 v[150:153], v[10:17], v[18:25], v[150:153], v188, v188 op_sel_hi:[0,0,0]
	v_mfma_scale_f32_16x16x128_f8f6f4 v[142:145], v[2:9], v[26:33], v[142:145], v188, v188 op_sel_hi:[0,0,0]
	v_mfma_scale_f32_16x16x128_f8f6f4 v[134:137], v[10:17], v[26:33], v[134:137], v188, v188 op_sel_hi:[0,0,0]
	v_mfma_scale_f32_16x16x128_f8f6f4 v[126:129], v[2:9], v[202:209], v[126:129], v188, v188 op_sel_hi:[0,0,0]
	v_mfma_scale_f32_16x16x128_f8f6f4 v[118:121], v[10:17], v[202:209], v[118:121], v188, v188 op_sel_hi:[0,0,0]
	v_mfma_scale_f32_16x16x128_f8f6f4 v[110:113], v[2:9], v[210:217], v[110:113], v188, v188 op_sel_hi:[0,0,0]
	v_mfma_scale_f32_16x16x128_f8f6f4 v[102:105], v[10:17], v[210:217], v[102:105], v188, v188 op_sel_hi:[0,0,0]
	s_barrier
	s_add_i32 s38, 0, 0x1c000
	s_add_i32 s0, s0, s43
	v_add_u32_e32 v162, s38, v197
	v_lshl_add_u64 v[180:181], v[180:181], 0, s[24:25]
	s_mov_b32 m0, s0
	ds_read_b128 v[218:221], v162
	ds_read_b128 v[222:225], v162 offset:1024
	ds_read_b128 v[226:229], v162 offset:2048
	ds_read_b128 v[230:233], v162 offset:3072
	global_load_lds_dwordx4 v[180:181], off
	v_lshl_add_u64 v[180:181], v[182:183], 0, s[24:25]
	s_add_i32 m0, s0, 0x2000
	s_nop 0
	global_load_lds_dwordx4 v[180:181], off
	s_waitcnt vmcnt(10)
	s_barrier
	s_waitcnt lgkmcnt(0)
	s_waitcnt lgkmcnt(0)
	v_mfma_scale_f32_16x16x128_f8f6f4 v[154:157], v[218:225], v[18:25], v[154:157], v188, v188 op_sel_hi:[0,0,0]
	v_mfma_scale_f32_16x16x128_f8f6f4 v[146:149], v[226:233], v[18:25], v[146:149], v188, v188 op_sel_hi:[0,0,0]
	v_mfma_scale_f32_16x16x128_f8f6f4 v[138:141], v[218:225], v[26:33], v[138:141], v188, v188 op_sel_hi:[0,0,0]
	v_mfma_scale_f32_16x16x128_f8f6f4 v[130:133], v[226:233], v[26:33], v[130:133], v188, v188 op_sel_hi:[0,0,0]
	v_mfma_scale_f32_16x16x128_f8f6f4 v[122:125], v[218:225], v[202:209], v[122:125], v188, v188 op_sel_hi:[0,0,0]
	v_mfma_scale_f32_16x16x128_f8f6f4 v[114:117], v[226:233], v[202:209], v[114:117], v188, v188 op_sel_hi:[0,0,0]
	v_mfma_scale_f32_16x16x128_f8f6f4 v[106:109], v[218:225], v[210:217], v[106:109], v188, v188 op_sel_hi:[0,0,0]
	v_mfma_scale_f32_16x16x128_f8f6f4 v[98:101], v[226:233], v[210:217], v[98:101], v188, v188 op_sel_hi:[0,0,0]
	s_mov_b32 m0, s51
	v_lshl_add_u64 v[180:181], v[186:187], 0, s[24:25]
	s_barrier
	ds_read_b128 v[18:21], v169 offset:49152
	ds_read_b128 v[22:25], v169 offset:50176
	ds_read_b128 v[26:29], v169 offset:51200
	ds_read_b128 v[30:33], v169 offset:52224
	ds_read_b128 v[202:205], v169 offset:53248
	ds_read_b128 v[206:209], v169 offset:54272
	ds_read_b128 v[210:213], v169 offset:55296
	ds_read_b128 v[214:217], v169 offset:56320
	global_load_lds_dwordx4 v[180:181], off
	v_lshl_add_u64 v[180:181], v[184:185], 0, s[24:25]
	s_mov_b32 m0, s52
	s_nop 0
	global_load_lds_dwordx4 v[180:181], off
	s_waitcnt vmcnt(10)
	s_barrier
	s_waitcnt lgkmcnt(0)
	s_waitcnt lgkmcnt(0)
	v_mfma_scale_f32_16x16x128_f8f6f4 v[94:97], v[2:9], v[18:25], v[94:97], v188, v188 op_sel_hi:[0,0,0]
	v_mfma_scale_f32_16x16x128_f8f6f4 v[86:89], v[10:17], v[18:25], v[86:89], v188, v188 op_sel_hi:[0,0,0]
	v_mfma_scale_f32_16x16x128_f8f6f4 v[78:81], v[2:9], v[26:33], v[78:81], v188, v188 op_sel_hi:[0,0,0]
	v_mfma_scale_f32_16x16x128_f8f6f4 v[70:73], v[10:17], v[26:33], v[70:73], v188, v188 op_sel_hi:[0,0,0]
	v_mfma_scale_f32_16x16x128_f8f6f4 v[62:65], v[2:9], v[202:209], v[62:65], v188, v188 op_sel_hi:[0,0,0]
	v_mfma_scale_f32_16x16x128_f8f6f4 v[54:57], v[10:17], v[202:209], v[54:57], v188, v188 op_sel_hi:[0,0,0]
	v_mfma_scale_f32_16x16x128_f8f6f4 v[46:49], v[2:9], v[210:217], v[46:49], v188, v188 op_sel_hi:[0,0,0]
	v_mfma_scale_f32_16x16x128_f8f6f4 v[38:41], v[10:17], v[210:217], v[38:41], v188, v188 op_sel_hi:[0,0,0]
	s_barrier
	s_add_u32 s0, s36, 0x20080
	s_addc_u32 s1, s37, 0
	s_add_i32 s36, s38, s43
	v_lshl_add_u64 v[2:3], s[0:1], 0, v[164:165]
	s_mov_b32 m0, s36
	s_nop 0
	global_load_lds_dwordx4 v[2:3], off
	v_lshl_add_u64 v[2:3], s[0:1], 0, v[166:167]
	s_add_i32 m0, s36, 0x2000
	s_nop 0
	global_load_lds_dwordx4 v[2:3], off
	s_waitcnt vmcnt(10)
	s_barrier
	v_mfma_scale_f32_16x16x128_f8f6f4 v[90:93], v[218:225], v[18:25], v[90:93], v188, v188 op_sel_hi:[0,0,0]
	v_mfma_scale_f32_16x16x128_f8f6f4 v[82:85], v[226:233], v[18:25], v[82:85], v188, v188 op_sel_hi:[0,0,0]
	v_mfma_scale_f32_16x16x128_f8f6f4 v[74:77], v[218:225], v[26:33], v[74:77], v188, v188 op_sel_hi:[0,0,0]
	v_mfma_scale_f32_16x16x128_f8f6f4 v[66:69], v[226:233], v[26:33], v[66:69], v188, v188 op_sel_hi:[0,0,0]
	v_mfma_scale_f32_16x16x128_f8f6f4 v[58:61], v[218:225], v[202:209], v[58:61], v188, v188 op_sel_hi:[0,0,0]
	v_mfma_scale_f32_16x16x128_f8f6f4 v[50:53], v[226:233], v[202:209], v[50:53], v188, v188 op_sel_hi:[0,0,0]
	v_mfma_scale_f32_16x16x128_f8f6f4 v[42:45], v[218:225], v[210:217], v[42:45], v188, v188 op_sel_hi:[0,0,0]
	v_mfma_scale_f32_16x16x128_f8f6f4 v[34:37], v[226:233], v[210:217], v[34:37], v188, v188 op_sel_hi:[0,0,0]
	s_add_i32 s56, s56, 2
	s_cmp_gt_u32 s56, 5
	s_mov_b64 s[38:39], s[14:15]
	s_barrier
	s_cbranch_scc0 .LBB0_2041
	v_mul_f32_e32 v5, 0x3b000000, v158
	v_mul_f32_e32 v6, 0xbcb8aa3b, v158
	v_exp_f32_e32 v6, v6
	s_ashr_i32 s35, s34, 31
	s_ashr_i32 s31, s30, 31
	s_lshl_b64 s[14:15], s[34:35], 18
	v_add_f32_e32 v6, 1.0, v6
	v_rcp_f32_e32 v6, v6
	s_lshl_b64 s[30:31], s[30:31], 15
	v_mov_b32_e32 v3, v195
	s_add_u32 s0, s6, s14
	v_mul_f32_e32 v5, v5, v6
	v_mul_f32_e32 v6, 0x3b000000, v159
	v_mul_f32_e32 v7, 0xbcb8aa3b, v159
	v_exp_f32_e32 v7, v7
	v_mul_f32_e32 v5, v5, v154
	v_med3_f32 v5, v5, s10, v190
	v_add_f32_e32 v7, 1.0, v7
	v_rcp_f32_e32 v7, v7
	s_nop 15
	s_nop 15
	v_mov_b32_e32 v2, v196
	v_mul_f32_e32 v6, v6, v7
	v_mul_f32_e32 v7, 0x3b000000, v160
	v_mul_f32_e32 v8, 0xbcb8aa3b, v160
	v_exp_f32_e32 v8, v8
	v_mul_f32_e32 v6, v6, v155
	v_add_u32_e32 v4, s49, v3
	v_add_f32_e32 v8, 1.0, v8
	v_rcp_f32_e32 v8, v8
	s_addc_u32 s1, s7, s15
	s_add_u32 s14, s0, s30
	v_mul_f32_e32 v7, v7, v8
	v_mul_f32_e32 v8, 0x3b000000, v161
	v_mul_f32_e32 v9, 0xbcb8aa3b, v161
	v_exp_f32_e32 v9, v9
	v_mul_f32_e32 v7, v7, v156
	v_lshl_add_u32 v2, v2, 3, s50
	v_add_f32_e32 v9, 1.0, v9
	v_rcp_f32_e32 v9, v9
	s_addc_u32 s15, s1, s31
	v_ashrrev_i32_e32 v3, 31, v2
	s_and_b64 vcc, exec, s[12:13]
	v_mul_f32_e32 v8, v8, v9
	v_mul_f32_e32 v9, 0x3b000000, v150
	v_mul_f32_e32 v10, 0xbcb8aa3b, v150
	v_exp_f32_e32 v10, v10
	v_mul_f32_e32 v8, v8, v157
	v_mov_b32_e32 v174, v200
	v_add_f32_e32 v10, 1.0, v10
	v_rcp_f32_e32 v10, v10
	v_mov_b32_e32 v172, v199
	v_mov_b32_e32 v170, v198
	v_mov_b32_e32 v168, v171
	v_mul_f32_e32 v9, v9, v10
	v_mul_f32_e32 v10, 0x3b000000, v151
	v_mul_f32_e32 v11, 0xbcb8aa3b, v151
	v_exp_f32_e32 v11, v11
	v_mul_f32_e32 v9, v9, v146
	s_mov_b32 s30, s28
	v_add_f32_e32 v11, 1.0, v11
	v_rcp_f32_e32 v11, v11
	s_mov_b32 s34, s54
	s_mov_b64 s[36:37], s[16:17]
	v_mul_f32_e32 v10, v10, v11
	v_mul_f32_e32 v11, 0x3b000000, v152
	v_mul_f32_e32 v12, 0xbcb8aa3b, v152
	v_exp_f32_e32 v12, v12
	v_mul_f32_e32 v10, v10, v147
	v_add_f32_e32 v12, 1.0, v12
	v_rcp_f32_e32 v12, v12
	s_nop 0
	v_mul_f32_e32 v11, v11, v12
	v_mul_f32_e32 v12, 0x3b000000, v153
	v_mul_f32_e32 v13, 0xbcb8aa3b, v153
	v_exp_f32_e32 v13, v13
	v_mul_f32_e32 v11, v11, v148
	v_add_f32_e32 v13, 1.0, v13
	v_rcp_f32_e32 v13, v13
	s_nop 0
	v_mul_f32_e32 v12, v12, v13
	v_med3_f32 v13, v6, s10, v190
	v_mov_b32_e32 v6, v163
	v_cvt_pk_fp8_f32 v6, v5, v13
	v_med3_f32 v5, v7, s10, v190
	v_med3_f32 v7, v8, s10, v190
	v_med3_f32 v8, v10, s10, v190
	v_cvt_pk_fp8_f32 v6, v5, v7 op_sel:[0,0,1]
	v_med3_f32 v5, v9, s10, v190
	v_mov_b32_e32 v7, v163
	v_cvt_pk_fp8_f32 v7, v5, v8
	v_mul_f32_e32 v12, v12, v149
	v_med3_f32 v5, v11, s10, v190
	v_med3_f32 v8, v12, s10, v190
	v_cvt_pk_fp8_f32 v7, v5, v8 op_sel:[0,0,1]
	v_ashrrev_i32_e32 v5, 31, v4
	v_lshlrev_b64 v[8:9], 7, v[4:5]
	v_lshl_add_u64 v[8:9], s[14:15], 0, v[8:9]
	v_lshl_add_u64 v[8:9], v[8:9], 0, v[2:3]
	v_mul_f32_e32 v5, 0x3b000000, v142
	global_store_dwordx2 v[8:9], v[6:7], off
	v_mul_f32_e32 v6, 0xbcb8aa3b, v142
	v_exp_f32_e32 v6, v6
	s_nop 0
	v_add_f32_e32 v6, 1.0, v6
	v_rcp_f32_e32 v6, v6
	s_nop 0
	v_mul_f32_e32 v5, v5, v6
	v_mul_f32_e32 v6, 0x3b000000, v143
	v_mul_f32_e32 v7, 0xbcb8aa3b, v143
	v_exp_f32_e32 v7, v7
	v_mul_f32_e32 v5, v5, v138
	v_med3_f32 v5, v5, s10, v190
	v_add_f32_e32 v7, 1.0, v7
	v_rcp_f32_e32 v7, v7
	s_nop 0
	v_mul_f32_e32 v6, v6, v7
	v_mul_f32_e32 v7, v6, v139
	v_mul_f32_e32 v6, 0x3b000000, v144
	v_mul_f32_e32 v8, 0xbcb8aa3b, v144
	v_exp_f32_e32 v8, v8
	v_med3_f32 v7, v7, s10, v190
	v_add_f32_e32 v8, 1.0, v8
	v_rcp_f32_e32 v8, v8
	s_nop 0
	v_mul_f32_e32 v6, v6, v8
	v_mul_f32_e32 v9, v6, v140
	v_mul_f32_e32 v6, 0x3b000000, v145
	v_mul_f32_e32 v8, 0xbcb8aa3b, v145
	v_exp_f32_e32 v8, v8
	s_nop 0
	v_add_f32_e32 v8, 1.0, v8
	v_rcp_f32_e32 v8, v8
	s_nop 0
	v_mul_f32_e32 v6, v6, v8
	v_mul_f32_e32 v10, v6, v141
	v_mul_f32_e32 v6, 0x3b000000, v134
	v_mul_f32_e32 v8, 0xbcb8aa3b, v134
	v_exp_f32_e32 v8, v8
	s_nop 0
	v_add_f32_e32 v8, 1.0, v8
	v_rcp_f32_e32 v8, v8
	s_nop 0
	v_mul_f32_e32 v6, v6, v8
	v_mul_f32_e32 v11, v6, v130
	v_mul_f32_e32 v6, 0x3b000000, v135
	v_mul_f32_e32 v8, 0xbcb8aa3b, v135
	v_exp_f32_e32 v8, v8
	s_nop 0
	v_add_f32_e32 v8, 1.0, v8
	v_rcp_f32_e32 v8, v8
	s_nop 0
	v_mul_f32_e32 v6, v6, v8
	v_mul_f32_e32 v12, v6, v131
	v_mul_f32_e32 v6, 0x3b000000, v136
	v_mul_f32_e32 v8, 0xbcb8aa3b, v136
	v_exp_f32_e32 v8, v8
	s_nop 0
	v_add_f32_e32 v8, 1.0, v8
	v_rcp_f32_e32 v8, v8
	s_nop 0
	v_mul_f32_e32 v6, v6, v8
	v_mul_f32_e32 v13, v6, v132
	v_mul_f32_e32 v6, 0x3b000000, v137
	v_mul_f32_e32 v8, 0xbcb8aa3b, v137
	v_exp_f32_e32 v8, v8
	s_nop 0
	v_add_f32_e32 v8, 1.0, v8
	v_rcp_f32_e32 v8, v8
	s_nop 0
	v_mul_f32_e32 v6, v6, v8
	v_mov_b32_e32 v8, v163
	v_cvt_pk_fp8_f32 v8, v5, v7
	v_med3_f32 v5, v9, s10, v190
	v_med3_f32 v7, v10, s10, v190
	v_mov_b32_e32 v9, v163
	v_cvt_pk_fp8_f32 v8, v5, v7 op_sel:[0,0,1]
	v_med3_f32 v5, v11, s10, v190
	v_med3_f32 v7, v12, s10, v190
	v_cvt_pk_fp8_f32 v9, v5, v7
	v_mul_f32_e32 v14, v6, v133
	v_add_u32_e32 v6, 16, v4
	v_med3_f32 v5, v13, s10, v190
	v_med3_f32 v7, v14, s10, v190
	v_cvt_pk_fp8_f32 v9, v5, v7 op_sel:[0,0,1]
	v_ashrrev_i32_e32 v7, 31, v6
	v_lshlrev_b64 v[6:7], 7, v[6:7]
	v_lshl_add_u64 v[6:7], s[14:15], 0, v[6:7]
	v_lshl_add_u64 v[6:7], v[6:7], 0, v[2:3]
	v_mul_f32_e32 v5, 0x3b000000, v126
	global_store_dwordx2 v[6:7], v[8:9], off
	v_mul_f32_e32 v6, 0xbcb8aa3b, v126
	v_exp_f32_e32 v6, v6
	s_nop 0
	v_add_f32_e32 v6, 1.0, v6
	v_rcp_f32_e32 v6, v6
	s_nop 0
	v_mul_f32_e32 v5, v5, v6
	v_mul_f32_e32 v6, 0x3b000000, v127
	v_mul_f32_e32 v7, 0xbcb8aa3b, v127
	v_exp_f32_e32 v7, v7
	v_mul_f32_e32 v5, v5, v122
	v_med3_f32 v5, v5, s10, v190
	v_add_f32_e32 v7, 1.0, v7
	v_rcp_f32_e32 v7, v7
	s_nop 0
	v_mul_f32_e32 v6, v6, v7
	v_mul_f32_e32 v7, v6, v123
	v_mul_f32_e32 v6, 0x3b000000, v128
	v_mul_f32_e32 v8, 0xbcb8aa3b, v128
	v_exp_f32_e32 v8, v8
	v_med3_f32 v7, v7, s10, v190
	v_add_f32_e32 v8, 1.0, v8
	v_rcp_f32_e32 v8, v8
	s_nop 0
	v_mul_f32_e32 v6, v6, v8
	v_mul_f32_e32 v9, v6, v124
	v_mul_f32_e32 v6, 0x3b000000, v129
	v_mul_f32_e32 v8, 0xbcb8aa3b, v129
	v_exp_f32_e32 v8, v8
	s_nop 0
	v_add_f32_e32 v8, 1.0, v8
	v_rcp_f32_e32 v8, v8
	s_nop 0
	v_mul_f32_e32 v6, v6, v8
	v_mul_f32_e32 v10, v6, v125
	v_mul_f32_e32 v6, 0x3b000000, v118
	v_mul_f32_e32 v8, 0xbcb8aa3b, v118
	v_exp_f32_e32 v8, v8
	s_nop 0
	v_add_f32_e32 v8, 1.0, v8
	v_rcp_f32_e32 v8, v8
	s_nop 0
	v_mul_f32_e32 v6, v6, v8
	v_mul_f32_e32 v11, v6, v114
	v_mul_f32_e32 v6, 0x3b000000, v119
	v_mul_f32_e32 v8, 0xbcb8aa3b, v119
	v_exp_f32_e32 v8, v8
	s_nop 0
	v_add_f32_e32 v8, 1.0, v8
	v_rcp_f32_e32 v8, v8
	s_nop 0
	v_mul_f32_e32 v6, v6, v8
	v_mul_f32_e32 v12, v6, v115
	v_mul_f32_e32 v6, 0x3b000000, v120
	v_mul_f32_e32 v8, 0xbcb8aa3b, v120
	v_exp_f32_e32 v8, v8
	s_nop 0
	v_add_f32_e32 v8, 1.0, v8
	v_rcp_f32_e32 v8, v8
	s_nop 0
	v_mul_f32_e32 v6, v6, v8
	v_mul_f32_e32 v13, v6, v116
	v_mul_f32_e32 v6, 0x3b000000, v121
	v_mul_f32_e32 v8, 0xbcb8aa3b, v121
	v_exp_f32_e32 v8, v8
	s_nop 0
	v_add_f32_e32 v8, 1.0, v8
	v_rcp_f32_e32 v8, v8
	s_nop 0
	v_mul_f32_e32 v6, v6, v8
	v_mov_b32_e32 v8, v163
	v_cvt_pk_fp8_f32 v8, v5, v7
	v_med3_f32 v5, v9, s10, v190
	v_med3_f32 v7, v10, s10, v190
	v_mov_b32_e32 v9, v163
	v_cvt_pk_fp8_f32 v8, v5, v7 op_sel:[0,0,1]
	v_med3_f32 v5, v11, s10, v190
	v_med3_f32 v7, v12, s10, v190
	v_cvt_pk_fp8_f32 v9, v5, v7
	v_mul_f32_e32 v14, v6, v117
	v_add_u32_e32 v6, 32, v4
	v_med3_f32 v5, v13, s10, v190
	v_med3_f32 v7, v14, s10, v190
	v_cvt_pk_fp8_f32 v9, v5, v7 op_sel:[0,0,1]
	v_ashrrev_i32_e32 v7, 31, v6
	v_lshlrev_b64 v[6:7], 7, v[6:7]
	v_lshl_add_u64 v[6:7], s[14:15], 0, v[6:7]
	v_lshl_add_u64 v[6:7], v[6:7], 0, v[2:3]
	v_mul_f32_e32 v5, 0x3b000000, v110
	global_store_dwordx2 v[6:7], v[8:9], off
	v_mul_f32_e32 v6, 0xbcb8aa3b, v110
	v_exp_f32_e32 v6, v6
	s_nop 0
	v_add_f32_e32 v6, 1.0, v6
	v_rcp_f32_e32 v6, v6
	s_nop 0
	v_mul_f32_e32 v5, v5, v6
	v_mul_f32_e32 v6, 0x3b000000, v111
	v_mul_f32_e32 v7, 0xbcb8aa3b, v111
	v_exp_f32_e32 v7, v7
	v_mul_f32_e32 v5, v5, v106
	v_med3_f32 v5, v5, s10, v190
	v_add_f32_e32 v7, 1.0, v7
	v_rcp_f32_e32 v7, v7
	s_nop 0
	v_mul_f32_e32 v6, v6, v7
	v_mul_f32_e32 v7, v6, v107
	v_mul_f32_e32 v6, 0x3b000000, v112
	v_mul_f32_e32 v8, 0xbcb8aa3b, v112
	v_exp_f32_e32 v8, v8
	v_med3_f32 v7, v7, s10, v190
	v_add_f32_e32 v8, 1.0, v8
	v_rcp_f32_e32 v8, v8
	s_nop 0
	v_mul_f32_e32 v6, v6, v8
	v_mul_f32_e32 v9, v6, v108
	v_mul_f32_e32 v6, 0x3b000000, v113
	v_mul_f32_e32 v8, 0xbcb8aa3b, v113
	v_exp_f32_e32 v8, v8
	s_nop 0
	v_add_f32_e32 v8, 1.0, v8
	v_rcp_f32_e32 v8, v8
	s_nop 0
	v_mul_f32_e32 v6, v6, v8
	v_mul_f32_e32 v10, v6, v109
	v_mul_f32_e32 v6, 0x3b000000, v102
	v_mul_f32_e32 v8, 0xbcb8aa3b, v102
	v_exp_f32_e32 v8, v8
	s_nop 0
	v_add_f32_e32 v8, 1.0, v8
	v_rcp_f32_e32 v8, v8
	s_nop 0
	v_mul_f32_e32 v6, v6, v8
	v_mul_f32_e32 v11, v6, v98
	v_mul_f32_e32 v6, 0x3b000000, v103
	v_mul_f32_e32 v8, 0xbcb8aa3b, v103
	v_exp_f32_e32 v8, v8
	s_nop 0
	v_add_f32_e32 v8, 1.0, v8
	v_rcp_f32_e32 v8, v8
	s_nop 0
	v_mul_f32_e32 v6, v6, v8
	v_mul_f32_e32 v12, v6, v99
	v_mul_f32_e32 v6, 0x3b000000, v104
	v_mul_f32_e32 v8, 0xbcb8aa3b, v104
	v_exp_f32_e32 v8, v8
	s_nop 0
	v_add_f32_e32 v8, 1.0, v8
	v_rcp_f32_e32 v8, v8
	s_nop 0
	v_mul_f32_e32 v6, v6, v8
	v_mul_f32_e32 v13, v6, v100
	v_mul_f32_e32 v6, 0x3b000000, v105
	v_mul_f32_e32 v8, 0xbcb8aa3b, v105
	v_exp_f32_e32 v8, v8
	s_nop 0
	v_add_f32_e32 v8, 1.0, v8
	v_rcp_f32_e32 v8, v8
	s_nop 0
	v_mul_f32_e32 v6, v6, v8
	v_mov_b32_e32 v8, v163
	v_cvt_pk_fp8_f32 v8, v5, v7
	v_med3_f32 v5, v9, s10, v190
	v_med3_f32 v7, v10, s10, v190
	v_mov_b32_e32 v9, v163
	v_cvt_pk_fp8_f32 v8, v5, v7 op_sel:[0,0,1]
	v_med3_f32 v5, v11, s10, v190
	v_med3_f32 v7, v12, s10, v190
	v_cvt_pk_fp8_f32 v9, v5, v7
	v_mul_f32_e32 v14, v6, v101
	v_add_u32_e32 v6, 48, v4
	v_med3_f32 v5, v13, s10, v190
	v_med3_f32 v7, v14, s10, v190
	v_cvt_pk_fp8_f32 v9, v5, v7 op_sel:[0,0,1]
	v_ashrrev_i32_e32 v7, 31, v6
	v_lshlrev_b64 v[6:7], 7, v[6:7]
	v_lshl_add_u64 v[6:7], s[14:15], 0, v[6:7]
	v_lshl_add_u64 v[6:7], v[6:7], 0, v[2:3]
	v_mul_f32_e32 v5, 0x3b000000, v94
	global_store_dwordx2 v[6:7], v[8:9], off
	v_mul_f32_e32 v7, 0xbcb8aa3b, v94
	v_exp_f32_e32 v7, v7
	v_add_u32_e32 v6, 0x80, v4
	v_add_f32_e32 v7, 1.0, v7
	v_rcp_f32_e32 v7, v7
	s_nop 0
	v_mul_f32_e32 v5, v5, v7
	v_mul_f32_e32 v7, 0x3b000000, v95
	v_mul_f32_e32 v8, 0xbcb8aa3b, v95
	v_exp_f32_e32 v8, v8
	v_mul_f32_e32 v5, v5, v90
	v_med3_f32 v5, v5, s10, v190
	v_add_f32_e32 v8, 1.0, v8
	v_rcp_f32_e32 v8, v8
	s_nop 0
	v_mul_f32_e32 v7, v7, v8
	v_mul_f32_e32 v8, 0x3b000000, v96
	v_mul_f32_e32 v9, 0xbcb8aa3b, v96
	v_exp_f32_e32 v9, v9
	v_mul_f32_e32 v7, v7, v91
	v_med3_f32 v7, v7, s10, v190
	v_add_f32_e32 v9, 1.0, v9
	v_rcp_f32_e32 v9, v9
	s_nop 0
	v_mul_f32_e32 v8, v8, v9
	v_mul_f32_e32 v9, v8, v92
	v_mul_f32_e32 v8, 0x3b000000, v97
	v_mul_f32_e32 v10, 0xbcb8aa3b, v97
	v_exp_f32_e32 v10, v10
	s_nop 0
	v_add_f32_e32 v10, 1.0, v10
	v_rcp_f32_e32 v10, v10
	s_nop 0
	v_mul_f32_e32 v8, v8, v10
	v_mul_f32_e32 v10, v8, v93
	v_mul_f32_e32 v8, 0x3b000000, v86
	v_mul_f32_e32 v11, 0xbcb8aa3b, v86
	v_exp_f32_e32 v11, v11
	s_nop 0
	v_add_f32_e32 v11, 1.0, v11
	v_rcp_f32_e32 v11, v11
	s_nop 0
	v_mul_f32_e32 v8, v8, v11
	v_mul_f32_e32 v11, v8, v82
	v_mul_f32_e32 v8, 0x3b000000, v87
	v_mul_f32_e32 v12, 0xbcb8aa3b, v87
	v_exp_f32_e32 v12, v12
	s_nop 0
	v_add_f32_e32 v12, 1.0, v12
	v_rcp_f32_e32 v12, v12
	s_nop 0
	v_mul_f32_e32 v8, v8, v12
	v_mul_f32_e32 v12, v8, v83
	v_mul_f32_e32 v8, 0x3b000000, v88
	v_mul_f32_e32 v13, 0xbcb8aa3b, v88
	v_exp_f32_e32 v13, v13
	s_nop 0
	v_add_f32_e32 v13, 1.0, v13
	v_rcp_f32_e32 v13, v13
	s_nop 0
	v_mul_f32_e32 v8, v8, v13
	v_mul_f32_e32 v13, v8, v84
	v_mul_f32_e32 v8, 0x3b000000, v89
	v_mul_f32_e32 v14, 0xbcb8aa3b, v89
	v_exp_f32_e32 v14, v14
	s_nop 0
	v_add_f32_e32 v14, 1.0, v14
	v_rcp_f32_e32 v14, v14
	s_nop 0
	v_mul_f32_e32 v8, v8, v14
	v_mul_f32_e32 v14, v8, v85
	v_mov_b32_e32 v8, v163
	v_cvt_pk_fp8_f32 v8, v5, v7
	v_med3_f32 v5, v9, s10, v190
	v_med3_f32 v7, v10, s10, v190
	v_mov_b32_e32 v9, v163
	v_cvt_pk_fp8_f32 v8, v5, v7 op_sel:[0,0,1]
	v_med3_f32 v5, v11, s10, v190
	v_med3_f32 v7, v12, s10, v190
	v_cvt_pk_fp8_f32 v9, v5, v7
	v_med3_f32 v5, v13, s10, v190
	v_med3_f32 v7, v14, s10, v190
	v_cvt_pk_fp8_f32 v9, v5, v7 op_sel:[0,0,1]
	v_ashrrev_i32_e32 v7, 31, v6
	v_lshlrev_b64 v[6:7], 7, v[6:7]
	v_lshl_add_u64 v[6:7], s[14:15], 0, v[6:7]
	v_lshl_add_u64 v[6:7], v[6:7], 0, v[2:3]
	v_mul_f32_e32 v5, 0x3b000000, v78
	global_store_dwordx2 v[6:7], v[8:9], off
	v_mul_f32_e32 v6, 0xbcb8aa3b, v78
	v_exp_f32_e32 v6, v6
	s_nop 0
	v_add_f32_e32 v6, 1.0, v6
	v_rcp_f32_e32 v6, v6
	s_nop 0
	v_mul_f32_e32 v5, v5, v6
	v_mul_f32_e32 v6, 0x3b000000, v79
	v_mul_f32_e32 v7, 0xbcb8aa3b, v79
	v_exp_f32_e32 v7, v7
	v_mul_f32_e32 v5, v5, v74
	v_med3_f32 v5, v5, s10, v190
	v_add_f32_e32 v7, 1.0, v7
	v_rcp_f32_e32 v7, v7
	s_nop 0
	v_mul_f32_e32 v6, v6, v7
	v_mul_f32_e32 v7, v6, v75
	v_mul_f32_e32 v6, 0x3b000000, v80
	v_mul_f32_e32 v8, 0xbcb8aa3b, v80
	v_exp_f32_e32 v8, v8
	v_med3_f32 v7, v7, s10, v190
	v_add_f32_e32 v8, 1.0, v8
	v_rcp_f32_e32 v8, v8
	s_nop 0
	v_mul_f32_e32 v6, v6, v8
	v_mul_f32_e32 v9, v6, v76
	v_mul_f32_e32 v6, 0x3b000000, v81
	v_mul_f32_e32 v8, 0xbcb8aa3b, v81
	v_exp_f32_e32 v8, v8
	s_nop 0
	v_add_f32_e32 v8, 1.0, v8
	v_rcp_f32_e32 v8, v8
	s_nop 0
	v_mul_f32_e32 v6, v6, v8
	v_mul_f32_e32 v10, v6, v77
	v_mul_f32_e32 v6, 0x3b000000, v70
	v_mul_f32_e32 v8, 0xbcb8aa3b, v70
	v_exp_f32_e32 v8, v8
	s_nop 0
	v_add_f32_e32 v8, 1.0, v8
	v_rcp_f32_e32 v8, v8
	s_nop 0
	v_mul_f32_e32 v6, v6, v8
	v_mul_f32_e32 v11, v6, v66
	v_mul_f32_e32 v6, 0x3b000000, v71
	v_mul_f32_e32 v8, 0xbcb8aa3b, v71
	v_exp_f32_e32 v8, v8
	s_nop 0
	v_add_f32_e32 v8, 1.0, v8
	v_rcp_f32_e32 v8, v8
	s_nop 0
	v_mul_f32_e32 v6, v6, v8
	v_mul_f32_e32 v12, v6, v67
	v_mul_f32_e32 v6, 0x3b000000, v72
	v_mul_f32_e32 v8, 0xbcb8aa3b, v72
	v_exp_f32_e32 v8, v8
	s_nop 0
	v_add_f32_e32 v8, 1.0, v8
	v_rcp_f32_e32 v8, v8
	s_nop 0
	v_mul_f32_e32 v6, v6, v8
	v_mul_f32_e32 v13, v6, v68
	v_mul_f32_e32 v6, 0x3b000000, v73
	v_mul_f32_e32 v8, 0xbcb8aa3b, v73
	v_exp_f32_e32 v8, v8
	s_nop 0
	v_add_f32_e32 v8, 1.0, v8
	v_rcp_f32_e32 v8, v8
	s_nop 0
	v_mul_f32_e32 v6, v6, v8
	v_mov_b32_e32 v8, v163
	v_cvt_pk_fp8_f32 v8, v5, v7
	v_med3_f32 v5, v9, s10, v190
	v_med3_f32 v7, v10, s10, v190
	v_mov_b32_e32 v9, v163
	v_cvt_pk_fp8_f32 v8, v5, v7 op_sel:[0,0,1]
	v_med3_f32 v5, v11, s10, v190
	v_med3_f32 v7, v12, s10, v190
	v_cvt_pk_fp8_f32 v9, v5, v7
	v_mul_f32_e32 v14, v6, v69
	v_add_u32_e32 v6, 0x90, v4
	v_med3_f32 v5, v13, s10, v190
	v_med3_f32 v7, v14, s10, v190
	v_cvt_pk_fp8_f32 v9, v5, v7 op_sel:[0,0,1]
	v_ashrrev_i32_e32 v7, 31, v6
	v_lshlrev_b64 v[6:7], 7, v[6:7]
	v_lshl_add_u64 v[6:7], s[14:15], 0, v[6:7]
	v_lshl_add_u64 v[6:7], v[6:7], 0, v[2:3]
	v_mul_f32_e32 v5, 0x3b000000, v62
	global_store_dwordx2 v[6:7], v[8:9], off
	v_mul_f32_e32 v6, 0xbcb8aa3b, v62
	v_exp_f32_e32 v6, v6
	s_nop 0
	v_add_f32_e32 v6, 1.0, v6
	v_rcp_f32_e32 v6, v6
	s_nop 0
	v_mul_f32_e32 v5, v5, v6
	v_mul_f32_e32 v6, 0x3b000000, v63
	v_mul_f32_e32 v7, 0xbcb8aa3b, v63
	v_exp_f32_e32 v7, v7
	v_mul_f32_e32 v5, v5, v58
	v_med3_f32 v5, v5, s10, v190
	v_add_f32_e32 v7, 1.0, v7
	v_rcp_f32_e32 v7, v7
	s_nop 0
	v_mul_f32_e32 v6, v6, v7
	v_mul_f32_e32 v7, v6, v59
	v_mul_f32_e32 v6, 0x3b000000, v64
	v_mul_f32_e32 v8, 0xbcb8aa3b, v64
	v_exp_f32_e32 v8, v8
	v_med3_f32 v7, v7, s10, v190
	v_add_f32_e32 v8, 1.0, v8
	v_rcp_f32_e32 v8, v8
	s_nop 0
	v_mul_f32_e32 v6, v6, v8
	v_mul_f32_e32 v9, v6, v60
	v_mul_f32_e32 v6, 0x3b000000, v65
	v_mul_f32_e32 v8, 0xbcb8aa3b, v65
	v_exp_f32_e32 v8, v8
	s_nop 0
	v_add_f32_e32 v8, 1.0, v8
	v_rcp_f32_e32 v8, v8
	s_nop 0
	v_mul_f32_e32 v6, v6, v8
	v_mul_f32_e32 v10, v6, v61
	v_mul_f32_e32 v6, 0x3b000000, v54
	v_mul_f32_e32 v8, 0xbcb8aa3b, v54
	v_exp_f32_e32 v8, v8
	s_nop 0
	v_add_f32_e32 v8, 1.0, v8
	v_rcp_f32_e32 v8, v8
	s_nop 0
	v_mul_f32_e32 v6, v6, v8
	v_mul_f32_e32 v11, v6, v50
	v_mul_f32_e32 v6, 0x3b000000, v55
	v_mul_f32_e32 v8, 0xbcb8aa3b, v55
	v_exp_f32_e32 v8, v8
	s_nop 0
	v_add_f32_e32 v8, 1.0, v8
	v_rcp_f32_e32 v8, v8
	s_nop 0
	v_mul_f32_e32 v6, v6, v8
	v_mul_f32_e32 v12, v6, v51
	v_mul_f32_e32 v6, 0x3b000000, v56
	v_mul_f32_e32 v8, 0xbcb8aa3b, v56
	v_exp_f32_e32 v8, v8
	s_nop 0
	v_add_f32_e32 v8, 1.0, v8
	v_rcp_f32_e32 v8, v8
	s_nop 0
	v_mul_f32_e32 v6, v6, v8
	v_mul_f32_e32 v13, v6, v52
	v_mul_f32_e32 v6, 0x3b000000, v57
	v_mul_f32_e32 v8, 0xbcb8aa3b, v57
	v_exp_f32_e32 v8, v8
	s_nop 0
	v_add_f32_e32 v8, 1.0, v8
	v_rcp_f32_e32 v8, v8
	s_nop 0
	v_mul_f32_e32 v6, v6, v8
	v_mov_b32_e32 v8, v163
	v_cvt_pk_fp8_f32 v8, v5, v7
	v_med3_f32 v5, v9, s10, v190
	v_med3_f32 v7, v10, s10, v190
	v_mov_b32_e32 v9, v163
	v_cvt_pk_fp8_f32 v8, v5, v7 op_sel:[0,0,1]
	v_med3_f32 v5, v11, s10, v190
	v_med3_f32 v7, v12, s10, v190
	v_cvt_pk_fp8_f32 v9, v5, v7
	v_mul_f32_e32 v14, v6, v53
	v_add_u32_e32 v6, 0xa0, v4
	v_med3_f32 v5, v13, s10, v190
	v_med3_f32 v7, v14, s10, v190
	v_cvt_pk_fp8_f32 v9, v5, v7 op_sel:[0,0,1]
	v_ashrrev_i32_e32 v7, 31, v6
	v_lshlrev_b64 v[6:7], 7, v[6:7]
	v_lshl_add_u64 v[6:7], s[14:15], 0, v[6:7]
	v_lshl_add_u64 v[6:7], v[6:7], 0, v[2:3]
	v_mul_f32_e32 v5, 0x3b000000, v46
	global_store_dwordx2 v[6:7], v[8:9], off
	v_mul_f32_e32 v6, 0xbcb8aa3b, v46
	v_exp_f32_e32 v6, v6
	v_add_u32_e32 v4, 0xb0, v4
	v_add_f32_e32 v6, 1.0, v6
	v_rcp_f32_e32 v6, v6
	s_nop 0
	v_mul_f32_e32 v5, v5, v6
	v_mul_f32_e32 v6, 0x3b000000, v47
	v_mul_f32_e32 v7, 0xbcb8aa3b, v47
	v_exp_f32_e32 v7, v7
	v_mul_f32_e32 v5, v5, v42
	v_med3_f32 v5, v5, s10, v190
	v_add_f32_e32 v7, 1.0, v7
	v_rcp_f32_e32 v7, v7
	s_nop 0
	v_mul_f32_e32 v6, v6, v7
	v_mul_f32_e32 v7, 0x3b000000, v48
	v_mul_f32_e32 v8, 0xbcb8aa3b, v48
	v_exp_f32_e32 v8, v8
	v_mul_f32_e32 v6, v6, v43
	v_add_f32_e32 v8, 1.0, v8
	v_rcp_f32_e32 v8, v8
	s_nop 0
	v_mul_f32_e32 v7, v7, v8
	v_mul_f32_e32 v8, 0x3b000000, v49
	v_mul_f32_e32 v9, 0xbcb8aa3b, v49
	v_exp_f32_e32 v9, v9
	v_mul_f32_e32 v7, v7, v44
	v_add_f32_e32 v9, 1.0, v9
	v_rcp_f32_e32 v9, v9
	s_nop 0
	v_mul_f32_e32 v8, v8, v9
	v_mul_f32_e32 v9, 0x3b000000, v38
	v_mul_f32_e32 v10, 0xbcb8aa3b, v38
	v_exp_f32_e32 v10, v10
	v_mul_f32_e32 v8, v8, v45
	v_add_f32_e32 v10, 1.0, v10
	v_rcp_f32_e32 v10, v10
	s_nop 0
	v_mul_f32_e32 v9, v9, v10
	v_mul_f32_e32 v10, 0x3b000000, v39
	v_mul_f32_e32 v11, 0xbcb8aa3b, v39
	v_exp_f32_e32 v11, v11
	v_mul_f32_e32 v9, v9, v34
	v_add_f32_e32 v11, 1.0, v11
	v_rcp_f32_e32 v11, v11
	s_nop 0
	v_mul_f32_e32 v10, v10, v11
	v_mul_f32_e32 v11, 0x3b000000, v40
	v_mul_f32_e32 v12, 0xbcb8aa3b, v40
	v_exp_f32_e32 v12, v12
	v_mul_f32_e32 v10, v10, v35
	v_add_f32_e32 v12, 1.0, v12
	v_rcp_f32_e32 v12, v12
	s_nop 0
	v_mul_f32_e32 v11, v11, v12
	v_mul_f32_e32 v12, 0x3b000000, v41
	v_mul_f32_e32 v13, 0xbcb8aa3b, v41
	v_exp_f32_e32 v13, v13
	v_mul_f32_e32 v11, v11, v36
	v_add_f32_e32 v13, 1.0, v13
	v_rcp_f32_e32 v13, v13
	s_nop 0
	v_mul_f32_e32 v12, v12, v13
	v_med3_f32 v13, v6, s10, v190
	v_mov_b32_e32 v6, v163
	v_cvt_pk_fp8_f32 v6, v5, v13
	v_med3_f32 v5, v7, s10, v190
	v_med3_f32 v7, v8, s10, v190
	v_med3_f32 v8, v10, s10, v190
	v_cvt_pk_fp8_f32 v6, v5, v7 op_sel:[0,0,1]
	v_med3_f32 v5, v9, s10, v190
	v_mov_b32_e32 v7, v163
	v_cvt_pk_fp8_f32 v7, v5, v8
	v_mul_f32_e32 v12, v12, v37
	v_med3_f32 v5, v11, s10, v190
	v_med3_f32 v8, v12, s10, v190
	v_cvt_pk_fp8_f32 v7, v5, v8 op_sel:[0,0,1]
	v_ashrrev_i32_e32 v5, 31, v4
	v_lshlrev_b64 v[4:5], 7, v[4:5]
	v_lshl_add_u64 v[4:5], s[14:15], 0, v[4:5]
	v_lshl_add_u64 v[2:3], v[4:5], 0, v[2:3]
	global_store_dwordx2 v[2:3], v[6:7], off
	s_cbranch_vccz .LBB0_2030
	s_waitcnt vmcnt(0)
	s_cmpk_gt_u32 s42, 0xff
	s_cbranch_scc1 .LBB0_1976
	s_barrier
	s_branch .LBB0_1976

.LBB0_2749:
	s_add_u32 s10, s34, 0x100
	s_addc_u32 s11, s35, 0
	s_add_u32 s30, s29, s34
	s_addc_u32 s31, s55, s35
	s_cmpk_eq_i32 s34, 0x300
	s_cselect_b64 vcc, -1, 0
	s_and_b64 s[0:1], vcc, exec
	s_cselect_b32 s1, 0, s10
	s_cselect_b32 s0, 0, s11
	s_cselect_b32 s30, s27, s30
	s_cselect_b32 s31, s25, s31
	s_add_u32 s36, s14, s1
	s_addc_u32 s37, s15, s0
	s_add_i32 s1, 0, 0x10000
	v_add_u32_e32 v14, s1, v196
	ds_read_b128 v[2:5], v14
	ds_read_b128 v[6:9], v14 offset:1024
	ds_read_b128 v[10:13], v14 offset:2048
	ds_read_b128 v[14:17], v14 offset:3072
	v_cndmask_b32_e32 v162, v168, v171, vcc
	v_cndmask_b32_e32 v184, v170, v197, vcc
	v_cndmask_b32_e32 v175, v172, v198, vcc
	v_cndmask_b32_e32 v173, v174, v199, vcc
	v_lshl_add_u64 v[18:19], v[178:179], 0, s[34:35]
	s_add_i32 m0, s45, 0xc000
	ds_read_b128 v[200:203], v169
	ds_read_b128 v[204:207], v169 offset:1024
	ds_read_b128 v[208:211], v169 offset:2048
	ds_read_b128 v[212:215], v169 offset:3072
	ds_read_b128 v[216:219], v169 offset:4096
	ds_read_b128 v[220:223], v169 offset:5120
	ds_read_b128 v[224:227], v169 offset:6144
	ds_read_b128 v[228:231], v169 offset:7168
	global_load_lds_dwordx4 v[18:19], off
	v_lshl_add_u64 v[18:19], v[176:177], 0, s[34:35]
	s_add_i32 m0, s45, 0xe000
	s_nop 0
	global_load_lds_dwordx4 v[18:19], off
	s_waitcnt lgkmcnt(8)
	s_waitcnt vmcnt(10)
	s_barrier
	s_waitcnt lgkmcnt(0)
	s_waitcnt lgkmcnt(0)
	v_mfma_scale_f32_16x16x128_f8f6f4 v[158:161], v[2:9], v[200:207], v[158:161], v1, v1 op_sel_hi:[0,0,0]
	v_mfma_scale_f32_16x16x128_f8f6f4 v[150:153], v[10:17], v[200:207], v[150:153], v1, v1 op_sel_hi:[0,0,0]
	v_mfma_scale_f32_16x16x128_f8f6f4 v[142:145], v[2:9], v[208:215], v[142:145], v1, v1 op_sel_hi:[0,0,0]
	v_mfma_scale_f32_16x16x128_f8f6f4 v[134:137], v[10:17], v[208:215], v[134:137], v1, v1 op_sel_hi:[0,0,0]
	v_mfma_scale_f32_16x16x128_f8f6f4 v[126:129], v[2:9], v[216:223], v[126:129], v1, v1 op_sel_hi:[0,0,0]
	v_mfma_scale_f32_16x16x128_f8f6f4 v[118:121], v[10:17], v[216:223], v[118:121], v1, v1 op_sel_hi:[0,0,0]
	v_mfma_scale_f32_16x16x128_f8f6f4 v[110:113], v[2:9], v[224:231], v[110:113], v1, v1 op_sel_hi:[0,0,0]
	v_mfma_scale_f32_16x16x128_f8f6f4 v[102:105], v[10:17], v[224:231], v[102:105], v1, v1 op_sel_hi:[0,0,0]
	s_barrier
	s_add_i32 s0, 0, 0x14000
	s_add_i32 s1, s1, s43
	v_add_u32_e32 v30, s0, v196
	v_lshl_add_u64 v[180:181], s[30:31], 0, v[164:165]
	s_mov_b32 m0, s1
	ds_read_b128 v[18:21], v30
	ds_read_b128 v[22:25], v30 offset:1024
	ds_read_b128 v[26:29], v30 offset:2048
	ds_read_b128 v[30:33], v30 offset:3072
	global_load_lds_dwordx4 v[180:181], off
	v_lshl_add_u64 v[182:183], s[30:31], 0, v[166:167]
	s_add_i32 m0, s1, 0x2000
	s_nop 0
	global_load_lds_dwordx4 v[182:183], off
	s_waitcnt vmcnt(10)
	s_barrier
	s_waitcnt lgkmcnt(0)
	s_waitcnt lgkmcnt(0)
	v_mfma_scale_f32_16x16x128_f8f6f4 v[154:157], v[18:25], v[200:207], v[154:157], v1, v1 op_sel_hi:[0,0,0]
	v_mfma_scale_f32_16x16x128_f8f6f4 v[146:149], v[26:33], v[200:207], v[146:149], v1, v1 op_sel_hi:[0,0,0]
	v_mfma_scale_f32_16x16x128_f8f6f4 v[138:141], v[18:25], v[208:215], v[138:141], v1, v1 op_sel_hi:[0,0,0]
	v_mfma_scale_f32_16x16x128_f8f6f4 v[130:133], v[26:33], v[208:215], v[130:133], v1, v1 op_sel_hi:[0,0,0]
	v_mfma_scale_f32_16x16x128_f8f6f4 v[122:125], v[18:25], v[216:223], v[122:125], v1, v1 op_sel_hi:[0,0,0]
	v_mfma_scale_f32_16x16x128_f8f6f4 v[114:117], v[26:33], v[216:223], v[114:117], v1, v1 op_sel_hi:[0,0,0]
	v_mfma_scale_f32_16x16x128_f8f6f4 v[106:109], v[18:25], v[224:231], v[106:109], v1, v1 op_sel_hi:[0,0,0]
	v_mfma_scale_f32_16x16x128_f8f6f4 v[98:101], v[26:33], v[224:231], v[98:101], v1, v1 op_sel_hi:[0,0,0]
	s_mov_b32 m0, s45
	s_barrier
	ds_read_b128 v[200:203], v169 offset:16384
	ds_read_b128 v[204:207], v169 offset:17408
	ds_read_b128 v[208:211], v169 offset:18432
	ds_read_b128 v[212:215], v169 offset:19456
	ds_read_b128 v[216:219], v169 offset:20480
	ds_read_b128 v[220:223], v169 offset:21504
	ds_read_b128 v[224:227], v169 offset:22528
	ds_read_b128 v[228:231], v169 offset:23552
	global_load_lds_dwordx4 v162, s[36:37]
	s_mov_b32 m0, s46
	v_mov_b32_e32 v185, v163
	global_load_lds_dwordx4 v184, s[36:37]
	s_waitcnt vmcnt(10)
	s_barrier
	s_waitcnt lgkmcnt(0)
	v_lshl_add_u64 v[186:187], s[36:37], 0, v[162:163]
	v_lshl_add_u64 v[184:185], s[36:37], 0, v[184:185]
	s_waitcnt lgkmcnt(0)
	v_mfma_scale_f32_16x16x128_f8f6f4 v[94:97], v[2:9], v[200:207], v[94:97], v1, v1 op_sel_hi:[0,0,0]
	v_mfma_scale_f32_16x16x128_f8f6f4 v[86:89], v[10:17], v[200:207], v[86:89], v1, v1 op_sel_hi:[0,0,0]
	v_mfma_scale_f32_16x16x128_f8f6f4 v[78:81], v[2:9], v[208:215], v[78:81], v1, v1 op_sel_hi:[0,0,0]
	v_mfma_scale_f32_16x16x128_f8f6f4 v[70:73], v[10:17], v[208:215], v[70:73], v1, v1 op_sel_hi:[0,0,0]
	v_mfma_scale_f32_16x16x128_f8f6f4 v[62:65], v[2:9], v[216:223], v[62:65], v1, v1 op_sel_hi:[0,0,0]
	v_mfma_scale_f32_16x16x128_f8f6f4 v[54:57], v[10:17], v[216:223], v[54:57], v1, v1 op_sel_hi:[0,0,0]
	v_mfma_scale_f32_16x16x128_f8f6f4 v[46:49], v[2:9], v[224:231], v[46:49], v1, v1 op_sel_hi:[0,0,0]
	v_mfma_scale_f32_16x16x128_f8f6f4 v[38:41], v[10:17], v[224:231], v[38:41], v1, v1 op_sel_hi:[0,0,0]
	s_barrier
	s_add_u32 s34, s30, 0x20000
	s_addc_u32 s35, s31, 0
	s_add_i32 s0, s0, s43
	v_lshl_add_u64 v[2:3], s[34:35], 0, v[164:165]
	s_mov_b32 m0, s0
	s_nop 0
	global_load_lds_dwordx4 v[2:3], off
	v_lshl_add_u64 v[2:3], s[34:35], 0, v[166:167]
	s_add_i32 m0, s0, 0x2000
	s_nop 0
	global_load_lds_dwordx4 v[2:3], off
	s_waitcnt vmcnt(10)
	s_barrier
	v_mfma_scale_f32_16x16x128_f8f6f4 v[90:93], v[18:25], v[200:207], v[90:93], v1, v1 op_sel_hi:[0,0,0]
	v_mfma_scale_f32_16x16x128_f8f6f4 v[82:85], v[26:33], v[200:207], v[82:85], v1, v1 op_sel_hi:[0,0,0]
	v_mfma_scale_f32_16x16x128_f8f6f4 v[74:77], v[18:25], v[208:215], v[74:77], v1, v1 op_sel_hi:[0,0,0]
	v_mfma_scale_f32_16x16x128_f8f6f4 v[66:69], v[26:33], v[208:215], v[66:69], v1, v1 op_sel_hi:[0,0,0]
	v_mfma_scale_f32_16x16x128_f8f6f4 v[58:61], v[18:25], v[216:223], v[58:61], v1, v1 op_sel_hi:[0,0,0]
	v_mfma_scale_f32_16x16x128_f8f6f4 v[50:53], v[26:33], v[216:223], v[50:53], v1, v1 op_sel_hi:[0,0,0]
	v_mfma_scale_f32_16x16x128_f8f6f4 v[42:45], v[18:25], v[224:231], v[42:45], v1, v1 op_sel_hi:[0,0,0]
	v_mfma_scale_f32_16x16x128_f8f6f4 v[34:37], v[26:33], v[224:231], v[34:37], v1, v1 op_sel_hi:[0,0,0]
	s_add_i32 s0, 0, 0x18000
	v_add_u32_e32 v14, s0, v196
	s_barrier
	ds_read_b128 v[2:5], v14
	ds_read_b128 v[6:9], v14 offset:1024
	ds_read_b128 v[10:13], v14 offset:2048
	ds_read_b128 v[14:17], v14 offset:3072
	s_mov_b32 m0, s47
	ds_read_b128 v[18:21], v169 offset:32768
	ds_read_b128 v[22:25], v169 offset:33792
	ds_read_b128 v[26:29], v169 offset:34816
	ds_read_b128 v[30:33], v169 offset:35840
	ds_read_b128 v[200:203], v169 offset:36864
	ds_read_b128 v[204:207], v169 offset:37888
	ds_read_b128 v[208:211], v169 offset:38912
	ds_read_b128 v[212:215], v169 offset:39936
	global_load_lds_dwordx4 v175, s[36:37]
	s_mov_b32 m0, s48
	s_nop 0
	global_load_lds_dwordx4 v173, s[36:37]
	s_waitcnt lgkmcnt(8)
	s_waitcnt vmcnt(10)
	s_barrier
	s_waitcnt lgkmcnt(0)
	s_waitcnt lgkmcnt(0)
	v_mfma_scale_f32_16x16x128_f8f6f4 v[158:161], v[2:9], v[18:25], v[158:161], v1, v1 op_sel_hi:[0,0,0]
	v_mfma_scale_f32_16x16x128_f8f6f4 v[150:153], v[10:17], v[18:25], v[150:153], v1, v1 op_sel_hi:[0,0,0]
	v_mfma_scale_f32_16x16x128_f8f6f4 v[142:145], v[2:9], v[26:33], v[142:145], v1, v1 op_sel_hi:[0,0,0]
	v_mfma_scale_f32_16x16x128_f8f6f4 v[134:137], v[10:17], v[26:33], v[134:137], v1, v1 op_sel_hi:[0,0,0]
	v_mfma_scale_f32_16x16x128_f8f6f4 v[126:129], v[2:9], v[200:207], v[126:129], v1, v1 op_sel_hi:[0,0,0]
	v_mfma_scale_f32_16x16x128_f8f6f4 v[118:121], v[10:17], v[200:207], v[118:121], v1, v1 op_sel_hi:[0,0,0]
	v_mfma_scale_f32_16x16x128_f8f6f4 v[110:113], v[2:9], v[208:215], v[110:113], v1, v1 op_sel_hi:[0,0,0]
	v_mfma_scale_f32_16x16x128_f8f6f4 v[102:105], v[10:17], v[208:215], v[102:105], v1, v1 op_sel_hi:[0,0,0]
	s_barrier
	s_add_i32 s34, 0, 0x1c000
	s_add_i32 s0, s0, s43
	v_add_u32_e32 v162, s34, v196
	v_lshl_add_u64 v[180:181], v[180:181], 0, s[20:21]
	s_mov_b32 m0, s0
	ds_read_b128 v[216:219], v162
	ds_read_b128 v[220:223], v162 offset:1024
	ds_read_b128 v[224:227], v162 offset:2048
	ds_read_b128 v[228:231], v162 offset:3072
	global_load_lds_dwordx4 v[180:181], off
	v_lshl_add_u64 v[180:181], v[182:183], 0, s[20:21]
	s_add_i32 m0, s0, 0x2000
	s_nop 0
	global_load_lds_dwordx4 v[180:181], off
	s_waitcnt vmcnt(10)
	s_barrier
	s_waitcnt lgkmcnt(0)
	s_waitcnt lgkmcnt(0)
	v_mfma_scale_f32_16x16x128_f8f6f4 v[154:157], v[216:223], v[18:25], v[154:157], v1, v1 op_sel_hi:[0,0,0]
	v_mfma_scale_f32_16x16x128_f8f6f4 v[146:149], v[224:231], v[18:25], v[146:149], v1, v1 op_sel_hi:[0,0,0]
	v_mfma_scale_f32_16x16x128_f8f6f4 v[138:141], v[216:223], v[26:33], v[138:141], v1, v1 op_sel_hi:[0,0,0]
	v_mfma_scale_f32_16x16x128_f8f6f4 v[130:133], v[224:231], v[26:33], v[130:133], v1, v1 op_sel_hi:[0,0,0]
	v_mfma_scale_f32_16x16x128_f8f6f4 v[122:125], v[216:223], v[200:207], v[122:125], v1, v1 op_sel_hi:[0,0,0]
	v_mfma_scale_f32_16x16x128_f8f6f4 v[114:117], v[224:231], v[200:207], v[114:117], v1, v1 op_sel_hi:[0,0,0]
	v_mfma_scale_f32_16x16x128_f8f6f4 v[106:109], v[216:223], v[208:215], v[106:109], v1, v1 op_sel_hi:[0,0,0]
	v_mfma_scale_f32_16x16x128_f8f6f4 v[98:101], v[224:231], v[208:215], v[98:101], v1, v1 op_sel_hi:[0,0,0]
	s_mov_b32 m0, s51
	v_lshl_add_u64 v[180:181], v[186:187], 0, s[20:21]
	s_barrier
	ds_read_b128 v[18:21], v169 offset:49152
	ds_read_b128 v[22:25], v169 offset:50176
	ds_read_b128 v[26:29], v169 offset:51200
	ds_read_b128 v[30:33], v169 offset:52224
	ds_read_b128 v[200:203], v169 offset:53248
	ds_read_b128 v[204:207], v169 offset:54272
	ds_read_b128 v[208:211], v169 offset:55296
	ds_read_b128 v[212:215], v169 offset:56320
	global_load_lds_dwordx4 v[180:181], off
	v_lshl_add_u64 v[180:181], v[184:185], 0, s[20:21]
	s_mov_b32 m0, s52
	s_nop 0
	global_load_lds_dwordx4 v[180:181], off
	s_waitcnt vmcnt(10)
	s_barrier
	s_waitcnt lgkmcnt(0)
	s_waitcnt lgkmcnt(0)
	v_mfma_scale_f32_16x16x128_f8f6f4 v[94:97], v[2:9], v[18:25], v[94:97], v1, v1 op_sel_hi:[0,0,0]
	v_mfma_scale_f32_16x16x128_f8f6f4 v[86:89], v[10:17], v[18:25], v[86:89], v1, v1 op_sel_hi:[0,0,0]
	v_mfma_scale_f32_16x16x128_f8f6f4 v[78:81], v[2:9], v[26:33], v[78:81], v1, v1 op_sel_hi:[0,0,0]
	v_mfma_scale_f32_16x16x128_f8f6f4 v[70:73], v[10:17], v[26:33], v[70:73], v1, v1 op_sel_hi:[0,0,0]
	v_mfma_scale_f32_16x16x128_f8f6f4 v[62:65], v[2:9], v[200:207], v[62:65], v1, v1 op_sel_hi:[0,0,0]
	v_mfma_scale_f32_16x16x128_f8f6f4 v[54:57], v[10:17], v[200:207], v[54:57], v1, v1 op_sel_hi:[0,0,0]
	v_mfma_scale_f32_16x16x128_f8f6f4 v[46:49], v[2:9], v[208:215], v[46:49], v1, v1 op_sel_hi:[0,0,0]
	v_mfma_scale_f32_16x16x128_f8f6f4 v[38:41], v[10:17], v[208:215], v[38:41], v1, v1 op_sel_hi:[0,0,0]
	s_barrier
	s_add_u32 s0, s30, 0x20080
	s_addc_u32 s1, s31, 0
	s_add_i32 s30, s34, s43
	v_lshl_add_u64 v[2:3], s[0:1], 0, v[164:165]
	s_mov_b32 m0, s30
	s_nop 0
	global_load_lds_dwordx4 v[2:3], off
	v_lshl_add_u64 v[2:3], s[0:1], 0, v[166:167]
	s_add_i32 m0, s30, 0x2000
	s_nop 0
	global_load_lds_dwordx4 v[2:3], off
	s_waitcnt vmcnt(10)
	s_barrier
	v_mfma_scale_f32_16x16x128_f8f6f4 v[90:93], v[216:223], v[18:25], v[90:93], v1, v1 op_sel_hi:[0,0,0]
	v_mfma_scale_f32_16x16x128_f8f6f4 v[82:85], v[224:231], v[18:25], v[82:85], v1, v1 op_sel_hi:[0,0,0]
	v_mfma_scale_f32_16x16x128_f8f6f4 v[74:77], v[216:223], v[26:33], v[74:77], v1, v1 op_sel_hi:[0,0,0]
	v_mfma_scale_f32_16x16x128_f8f6f4 v[66:69], v[224:231], v[26:33], v[66:69], v1, v1 op_sel_hi:[0,0,0]
	v_mfma_scale_f32_16x16x128_f8f6f4 v[58:61], v[216:223], v[200:207], v[58:61], v1, v1 op_sel_hi:[0,0,0]
	v_mfma_scale_f32_16x16x128_f8f6f4 v[50:53], v[224:231], v[200:207], v[50:53], v1, v1 op_sel_hi:[0,0,0]
	v_mfma_scale_f32_16x16x128_f8f6f4 v[42:45], v[216:223], v[208:215], v[42:45], v1, v1 op_sel_hi:[0,0,0]
	v_mfma_scale_f32_16x16x128_f8f6f4 v[34:37], v[224:231], v[208:215], v[34:37], v1, v1 op_sel_hi:[0,0,0]
	s_add_i32 s56, s56, 2
	s_cmp_gt_u32 s56, 5
	s_mov_b64 s[34:35], s[10:11]
	s_barrier
	s_cbranch_scc0 .LBB0_2749
	v_mul_f32_e32 v5, 0x3b000000, v158
	v_mul_f32_e32 v6, 0xbcb8aa3b, v158
	v_exp_f32_e32 v6, v6
	s_ashr_i32 s29, s28, 31
	s_ashr_i32 s27, s26, 31
	s_lshl_b64 s[10:11], s[28:29], 18
	v_add_f32_e32 v6, 1.0, v6
	v_rcp_f32_e32 v6, v6
	s_lshl_b64 s[26:27], s[26:27], 15
	v_mov_b32_e32 v3, v194
	s_add_u32 s0, s8, s10
	v_mul_f32_e32 v5, v5, v6
	v_mul_f32_e32 v6, 0x3b000000, v159
	v_mul_f32_e32 v7, 0xbcb8aa3b, v159
	v_exp_f32_e32 v7, v7
	v_mul_f32_e32 v5, v5, v154
	v_med3_f32 v5, v5, s40, v189
	v_add_f32_e32 v7, 1.0, v7
	v_rcp_f32_e32 v7, v7
	s_nop 15
	s_nop 15
	v_mov_b32_e32 v2, v195
	v_mul_f32_e32 v6, v6, v7
	v_mul_f32_e32 v7, 0x3b000000, v160
	v_mul_f32_e32 v8, 0xbcb8aa3b, v160
	v_exp_f32_e32 v8, v8
	v_mul_f32_e32 v6, v6, v155
	v_add_u32_e32 v4, s49, v3
	v_add_f32_e32 v8, 1.0, v8
	v_rcp_f32_e32 v8, v8
	s_addc_u32 s1, s9, s11
	s_add_u32 s10, s0, s26
	v_mul_f32_e32 v7, v7, v8
	v_mul_f32_e32 v8, 0x3b000000, v161
	v_mul_f32_e32 v9, 0xbcb8aa3b, v161
	v_exp_f32_e32 v9, v9
	v_mul_f32_e32 v7, v7, v156
	v_lshl_add_u32 v2, v2, 3, s50
	v_add_f32_e32 v9, 1.0, v9
	v_rcp_f32_e32 v9, v9
	s_addc_u32 s11, s1, s27
	v_ashrrev_i32_e32 v3, 31, v2
	s_and_b64 vcc, exec, s[6:7]
	v_mul_f32_e32 v8, v8, v9
	v_mul_f32_e32 v9, 0x3b000000, v150
	v_mul_f32_e32 v10, 0xbcb8aa3b, v150
	v_exp_f32_e32 v10, v10
	v_mul_f32_e32 v8, v8, v157
	v_mov_b32_e32 v174, v199
	v_add_f32_e32 v10, 1.0, v10
	v_rcp_f32_e32 v10, v10
	v_mov_b32_e32 v172, v198
	v_mov_b32_e32 v170, v197
	v_mov_b32_e32 v168, v171
	v_mul_f32_e32 v9, v9, v10
	v_mul_f32_e32 v10, 0x3b000000, v151
	v_mul_f32_e32 v11, 0xbcb8aa3b, v151
	v_exp_f32_e32 v11, v11
	v_mul_f32_e32 v9, v9, v146
	s_mov_b32 s26, s24
	v_add_f32_e32 v11, 1.0, v11
	v_rcp_f32_e32 v11, v11
	s_mov_b32 s28, s54
	s_mov_b64 s[30:31], s[12:13]
	v_mul_f32_e32 v10, v10, v11
	v_mul_f32_e32 v11, 0x3b000000, v152
	v_mul_f32_e32 v12, 0xbcb8aa3b, v152
	v_exp_f32_e32 v12, v12
	v_mul_f32_e32 v10, v10, v147
	v_add_f32_e32 v12, 1.0, v12
	v_rcp_f32_e32 v12, v12
	s_nop 0
	v_mul_f32_e32 v11, v11, v12
	v_mul_f32_e32 v12, 0x3b000000, v153
	v_mul_f32_e32 v13, 0xbcb8aa3b, v153
	v_exp_f32_e32 v13, v13
	v_mul_f32_e32 v11, v11, v148
	v_add_f32_e32 v13, 1.0, v13
	v_rcp_f32_e32 v13, v13
	s_nop 0
	v_mul_f32_e32 v12, v12, v13
	v_med3_f32 v13, v6, s40, v189
	v_mov_b32_e32 v6, v163
	v_cvt_pk_fp8_f32 v6, v5, v13
	v_med3_f32 v5, v7, s40, v189
	v_med3_f32 v7, v8, s40, v189
	v_med3_f32 v8, v10, s40, v189
	v_cvt_pk_fp8_f32 v6, v5, v7 op_sel:[0,0,1]
	v_med3_f32 v5, v9, s40, v189
	v_mov_b32_e32 v7, v163
	v_cvt_pk_fp8_f32 v7, v5, v8
	v_mul_f32_e32 v12, v12, v149
	v_med3_f32 v5, v11, s40, v189
	v_med3_f32 v8, v12, s40, v189
	v_cvt_pk_fp8_f32 v7, v5, v8 op_sel:[0,0,1]
	v_ashrrev_i32_e32 v5, 31, v4
	v_lshlrev_b64 v[8:9], 7, v[4:5]
	v_lshl_add_u64 v[8:9], s[10:11], 0, v[8:9]
	v_lshl_add_u64 v[8:9], v[8:9], 0, v[2:3]
	v_mul_f32_e32 v5, 0x3b000000, v142
	global_store_dwordx2 v[8:9], v[6:7], off
	v_mul_f32_e32 v6, 0xbcb8aa3b, v142
	v_exp_f32_e32 v6, v6
	s_nop 0
	v_add_f32_e32 v6, 1.0, v6
	v_rcp_f32_e32 v6, v6
	s_nop 0
	v_mul_f32_e32 v5, v5, v6
	v_mul_f32_e32 v6, 0x3b000000, v143
	v_mul_f32_e32 v7, 0xbcb8aa3b, v143
	v_exp_f32_e32 v7, v7
	v_mul_f32_e32 v5, v5, v138
	v_med3_f32 v5, v5, s40, v189
	v_add_f32_e32 v7, 1.0, v7
	v_rcp_f32_e32 v7, v7
	s_nop 0
	v_mul_f32_e32 v6, v6, v7
	v_mul_f32_e32 v7, v6, v139
	v_mul_f32_e32 v6, 0x3b000000, v144
	v_mul_f32_e32 v8, 0xbcb8aa3b, v144
	v_exp_f32_e32 v8, v8
	v_med3_f32 v7, v7, s40, v189
	v_add_f32_e32 v8, 1.0, v8
	v_rcp_f32_e32 v8, v8
	s_nop 0
	v_mul_f32_e32 v6, v6, v8
	v_mul_f32_e32 v9, v6, v140
	v_mul_f32_e32 v6, 0x3b000000, v145
	v_mul_f32_e32 v8, 0xbcb8aa3b, v145
	v_exp_f32_e32 v8, v8
	s_nop 0
	v_add_f32_e32 v8, 1.0, v8
	v_rcp_f32_e32 v8, v8
	s_nop 0
	v_mul_f32_e32 v6, v6, v8
	v_mul_f32_e32 v10, v6, v141
	v_mul_f32_e32 v6, 0x3b000000, v134
	v_mul_f32_e32 v8, 0xbcb8aa3b, v134
	v_exp_f32_e32 v8, v8
	s_nop 0
	v_add_f32_e32 v8, 1.0, v8
	v_rcp_f32_e32 v8, v8
	s_nop 0
	v_mul_f32_e32 v6, v6, v8
	v_mul_f32_e32 v11, v6, v130
	v_mul_f32_e32 v6, 0x3b000000, v135
	v_mul_f32_e32 v8, 0xbcb8aa3b, v135
	v_exp_f32_e32 v8, v8
	s_nop 0
	v_add_f32_e32 v8, 1.0, v8
	v_rcp_f32_e32 v8, v8
	s_nop 0
	v_mul_f32_e32 v6, v6, v8
	v_mul_f32_e32 v12, v6, v131
	v_mul_f32_e32 v6, 0x3b000000, v136
	v_mul_f32_e32 v8, 0xbcb8aa3b, v136
	v_exp_f32_e32 v8, v8
	s_nop 0
	v_add_f32_e32 v8, 1.0, v8
	v_rcp_f32_e32 v8, v8
	s_nop 0
	v_mul_f32_e32 v6, v6, v8
	v_mul_f32_e32 v13, v6, v132
	v_mul_f32_e32 v6, 0x3b000000, v137
	v_mul_f32_e32 v8, 0xbcb8aa3b, v137
	v_exp_f32_e32 v8, v8
	s_nop 0
	v_add_f32_e32 v8, 1.0, v8
	v_rcp_f32_e32 v8, v8
	s_nop 0
	v_mul_f32_e32 v6, v6, v8
	v_mov_b32_e32 v8, v163
	v_cvt_pk_fp8_f32 v8, v5, v7
	v_med3_f32 v5, v9, s40, v189
	v_med3_f32 v7, v10, s40, v189
	v_mov_b32_e32 v9, v163
	v_cvt_pk_fp8_f32 v8, v5, v7 op_sel:[0,0,1]
	v_med3_f32 v5, v11, s40, v189
	v_med3_f32 v7, v12, s40, v189
	v_cvt_pk_fp8_f32 v9, v5, v7
	v_mul_f32_e32 v14, v6, v133
	v_add_u32_e32 v6, 16, v4
	v_med3_f32 v5, v13, s40, v189
	v_med3_f32 v7, v14, s40, v189
	v_cvt_pk_fp8_f32 v9, v5, v7 op_sel:[0,0,1]
	v_ashrrev_i32_e32 v7, 31, v6
	v_lshlrev_b64 v[6:7], 7, v[6:7]
	v_lshl_add_u64 v[6:7], s[10:11], 0, v[6:7]
	v_lshl_add_u64 v[6:7], v[6:7], 0, v[2:3]
	v_mul_f32_e32 v5, 0x3b000000, v126
	global_store_dwordx2 v[6:7], v[8:9], off
	v_mul_f32_e32 v6, 0xbcb8aa3b, v126
	v_exp_f32_e32 v6, v6
	s_nop 0
	v_add_f32_e32 v6, 1.0, v6
	v_rcp_f32_e32 v6, v6
	s_nop 0
	v_mul_f32_e32 v5, v5, v6
	v_mul_f32_e32 v6, 0x3b000000, v127
	v_mul_f32_e32 v7, 0xbcb8aa3b, v127
	v_exp_f32_e32 v7, v7
	v_mul_f32_e32 v5, v5, v122
	v_med3_f32 v5, v5, s40, v189
	v_add_f32_e32 v7, 1.0, v7
	v_rcp_f32_e32 v7, v7
	s_nop 0
	v_mul_f32_e32 v6, v6, v7
	v_mul_f32_e32 v7, v6, v123
	v_mul_f32_e32 v6, 0x3b000000, v128
	v_mul_f32_e32 v8, 0xbcb8aa3b, v128
	v_exp_f32_e32 v8, v8
	v_med3_f32 v7, v7, s40, v189
	v_add_f32_e32 v8, 1.0, v8
	v_rcp_f32_e32 v8, v8
	s_nop 0
	v_mul_f32_e32 v6, v6, v8
	v_mul_f32_e32 v9, v6, v124
	v_mul_f32_e32 v6, 0x3b000000, v129
	v_mul_f32_e32 v8, 0xbcb8aa3b, v129
	v_exp_f32_e32 v8, v8
	s_nop 0
	v_add_f32_e32 v8, 1.0, v8
	v_rcp_f32_e32 v8, v8
	s_nop 0
	v_mul_f32_e32 v6, v6, v8
	v_mul_f32_e32 v10, v6, v125
	v_mul_f32_e32 v6, 0x3b000000, v118
	v_mul_f32_e32 v8, 0xbcb8aa3b, v118
	v_exp_f32_e32 v8, v8
	s_nop 0
	v_add_f32_e32 v8, 1.0, v8
	v_rcp_f32_e32 v8, v8
	s_nop 0
	v_mul_f32_e32 v6, v6, v8
	v_mul_f32_e32 v11, v6, v114
	v_mul_f32_e32 v6, 0x3b000000, v119
	v_mul_f32_e32 v8, 0xbcb8aa3b, v119
	v_exp_f32_e32 v8, v8
	s_nop 0
	v_add_f32_e32 v8, 1.0, v8
	v_rcp_f32_e32 v8, v8
	s_nop 0
	v_mul_f32_e32 v6, v6, v8
	v_mul_f32_e32 v12, v6, v115
	v_mul_f32_e32 v6, 0x3b000000, v120
	v_mul_f32_e32 v8, 0xbcb8aa3b, v120
	v_exp_f32_e32 v8, v8
	s_nop 0
	v_add_f32_e32 v8, 1.0, v8
	v_rcp_f32_e32 v8, v8
	s_nop 0
	v_mul_f32_e32 v6, v6, v8
	v_mul_f32_e32 v13, v6, v116
	v_mul_f32_e32 v6, 0x3b000000, v121
	v_mul_f32_e32 v8, 0xbcb8aa3b, v121
	v_exp_f32_e32 v8, v8
	s_nop 0
	v_add_f32_e32 v8, 1.0, v8
	v_rcp_f32_e32 v8, v8
	s_nop 0
	v_mul_f32_e32 v6, v6, v8
	v_mov_b32_e32 v8, v163
	v_cvt_pk_fp8_f32 v8, v5, v7
	v_med3_f32 v5, v9, s40, v189
	v_med3_f32 v7, v10, s40, v189
	v_mov_b32_e32 v9, v163
	v_cvt_pk_fp8_f32 v8, v5, v7 op_sel:[0,0,1]
	v_med3_f32 v5, v11, s40, v189
	v_med3_f32 v7, v12, s40, v189
	v_cvt_pk_fp8_f32 v9, v5, v7
	v_mul_f32_e32 v14, v6, v117
	v_add_u32_e32 v6, 32, v4
	v_med3_f32 v5, v13, s40, v189
	v_med3_f32 v7, v14, s40, v189
	v_cvt_pk_fp8_f32 v9, v5, v7 op_sel:[0,0,1]
	v_ashrrev_i32_e32 v7, 31, v6
	v_lshlrev_b64 v[6:7], 7, v[6:7]
	v_lshl_add_u64 v[6:7], s[10:11], 0, v[6:7]
	v_lshl_add_u64 v[6:7], v[6:7], 0, v[2:3]
	v_mul_f32_e32 v5, 0x3b000000, v110
	global_store_dwordx2 v[6:7], v[8:9], off
	v_mul_f32_e32 v6, 0xbcb8aa3b, v110
	v_exp_f32_e32 v6, v6
	s_nop 0
	v_add_f32_e32 v6, 1.0, v6
	v_rcp_f32_e32 v6, v6
	s_nop 0
	v_mul_f32_e32 v5, v5, v6
	v_mul_f32_e32 v6, 0x3b000000, v111
	v_mul_f32_e32 v7, 0xbcb8aa3b, v111
	v_exp_f32_e32 v7, v7
	v_mul_f32_e32 v5, v5, v106
	v_med3_f32 v5, v5, s40, v189
	v_add_f32_e32 v7, 1.0, v7
	v_rcp_f32_e32 v7, v7
	s_nop 0
	v_mul_f32_e32 v6, v6, v7
	v_mul_f32_e32 v7, v6, v107
	v_mul_f32_e32 v6, 0x3b000000, v112
	v_mul_f32_e32 v8, 0xbcb8aa3b, v112
	v_exp_f32_e32 v8, v8
	v_med3_f32 v7, v7, s40, v189
	v_add_f32_e32 v8, 1.0, v8
	v_rcp_f32_e32 v8, v8
	s_nop 0
	v_mul_f32_e32 v6, v6, v8
	v_mul_f32_e32 v9, v6, v108
	v_mul_f32_e32 v6, 0x3b000000, v113
	v_mul_f32_e32 v8, 0xbcb8aa3b, v113
	v_exp_f32_e32 v8, v8
	s_nop 0
	v_add_f32_e32 v8, 1.0, v8
	v_rcp_f32_e32 v8, v8
	s_nop 0
	v_mul_f32_e32 v6, v6, v8
	v_mul_f32_e32 v10, v6, v109
	v_mul_f32_e32 v6, 0x3b000000, v102
	v_mul_f32_e32 v8, 0xbcb8aa3b, v102
	v_exp_f32_e32 v8, v8
	s_nop 0
	v_add_f32_e32 v8, 1.0, v8
	v_rcp_f32_e32 v8, v8
	s_nop 0
	v_mul_f32_e32 v6, v6, v8
	v_mul_f32_e32 v11, v6, v98
	v_mul_f32_e32 v6, 0x3b000000, v103
	v_mul_f32_e32 v8, 0xbcb8aa3b, v103
	v_exp_f32_e32 v8, v8
	s_nop 0
	v_add_f32_e32 v8, 1.0, v8
	v_rcp_f32_e32 v8, v8
	s_nop 0
	v_mul_f32_e32 v6, v6, v8
	v_mul_f32_e32 v12, v6, v99
	v_mul_f32_e32 v6, 0x3b000000, v104
	v_mul_f32_e32 v8, 0xbcb8aa3b, v104
	v_exp_f32_e32 v8, v8
	s_nop 0
	v_add_f32_e32 v8, 1.0, v8
	v_rcp_f32_e32 v8, v8
	s_nop 0
	v_mul_f32_e32 v6, v6, v8
	v_mul_f32_e32 v13, v6, v100
	v_mul_f32_e32 v6, 0x3b000000, v105
	v_mul_f32_e32 v8, 0xbcb8aa3b, v105
	v_exp_f32_e32 v8, v8
	s_nop 0
	v_add_f32_e32 v8, 1.0, v8
	v_rcp_f32_e32 v8, v8
	s_nop 0
	v_mul_f32_e32 v6, v6, v8
	v_mov_b32_e32 v8, v163
	v_cvt_pk_fp8_f32 v8, v5, v7
	v_med3_f32 v5, v9, s40, v189
	v_med3_f32 v7, v10, s40, v189
	v_mov_b32_e32 v9, v163
	v_cvt_pk_fp8_f32 v8, v5, v7 op_sel:[0,0,1]
	v_med3_f32 v5, v11, s40, v189
	v_med3_f32 v7, v12, s40, v189
	v_cvt_pk_fp8_f32 v9, v5, v7
	v_mul_f32_e32 v14, v6, v101
	v_add_u32_e32 v6, 48, v4
	v_med3_f32 v5, v13, s40, v189
	v_med3_f32 v7, v14, s40, v189
	v_cvt_pk_fp8_f32 v9, v5, v7 op_sel:[0,0,1]
	v_ashrrev_i32_e32 v7, 31, v6
	v_lshlrev_b64 v[6:7], 7, v[6:7]
	v_lshl_add_u64 v[6:7], s[10:11], 0, v[6:7]
	v_lshl_add_u64 v[6:7], v[6:7], 0, v[2:3]
	v_mul_f32_e32 v5, 0x3b000000, v94
	global_store_dwordx2 v[6:7], v[8:9], off
	v_mul_f32_e32 v7, 0xbcb8aa3b, v94
	v_exp_f32_e32 v7, v7
	v_add_u32_e32 v6, 0x80, v4
	v_add_f32_e32 v7, 1.0, v7
	v_rcp_f32_e32 v7, v7
	s_nop 0
	v_mul_f32_e32 v5, v5, v7
	v_mul_f32_e32 v7, 0x3b000000, v95
	v_mul_f32_e32 v8, 0xbcb8aa3b, v95
	v_exp_f32_e32 v8, v8
	v_mul_f32_e32 v5, v5, v90
	v_med3_f32 v5, v5, s40, v189
	v_add_f32_e32 v8, 1.0, v8
	v_rcp_f32_e32 v8, v8
	s_nop 0
	v_mul_f32_e32 v7, v7, v8
	v_mul_f32_e32 v8, 0x3b000000, v96
	v_mul_f32_e32 v9, 0xbcb8aa3b, v96
	v_exp_f32_e32 v9, v9
	v_mul_f32_e32 v7, v7, v91
	v_med3_f32 v7, v7, s40, v189
	v_add_f32_e32 v9, 1.0, v9
	v_rcp_f32_e32 v9, v9
	s_nop 0
	v_mul_f32_e32 v8, v8, v9
	v_mul_f32_e32 v9, v8, v92
	v_mul_f32_e32 v8, 0x3b000000, v97
	v_mul_f32_e32 v10, 0xbcb8aa3b, v97
	v_exp_f32_e32 v10, v10
	s_nop 0
	v_add_f32_e32 v10, 1.0, v10
	v_rcp_f32_e32 v10, v10
	s_nop 0
	v_mul_f32_e32 v8, v8, v10
	v_mul_f32_e32 v10, v8, v93
	v_mul_f32_e32 v8, 0x3b000000, v86
	v_mul_f32_e32 v11, 0xbcb8aa3b, v86
	v_exp_f32_e32 v11, v11
	s_nop 0
	v_add_f32_e32 v11, 1.0, v11
	v_rcp_f32_e32 v11, v11
	s_nop 0
	v_mul_f32_e32 v8, v8, v11
	v_mul_f32_e32 v11, v8, v82
	v_mul_f32_e32 v8, 0x3b000000, v87
	v_mul_f32_e32 v12, 0xbcb8aa3b, v87
	v_exp_f32_e32 v12, v12
	s_nop 0
	v_add_f32_e32 v12, 1.0, v12
	v_rcp_f32_e32 v12, v12
	s_nop 0
	v_mul_f32_e32 v8, v8, v12
	v_mul_f32_e32 v12, v8, v83
	v_mul_f32_e32 v8, 0x3b000000, v88
	v_mul_f32_e32 v13, 0xbcb8aa3b, v88
	v_exp_f32_e32 v13, v13
	s_nop 0
	v_add_f32_e32 v13, 1.0, v13
	v_rcp_f32_e32 v13, v13
	s_nop 0
	v_mul_f32_e32 v8, v8, v13
	v_mul_f32_e32 v13, v8, v84
	v_mul_f32_e32 v8, 0x3b000000, v89
	v_mul_f32_e32 v14, 0xbcb8aa3b, v89
	v_exp_f32_e32 v14, v14
	s_nop 0
	v_add_f32_e32 v14, 1.0, v14
	v_rcp_f32_e32 v14, v14
	s_nop 0
	v_mul_f32_e32 v8, v8, v14
	v_mul_f32_e32 v14, v8, v85
	v_mov_b32_e32 v8, v163
	v_cvt_pk_fp8_f32 v8, v5, v7
	v_med3_f32 v5, v9, s40, v189
	v_med3_f32 v7, v10, s40, v189
	v_mov_b32_e32 v9, v163
	v_cvt_pk_fp8_f32 v8, v5, v7 op_sel:[0,0,1]
	v_med3_f32 v5, v11, s40, v189
	v_med3_f32 v7, v12, s40, v189
	v_cvt_pk_fp8_f32 v9, v5, v7
	v_med3_f32 v5, v13, s40, v189
	v_med3_f32 v7, v14, s40, v189
	v_cvt_pk_fp8_f32 v9, v5, v7 op_sel:[0,0,1]
	v_ashrrev_i32_e32 v7, 31, v6
	v_lshlrev_b64 v[6:7], 7, v[6:7]
	v_lshl_add_u64 v[6:7], s[10:11], 0, v[6:7]
	v_lshl_add_u64 v[6:7], v[6:7], 0, v[2:3]
	v_mul_f32_e32 v5, 0x3b000000, v78
	global_store_dwordx2 v[6:7], v[8:9], off
	v_mul_f32_e32 v6, 0xbcb8aa3b, v78
	v_exp_f32_e32 v6, v6
	s_nop 0
	v_add_f32_e32 v6, 1.0, v6
	v_rcp_f32_e32 v6, v6
	s_nop 0
	v_mul_f32_e32 v5, v5, v6
	v_mul_f32_e32 v6, 0x3b000000, v79
	v_mul_f32_e32 v7, 0xbcb8aa3b, v79
	v_exp_f32_e32 v7, v7
	v_mul_f32_e32 v5, v5, v74
	v_med3_f32 v5, v5, s40, v189
	v_add_f32_e32 v7, 1.0, v7
	v_rcp_f32_e32 v7, v7
	s_nop 0
	v_mul_f32_e32 v6, v6, v7
	v_mul_f32_e32 v7, v6, v75
	v_mul_f32_e32 v6, 0x3b000000, v80
	v_mul_f32_e32 v8, 0xbcb8aa3b, v80
	v_exp_f32_e32 v8, v8
	v_med3_f32 v7, v7, s40, v189
	v_add_f32_e32 v8, 1.0, v8
	v_rcp_f32_e32 v8, v8
	s_nop 0
	v_mul_f32_e32 v6, v6, v8
	v_mul_f32_e32 v9, v6, v76
	v_mul_f32_e32 v6, 0x3b000000, v81
	v_mul_f32_e32 v8, 0xbcb8aa3b, v81
	v_exp_f32_e32 v8, v8
	s_nop 0
	v_add_f32_e32 v8, 1.0, v8
	v_rcp_f32_e32 v8, v8
	s_nop 0
	v_mul_f32_e32 v6, v6, v8
	v_mul_f32_e32 v10, v6, v77
	v_mul_f32_e32 v6, 0x3b000000, v70
	v_mul_f32_e32 v8, 0xbcb8aa3b, v70
	v_exp_f32_e32 v8, v8
	s_nop 0
	v_add_f32_e32 v8, 1.0, v8
	v_rcp_f32_e32 v8, v8
	s_nop 0
	v_mul_f32_e32 v6, v6, v8
	v_mul_f32_e32 v11, v6, v66
	v_mul_f32_e32 v6, 0x3b000000, v71
	v_mul_f32_e32 v8, 0xbcb8aa3b, v71
	v_exp_f32_e32 v8, v8
	s_nop 0
	v_add_f32_e32 v8, 1.0, v8
	v_rcp_f32_e32 v8, v8
	s_nop 0
	v_mul_f32_e32 v6, v6, v8
	v_mul_f32_e32 v12, v6, v67
	v_mul_f32_e32 v6, 0x3b000000, v72
	v_mul_f32_e32 v8, 0xbcb8aa3b, v72
	v_exp_f32_e32 v8, v8
	s_nop 0
	v_add_f32_e32 v8, 1.0, v8
	v_rcp_f32_e32 v8, v8
	s_nop 0
	v_mul_f32_e32 v6, v6, v8
	v_mul_f32_e32 v13, v6, v68
	v_mul_f32_e32 v6, 0x3b000000, v73
	v_mul_f32_e32 v8, 0xbcb8aa3b, v73
	v_exp_f32_e32 v8, v8
	s_nop 0
	v_add_f32_e32 v8, 1.0, v8
	v_rcp_f32_e32 v8, v8
	s_nop 0
	v_mul_f32_e32 v6, v6, v8
	v_mov_b32_e32 v8, v163
	v_cvt_pk_fp8_f32 v8, v5, v7
	v_med3_f32 v5, v9, s40, v189
	v_med3_f32 v7, v10, s40, v189
	v_mov_b32_e32 v9, v163
	v_cvt_pk_fp8_f32 v8, v5, v7 op_sel:[0,0,1]
	v_med3_f32 v5, v11, s40, v189
	v_med3_f32 v7, v12, s40, v189
	v_cvt_pk_fp8_f32 v9, v5, v7
	v_mul_f32_e32 v14, v6, v69
	v_add_u32_e32 v6, 0x90, v4
	v_med3_f32 v5, v13, s40, v189
	v_med3_f32 v7, v14, s40, v189
	v_cvt_pk_fp8_f32 v9, v5, v7 op_sel:[0,0,1]
	v_ashrrev_i32_e32 v7, 31, v6
	v_lshlrev_b64 v[6:7], 7, v[6:7]
	v_lshl_add_u64 v[6:7], s[10:11], 0, v[6:7]
	v_lshl_add_u64 v[6:7], v[6:7], 0, v[2:3]
	v_mul_f32_e32 v5, 0x3b000000, v62
	global_store_dwordx2 v[6:7], v[8:9], off
	v_mul_f32_e32 v6, 0xbcb8aa3b, v62
	v_exp_f32_e32 v6, v6
	s_nop 0
	v_add_f32_e32 v6, 1.0, v6
	v_rcp_f32_e32 v6, v6
	s_nop 0
	v_mul_f32_e32 v5, v5, v6
	v_mul_f32_e32 v6, 0x3b000000, v63
	v_mul_f32_e32 v7, 0xbcb8aa3b, v63
	v_exp_f32_e32 v7, v7
	v_mul_f32_e32 v5, v5, v58
	v_med3_f32 v5, v5, s40, v189
	v_add_f32_e32 v7, 1.0, v7
	v_rcp_f32_e32 v7, v7
	s_nop 0
	v_mul_f32_e32 v6, v6, v7
	v_mul_f32_e32 v7, v6, v59
	v_mul_f32_e32 v6, 0x3b000000, v64
	v_mul_f32_e32 v8, 0xbcb8aa3b, v64
	v_exp_f32_e32 v8, v8
	v_med3_f32 v7, v7, s40, v189
	v_add_f32_e32 v8, 1.0, v8
	v_rcp_f32_e32 v8, v8
	s_nop 0
	v_mul_f32_e32 v6, v6, v8
	v_mul_f32_e32 v9, v6, v60
	v_mul_f32_e32 v6, 0x3b000000, v65
	v_mul_f32_e32 v8, 0xbcb8aa3b, v65
	v_exp_f32_e32 v8, v8
	s_nop 0
	v_add_f32_e32 v8, 1.0, v8
	v_rcp_f32_e32 v8, v8
	s_nop 0
	v_mul_f32_e32 v6, v6, v8
	v_mul_f32_e32 v10, v6, v61
	v_mul_f32_e32 v6, 0x3b000000, v54
	v_mul_f32_e32 v8, 0xbcb8aa3b, v54
	v_exp_f32_e32 v8, v8
	s_nop 0
	v_add_f32_e32 v8, 1.0, v8
	v_rcp_f32_e32 v8, v8
	s_nop 0
	v_mul_f32_e32 v6, v6, v8
	v_mul_f32_e32 v11, v6, v50
	v_mul_f32_e32 v6, 0x3b000000, v55
	v_mul_f32_e32 v8, 0xbcb8aa3b, v55
	v_exp_f32_e32 v8, v8
	s_nop 0
	v_add_f32_e32 v8, 1.0, v8
	v_rcp_f32_e32 v8, v8
	s_nop 0
	v_mul_f32_e32 v6, v6, v8
	v_mul_f32_e32 v12, v6, v51
	v_mul_f32_e32 v6, 0x3b000000, v56
	v_mul_f32_e32 v8, 0xbcb8aa3b, v56
	v_exp_f32_e32 v8, v8
	s_nop 0
	v_add_f32_e32 v8, 1.0, v8
	v_rcp_f32_e32 v8, v8
	s_nop 0
	v_mul_f32_e32 v6, v6, v8
	v_mul_f32_e32 v13, v6, v52
	v_mul_f32_e32 v6, 0x3b000000, v57
	v_mul_f32_e32 v8, 0xbcb8aa3b, v57
	v_exp_f32_e32 v8, v8
	s_nop 0
	v_add_f32_e32 v8, 1.0, v8
	v_rcp_f32_e32 v8, v8
	s_nop 0
	v_mul_f32_e32 v6, v6, v8
	v_mov_b32_e32 v8, v163
	v_cvt_pk_fp8_f32 v8, v5, v7
	v_med3_f32 v5, v9, s40, v189
	v_med3_f32 v7, v10, s40, v189
	v_mov_b32_e32 v9, v163
	v_cvt_pk_fp8_f32 v8, v5, v7 op_sel:[0,0,1]
	v_med3_f32 v5, v11, s40, v189
	v_med3_f32 v7, v12, s40, v189
	v_cvt_pk_fp8_f32 v9, v5, v7
	v_mul_f32_e32 v14, v6, v53
	v_add_u32_e32 v6, 0xa0, v4
	v_med3_f32 v5, v13, s40, v189
	v_med3_f32 v7, v14, s40, v189
	v_cvt_pk_fp8_f32 v9, v5, v7 op_sel:[0,0,1]
	v_ashrrev_i32_e32 v7, 31, v6
	v_lshlrev_b64 v[6:7], 7, v[6:7]
	v_lshl_add_u64 v[6:7], s[10:11], 0, v[6:7]
	v_lshl_add_u64 v[6:7], v[6:7], 0, v[2:3]
	v_mul_f32_e32 v5, 0x3b000000, v46
	global_store_dwordx2 v[6:7], v[8:9], off
	v_mul_f32_e32 v6, 0xbcb8aa3b, v46
	v_exp_f32_e32 v6, v6
	v_add_u32_e32 v4, 0xb0, v4
	v_add_f32_e32 v6, 1.0, v6
	v_rcp_f32_e32 v6, v6
	s_nop 0
	v_mul_f32_e32 v5, v5, v6
	v_mul_f32_e32 v6, 0x3b000000, v47
	v_mul_f32_e32 v7, 0xbcb8aa3b, v47
	v_exp_f32_e32 v7, v7
	v_mul_f32_e32 v5, v5, v42
	v_med3_f32 v5, v5, s40, v189
	v_add_f32_e32 v7, 1.0, v7
	v_rcp_f32_e32 v7, v7
	s_nop 0
	v_mul_f32_e32 v6, v6, v7
	v_mul_f32_e32 v7, 0x3b000000, v48
	v_mul_f32_e32 v8, 0xbcb8aa3b, v48
	v_exp_f32_e32 v8, v8
	v_mul_f32_e32 v6, v6, v43
	v_add_f32_e32 v8, 1.0, v8
	v_rcp_f32_e32 v8, v8
	s_nop 0
	v_mul_f32_e32 v7, v7, v8
	v_mul_f32_e32 v8, 0x3b000000, v49
	v_mul_f32_e32 v9, 0xbcb8aa3b, v49
	v_exp_f32_e32 v9, v9
	v_mul_f32_e32 v7, v7, v44
	v_add_f32_e32 v9, 1.0, v9
	v_rcp_f32_e32 v9, v9
	s_nop 0
	v_mul_f32_e32 v8, v8, v9
	v_mul_f32_e32 v9, 0x3b000000, v38
	v_mul_f32_e32 v10, 0xbcb8aa3b, v38
	v_exp_f32_e32 v10, v10
	v_mul_f32_e32 v8, v8, v45
	v_add_f32_e32 v10, 1.0, v10
	v_rcp_f32_e32 v10, v10
	s_nop 0
	v_mul_f32_e32 v9, v9, v10
	v_mul_f32_e32 v10, 0x3b000000, v39
	v_mul_f32_e32 v11, 0xbcb8aa3b, v39
	v_exp_f32_e32 v11, v11
	v_mul_f32_e32 v9, v9, v34
	v_add_f32_e32 v11, 1.0, v11
	v_rcp_f32_e32 v11, v11
	s_nop 0
	v_mul_f32_e32 v10, v10, v11
	v_mul_f32_e32 v11, 0x3b000000, v40
	v_mul_f32_e32 v12, 0xbcb8aa3b, v40
	v_exp_f32_e32 v12, v12
	v_mul_f32_e32 v10, v10, v35
	v_add_f32_e32 v12, 1.0, v12
	v_rcp_f32_e32 v12, v12
	s_nop 0
	v_mul_f32_e32 v11, v11, v12
	v_mul_f32_e32 v12, 0x3b000000, v41
	v_mul_f32_e32 v13, 0xbcb8aa3b, v41
	v_exp_f32_e32 v13, v13
	v_mul_f32_e32 v11, v11, v36
	v_add_f32_e32 v13, 1.0, v13
	v_rcp_f32_e32 v13, v13
	s_nop 0
	v_mul_f32_e32 v12, v12, v13
	v_med3_f32 v13, v6, s40, v189
	v_mov_b32_e32 v6, v163
	v_cvt_pk_fp8_f32 v6, v5, v13
	v_med3_f32 v5, v7, s40, v189
	v_med3_f32 v7, v8, s40, v189
	v_med3_f32 v8, v10, s40, v189
	v_cvt_pk_fp8_f32 v6, v5, v7 op_sel:[0,0,1]
	v_med3_f32 v5, v9, s40, v189
	v_mov_b32_e32 v7, v163
	v_cvt_pk_fp8_f32 v7, v5, v8
	v_mul_f32_e32 v12, v12, v37
	v_med3_f32 v5, v11, s40, v189
	v_med3_f32 v8, v12, s40, v189
	v_cvt_pk_fp8_f32 v7, v5, v8 op_sel:[0,0,1]
	v_ashrrev_i32_e32 v5, 31, v4
	v_lshlrev_b64 v[4:5], 7, v[4:5]
	v_lshl_add_u64 v[4:5], s[10:11], 0, v[4:5]
	v_lshl_add_u64 v[2:3], v[4:5], 0, v[2:3]
	global_store_dwordx2 v[2:3], v[6:7], off
	s_cbranch_vccz .LBB0_2738
	s_waitcnt vmcnt(0)
	s_cmpk_gt_u32 s42, 0xff
	s_cbranch_scc1 .LBB0_2684
	s_barrier
	s_branch .LBB0_2684
